# software-pipelined MLA/diff attention loops: barrier moved mid-pipeline, LDS reads one step ahead with counted lgkmcnt, LDS-DMA issue interleaved, 16x16x128 row-sum MFMA
# speedup vs baseline: 1.0353x; 1.0214x over previous
.LBB0_1288:
	s_ashr_i32 s8, s6, 6
	s_and_b32 s9, s6, 63
	s_lshr_b32 s6, s42, 1
	s_add_i32 s20, s6, s30
	s_lshl_b32 s6, s42, 5
	s_and_b32 s6, s6, 32
	s_add_i32 s26, s6, s29
	s_and_b64 s[6:7], s[14:15], exec
	s_cselect_b32 s8, s20, s8
	s_cselect_b32 s6, s26, s9
	s_lshr_b32 s7, s8, 3
	s_mulk_i32 s7, 0x4100
	s_lshl_b32 s6, s6, 8
	s_and_b32 s9, s8, 7
	s_add_i32 s7, s7, s6
	v_add_u32_e32 v166, s7, v170
	s_lshl_b32 s20, s9, 7
	s_lshl_b32 s6, s9, 2
	s_mul_i32 s44, s8, 0x208000
	v_ashrrev_i32_e32 v167, 31, v166
	s_mul_hi_i32 s45, s8, 0x208000
	s_add_u32 s53, s31, s44
	v_lshlrev_b64 v[4:5], 5, v[166:167]
	s_addc_u32 s55, s34, s45
	s_mul_i32 s50, s8, 0x104000
	v_lshl_add_u64 v[4:5], s[12:13], 0, v[4:5]
	s_mov_b32 s7, s21
	s_mul_hi_i32 s51, s8, 0x104000
	s_add_u32 s62, s35, s50
	v_lshl_add_u64 v[4:5], v[4:5], 0, s[6:7]
	s_addc_u32 s63, s36, s51
	s_add_i32 s6, s8, 32
	v_lshlrev_b64 v[2:3], 10, v[166:167]
	s_ashr_i32 s7, s6, 31
	v_lshl_add_u64 v[2:3], s[16:17], 0, v[2:3]
	s_lshl_b64 s[6:7], s[6:7], 2
	v_lshl_add_u64 v[2:3], v[2:3], 0, s[20:21]
	s_add_u32 s6, s3, s6
	s_addc_u32 s7, s28, s7
	v_lshl_add_u64 v[2:3], v[2:3], 0, v[178:179]
	global_load_dword v58, v[4:5], off
	global_load_dword v50, v163, s[6:7]
	global_load_dwordx4 v[142:145], v[2:3], off offset:16
	global_load_dwordx4 v[138:141], v[2:3], off
	global_load_dwordx4 v[150:153], v[2:3], off offset:80
	global_load_dwordx4 v[146:149], v[2:3], off offset:64
	v_readfirstlane_b32 s6, v1
	s_ashr_i32 s26, s6, 6
	s_cmp_lt_i32 s26, 6
	s_mul_i32 s46, s26, 0xc00
	s_cselect_b64 s[8:9], -1, 0
	s_add_i32 s52, s46, 0xffffc000
	s_add_u32 s27, s62, s52
	s_addc_u32 s43, s63, 0
	s_ashr_i32 s47, s46, 31
	s_add_u32 s49, s53, s46
	s_addc_u32 s64, s55, s47
	s_and_b64 s[6:7], s[8:9], exec
	s_cselect_b32 s7, s64, s43
	s_cselect_b32 s6, s49, s27
	s_add_i32 s43, s46, 0
	s_cmp_lt_i32 s26, 5
	s_cselect_b64 s[26:27], -1, 0
	s_add_i32 s65, s46, 0x400
	s_ashr_i32 s66, s65, 31
	s_add_u32 s67, s49, 0x400
	s_addc_u32 s68, s64, 0
	s_add_i32 s48, s46, 0xffffc400
	s_add_u32 s69, s62, s48
	s_addc_u32 s70, s63, 0
	v_lshl_add_u64 v[2:3], s[6:7], 0, v[164:165]
	s_and_b64 s[6:7], s[26:27], exec
	s_mov_b32 m0, s43
	s_cselect_b32 s7, s68, s70
	s_cselect_b32 s6, s67, s69
	s_add_i32 s67, s46, 0x800
	v_lshrrev_b32 v154, 2, v0
	v_xor_b32 v154, v154, v0
	v_bfe_u32 v154, v154, 2, 1
	v_add_u32 v154, -1, v154
	v_and_b32 v154, 0x38383838, v154
	v_mov_b32 v155, v154
	v_mov_b32 v156, v154
	v_mov_b32 v157, v154
	v_mov_b32 v158, v154
	v_mov_b32 v159, v154
	v_mov_b32 v160, v154
	v_mov_b32 v161, v154
	global_load_lds_dwordx4 v[2:3], off
	s_add_i32 m0, s43, 0x400
	s_ashr_i32 s68, s67, 31
	s_add_u32 s69, s49, 0x800
	s_addc_u32 s64, s64, 0
	s_add_i32 s49, s46, 0xffffc800
	s_add_u32 s70, s62, s49
	s_addc_u32 s71, s63, 0
	v_lshl_add_u64 v[2:3], s[6:7], 0, v[164:165]
	s_and_b64 s[6:7], s[26:27], exec
	global_load_lds_dwordx4 v[2:3], off
	s_cselect_b32 s7, s64, s71
	s_cselect_b32 s6, s69, s70
	s_add_i32 m0, s43, 0x800
	s_add_u32 s62, s62, 0x2000
	s_addc_u32 s63, s63, 0
	s_add_u32 s53, s53, 0x4000
	s_addc_u32 s55, s55, 0
	s_add_u32 s64, s53, s46
	s_addc_u32 s69, s55, s47
	s_add_u32 s70, s62, s52
	s_addc_u32 s71, s63, 0
	v_lshl_add_u64 v[2:3], s[6:7], 0, v[164:165]
	s_and_b64 s[6:7], s[8:9], exec
	global_load_lds_dwordx4 v[2:3], off
	s_cselect_b32 s7, s69, s71
	s_cselect_b32 s6, s64, s70
	s_add_i32 m0, s43, 0x6000
	s_add_u32 s64, s53, s65
	s_addc_u32 s65, s55, s66
	s_add_u32 s66, s62, s48
	s_addc_u32 s69, s63, 0
	v_lshl_add_u64 v[2:3], s[6:7], 0, v[164:165]
	s_and_b64 s[6:7], s[26:27], exec
	global_load_lds_dwordx4 v[2:3], off
	s_cselect_b32 s7, s65, s69
	s_cselect_b32 s6, s64, s66
	s_add_i32 m0, s43, 0x6400
	s_add_u32 s53, s53, s67
	s_addc_u32 s55, s55, s68
	s_add_u32 s62, s62, s49
	s_addc_u32 s63, s63, 0
	v_lshl_add_u64 v[2:3], s[6:7], 0, v[164:165]
	s_and_b64 s[6:7], s[26:27], exec
	s_cselect_b32 s7, s55, s63
	s_cselect_b32 s6, s53, s62
	global_load_lds_dwordx4 v[2:3], off
	v_lshl_add_u64 v[2:3], s[6:7], 0, v[164:165]
	s_add_i32 m0, s43, 0x6800
	s_waitcnt vmcnt(0)
	v_mul_f32_e32 v51, 0x4f800000, v50
	global_load_lds_dwordx4 v[2:3], off
	s_waitcnt vmcnt(3)
	s_barrier
	ds_read_b128 v[2:5], v171
	ds_read_b128 v[6:9], v171 offset:1024
	s_waitcnt lgkmcnt(0)
	v_mfma_scale_f32_32x32x64_f8f6f4 v[2:17], v[2:9], v[138:145], 0, v174, v174 op_sel_hi:[0,0,0]
	ds_read_b128 v[18:21], v171 offset:2048
	ds_read_b128 v[22:25], v171 offset:3072
	v_cmp_gt_f32_e32 vcc, s37, v50
	s_add_u32 s44, s44, s46
	s_addc_u32 s45, s45, s47
	v_cndmask_b32_e32 v59, v50, v51, vcc
	v_sqrt_f32_e32 v60, v59
	s_add_u32 s46, s50, s49
	s_addc_u32 s47, s51, 0
	s_add_u32 s48, s50, s48
	v_add_u32_e32 v61, -1, v60
	v_fma_f32 v62, -v61, v60, v59
	v_cmp_ge_f32_e64 s[6:7], 0, v62
	v_add_u32_e32 v62, 1, v60
	s_addc_u32 s49, s51, 0
	v_cndmask_b32_e64 v61, v60, v61, s[6:7]
	s_waitcnt lgkmcnt(0)
	v_mfma_scale_f32_32x32x64_f8f6f4 v[2:17], v[18:25], v[146:153], v[2:17], v174, v174 op_sel_hi:[0,0,0]
	ds_read_b128 v[18:21], v171 offset:4096
	ds_read_b128 v[22:25], v171 offset:5120
	ds_read_b128 v[34:37], v171 offset:6144
	ds_read_b128 v[38:41], v171 offset:7168
	v_fma_f32 v60, -v62, v60, v59
	v_cmp_lt_f32_e64 s[6:7], 0, v60
	s_add_u32 s50, s50, s52
	s_addc_u32 s51, s51, 0
	v_cndmask_b32_e64 v60, v61, v62, s[6:7]
	s_mov_b32 s55, 0
	s_mov_b32 s52, 0
	v_mov_b32_e32 v61, v163
	v_mov_b32_e32 v62, v163
	v_mov_b32_e32 v63, v163
	v_mov_b32_e32 v64, v163
	v_mov_b32_e32 v65, v163
	s_nop 3
	v_max3_f32 v2, v2, s39, v3
	s_waitcnt lgkmcnt(0)
	v_mfma_scale_f32_32x32x64_f8f6f4 v[18:33], v[18:25], v[138:145], 0, v174, v174 op_sel_hi:[0,0,0]
	v_max3_f32 v2, v2, v4, v5
	v_max3_f32 v2, v2, v6, v7
	v_max3_f32 v2, v2, v8, v9
	v_max3_f32 v2, v2, v10, v11
	v_max3_f32 v2, v2, v12, v13
	v_max3_f32 v2, v2, v14, v15
	v_max3_f32 v2, v2, v16, v17
	v_mfma_scale_f32_32x32x64_f8f6f4 v[18:33], v[34:41], v[146:153], v[18:33], v174, v174 op_sel_hi:[0,0,0]
	ds_read_b128 v[34:37], v171 offset:8192
	ds_read_b128 v[38:41], v171 offset:9216
	ds_read_b128 v[50:53], v171 offset:10240
	ds_read_b128 v[54:57], v171 offset:11264
	s_waitcnt lgkmcnt(0)
	v_mfma_scale_f32_32x32x64_f8f6f4 v[34:49], v[34:41], v[138:145], 0, v174, v174 op_sel_hi:[0,0,0]
	s_nop 13
	v_max3_f32 v2, v2, v18, v19
	v_max3_f32 v2, v2, v20, v21
	v_max3_f32 v18, v2, v22, v23
	v_max3_f32 v18, v18, v24, v25
	v_max3_f32 v18, v18, v26, v27
	v_max3_f32 v18, v18, v28, v29
	v_max3_f32 v18, v18, v30, v31
	v_max3_f32 v26, v18, v32, v33
	v_mov_b32_e32 v27, v163
	v_mov_b32_e32 v28, v163
	v_mov_b32_e32 v29, v163
	v_mov_b32_e32 v30, v163
	v_mov_b32_e32 v31, v163
	v_mov_b32_e32 v32, v163
	v_mov_b32_e32 v33, v163
	v_mfma_scale_f32_32x32x64_f8f6f4 v[34:49], v[50:57], v[146:153], v[34:49], v174, v174 op_sel_hi:[0,0,0]
	v_mul_f32_e32 v50, 0x37800000, v60
	v_cndmask_b32_e32 v60, v60, v50, vcc
	ds_read_b128 v[50:53], v171 offset:12288
	ds_read_b128 v[54:57], v171 offset:13312
	ds_read_b128 v[18:21], v171 offset:14336
	ds_read_b128 v[22:25], v171 offset:15360
	v_cmp_lt_i32_e32 vcc, v176, v177
	s_nop 12
	v_max3_f32 v26, v26, v34, v35
	s_waitcnt lgkmcnt(0)
	v_mfma_scale_f32_32x32x64_f8f6f4 v[2:17], v[50:57], v[138:145], 0, v174, v174 op_sel_hi:[0,0,0]
	v_max3_f32 v26, v26, v36, v37
	v_max3_f32 v26, v26, v38, v39
	v_max3_f32 v26, v26, v40, v41
	v_max3_f32 v26, v26, v42, v43
	v_max3_f32 v26, v26, v44, v45
	v_max3_f32 v26, v26, v46, v47
	v_max3_f32 v26, v26, v48, v49
	v_mov_b32_e32 v50, 0
	v_mov_b32_e32 v51, v163
	v_mov_b32_e32 v52, v163
	v_mov_b32_e32 v53, v163
	v_mov_b32_e32 v54, v163
	v_mov_b32_e32 v55, v163
	v_mov_b32_e32 v56, v163
	v_mov_b32_e32 v57, v163
	v_mfma_scale_f32_32x32x64_f8f6f4 v[2:17], v[18:25], v[146:153], v[2:17], v174, v174 op_sel_hi:[0,0,0]
	v_mov_b32_e32 v18, 0
	v_mov_b32_e32 v19, v163
	v_mov_b32_e32 v20, v163
	v_mov_b32_e32 v21, v163
	v_mov_b32_e32 v22, v163
	v_mov_b32_e32 v23, v163
	v_mov_b32_e32 v24, v163
	v_mov_b32_e32 v25, v163
	s_nop 11
	v_max3_f32 v2, v26, v2, v3
	v_max3_f32 v2, v2, v4, v5
	v_max3_f32 v2, v2, v6, v7
	v_max3_f32 v2, v2, v8, v9
	v_max3_f32 v2, v2, v10, v11
	v_max3_f32 v2, v2, v12, v13
	v_max3_f32 v2, v2, v14, v15
	v_cndmask_b32_e32 v3, v175, v176, vcc
	v_max3_f32 v2, v2, v16, v17
	v_lshlrev_b32_e32 v3, 2, v3
	ds_bpermute_b32 v3, v3, v2
	v_cmp_class_f32_e32 vcc, v59, v172
	v_mov_b32_e32 v26, v163
	v_mov_b32_e32 v5, v163
	v_cndmask_b32_e32 v4, v60, v59, vcc
	s_waitcnt lgkmcnt(0)
	v_max_f32_e32 v3, v3, v3
	v_mul_f32_e32 v4, v58, v4
	v_max_f32_e32 v2, v2, v3
	v_fmamk_f32 v4, v4, 0x3f90a3d7, v173
	v_add_f32_e32 v2, 0x42800000, v2
	v_min_f32_e32 v2, v4, v2
	v_add_f32_e32 v2, 0xc2ec0000, v2
	v_xor_b32_e32 v34, 0x80000000, v2
	v_mov_b32_e32 v35, v34
	v_mov_b32_e32 v36, v34
	v_mov_b32_e32 v37, v34
	v_mov_b32_e32 v38, v34
	v_mov_b32_e32 v39, v34
	v_mov_b32_e32 v40, v34
	v_mov_b32_e32 v41, v34
	v_mov_b32_e32 v42, v34
	v_mov_b32_e32 v43, v34
	v_mov_b32_e32 v44, v34
	v_mov_b32_e32 v45, v34
	v_mov_b32_e32 v46, v34
	v_mov_b32_e32 v47, v34
	v_mov_b32_e32 v48, v34
	v_mov_b32_e32 v49, v34
	v_mov_b32_e32 v58, v163
	v_mov_b32_e32 v59, v163
	v_mov_b32_e32 v60, v163
	v_mov_b32_e32 v2, 0
	v_mov_b32_e32 v3, v163
	v_mov_b32_e32 v4, v163
	v_mov_b32_e32 v6, v163
	v_mov_b32_e32 v7, v163
	v_mov_b32_e32 v8, v163
	v_mov_b32_e32 v9, v163
	v_mov_b32_e32 v10, v163
	v_mov_b32_e32 v11, v163
	v_mov_b32_e32 v12, v163
	v_mov_b32_e32 v13, v163
	v_mov_b32_e32 v14, v163
	v_mov_b32_e32 v15, v163
	v_mov_b32_e32 v16, v163
	v_mov_b32_e32 v17, v163
	v_mov_b32_e32 v86, v163
	v_mov_b32_e32 v87, v163
	v_mov_b32_e32 v88, v163
	v_mov_b32_e32 v89, v163
	v_mov_b32_e32 v90, v163
	v_mov_b32_e32 v91, v163
	v_mov_b32_e32 v92, v163
	v_mov_b32_e32 v93, v163
	v_mov_b32_e32 v94, v163
	v_mov_b32_e32 v95, v163
	v_mov_b32_e32 v96, v163
	v_mov_b32_e32 v97, v163
	v_mov_b32_e32 v98, v163
	v_mov_b32_e32 v99, v163
	v_mov_b32_e32 v100, v163
	v_mov_b32_e32 v101, v163
	v_mov_b32_e32 v102, v163
	v_mov_b32_e32 v103, v163
	v_mov_b32_e32 v104, v163
	v_mov_b32_e32 v105, v163
	v_mov_b32_e32 v106, v163
	v_mov_b32_e32 v107, v163
	v_mov_b32_e32 v108, v163
	v_mov_b32_e32 v109, v163
	v_mov_b32_e32 v110, v163
	v_mov_b32_e32 v111, v163
	v_mov_b32_e32 v112, v163
	v_mov_b32_e32 v113, v163
	v_mov_b32_e32 v114, v163
	v_mov_b32_e32 v115, v163
	v_mov_b32_e32 v116, v163
	v_mov_b32_e32 v117, v163
	v_mov_b32_e32 v228, v163
	v_mov_b32_e32 v229, v163
	v_mov_b32_e32 v230, v163
	v_mov_b32_e32 v231, v163
	v_mov_b32_e32 v232, v163
	v_mov_b32_e32 v233, v163
	v_mov_b32_e32 v234, v163
	v_mov_b32_e32 v235, v163
	v_mov_b32_e32 v236, v163
	v_mov_b32_e32 v237, v163
	v_mov_b32_e32 v238, v163
	v_mov_b32_e32 v239, v163
	v_mov_b32_e32 v240, v163
	v_mov_b32_e32 v241, v163
	v_mov_b32_e32 v242, v163
	v_mov_b32_e32 v243, v163
	s_branch .LBB0_1290
.LBB0_1290:
	s_waitcnt vmcnt(0) lgkmcnt(0)
	s_barrier
	s_cmpk_gt_u32 s52, 0x7f
	s_cselect_b64 s[6:7], -1, 0
	s_xor_b32 s53, s55, 2
	s_mul_i32 s100, s55, 0x6000
	s_add_i32 s52, s52, 2
	s_andn2_b64 vcc, exec, s[6:7]
	v_add_u32_e32 v167, s100, v171
	s_mov_b32 s55, s53
.LBB0_1289:
	ds_read_b128 v[190:193], v167
	ds_read_b128 v[194:197], v167 offset:1024
	ds_read_b128 v[198:201], v167 offset:2048
	ds_read_b128 v[202:205], v167 offset:3072
	ds_read_b128 v[206:209], v167 offset:4096
	ds_read_b128 v[210:213], v167 offset:5120
	ds_read_b128 v[220:223], v167 offset:6144
	ds_read_b128 v[224:227], v167 offset:7168
	v_med3_f32 v86, v86, 0, v180
	v_med3_f32 v90, v90, 0, v180
	v_med3_f32 v94, v94, 0, v180
	v_med3_f32 v98, v98, 0, v180
	v_cvt_pk_u8_f32 v118, v86, 0, 0
	v_cvt_pk_u8_f32 v119, v90, 0, 0
	v_cvt_pk_u8_f32 v120, v94, 0, 0
	v_cvt_pk_u8_f32 v121, v98, 0, 0
	v_med3_f32 v87, v87, 0, v180
	v_med3_f32 v91, v91, 0, v180
	v_med3_f32 v95, v95, 0, v180
	v_med3_f32 v99, v99, 0, v180
	v_cvt_pk_u8_f32 v118, v87, 1, v118
	v_cvt_pk_u8_f32 v119, v91, 1, v119
	v_cvt_pk_u8_f32 v120, v95, 1, v120
	v_cvt_pk_u8_f32 v121, v99, 1, v121
	s_waitcnt lgkmcnt(6)
	v_mfma_scale_f32_32x32x64_f8f6f4 v[54:69], v[190:197], v[138:145], v[34:49], v174, v174 op_sel_hi:[0,0,0]
	v_med3_f32 v88, v88, 0, v180
	v_med3_f32 v92, v92, 0, v180
	v_med3_f32 v96, v96, 0, v180
	v_med3_f32 v100, v100, 0, v180
	v_cvt_pk_u8_f32 v118, v88, 2, v118
	v_cvt_pk_u8_f32 v119, v92, 2, v119
	v_cvt_pk_u8_f32 v120, v96, 2, v120
	v_cvt_pk_u8_f32 v121, v100, 2, v121
	v_med3_f32 v89, v89, 0, v180
	v_med3_f32 v93, v93, 0, v180
	v_med3_f32 v97, v97, 0, v180
	v_med3_f32 v101, v101, 0, v180
	v_cvt_pk_u8_f32 v118, v89, 3, v118
	v_cvt_pk_u8_f32 v119, v93, 3, v119
	v_cvt_pk_u8_f32 v120, v97, 3, v120
	v_cvt_pk_u8_f32 v121, v101, 3, v121
	s_waitcnt lgkmcnt(4)
	v_mfma_scale_f32_32x32x64_f8f6f4 v[54:69], v[198:205], v[146:153], v[54:69], v174, v174 op_sel_hi:[0,0,0]
	v_med3_f32 v102, v102, 0, v180
	v_med3_f32 v106, v106, 0, v180
	v_med3_f32 v110, v110, 0, v180
	v_med3_f32 v114, v114, 0, v180
	v_cvt_pk_u8_f32 v122, v102, 0, 0
	v_cvt_pk_u8_f32 v123, v106, 0, 0
	v_cvt_pk_u8_f32 v124, v110, 0, 0
	v_cvt_pk_u8_f32 v125, v114, 0, 0
	v_med3_f32 v103, v103, 0, v180
	v_med3_f32 v107, v107, 0, v180
	v_med3_f32 v111, v111, 0, v180
	v_med3_f32 v115, v115, 0, v180
	v_cvt_pk_u8_f32 v122, v103, 1, v122
	v_cvt_pk_u8_f32 v123, v107, 1, v123
	v_cvt_pk_u8_f32 v124, v111, 1, v124
	v_cvt_pk_u8_f32 v125, v115, 1, v125
	s_waitcnt lgkmcnt(2)
	v_mfma_scale_f32_32x32x64_f8f6f4 v[70:85], v[206:213], v[138:145], v[34:49], v174, v174 op_sel_hi:[0,0,0]
	v_med3_f32 v104, v104, 0, v180
	v_med3_f32 v108, v108, 0, v180
	v_med3_f32 v112, v112, 0, v180
	v_med3_f32 v116, v116, 0, v180
	v_cvt_pk_u8_f32 v122, v104, 2, v122
	v_cvt_pk_u8_f32 v123, v108, 2, v123
	v_cvt_pk_u8_f32 v124, v112, 2, v124
	v_cvt_pk_u8_f32 v125, v116, 2, v125
	v_med3_f32 v105, v105, 0, v180
	v_med3_f32 v109, v109, 0, v180
	v_med3_f32 v113, v113, 0, v180
	v_med3_f32 v117, v117, 0, v180
	v_cvt_pk_u8_f32 v122, v105, 3, v122
	v_cvt_pk_u8_f32 v123, v109, 3, v123
	v_cvt_pk_u8_f32 v124, v113, 3, v124
	v_cvt_pk_u8_f32 v125, v117, 3, v125
	s_waitcnt lgkmcnt(0)
	v_mfma_scale_f32_32x32x64_f8f6f4 v[70:85], v[220:227], v[146:153], v[70:85], v174, v174 op_sel_hi:[0,0,0]
	s_nop 1
	v_mfma_scale_f32_32x32x64_f8f6f4 v[18:33], v[228:235], v[118:125], v[18:33], v174, v174 op_sel_hi:[0,0,0] blgp:1
	ds_read_b128 v[190:193], v167 offset:8192
	ds_read_b128 v[194:197], v167 offset:9216
	ds_read_b128 v[198:201], v167 offset:10240
	ds_read_b128 v[202:205], v167 offset:11264
	s_cbranch_vccz .Ldma_mla0_skip0
	s_add_u32 s65, s18, s44
	s_addc_u32 s66, s19, s45
	s_add_u32 s67, s65, 0x23076100
	s_addc_u32 s68, s66, 0
	s_add_u32 s69, s18, s50
	s_addc_u32 s70, s19, s51
	s_add_u32 s71, s69, 0x26132100
	s_addc_u32 s72, s70, 0
	s_mul_i32 s64, s53, 0x6000
	s_and_b64 s[62:63], s[8:9], exec
	s_cselect_b32 s63, s68, s72
	s_cselect_b32 s62, s67, s71
	s_add_i32 s64, s43, s64
	s_add_u32 s67, s65, 0x23076500
	s_addc_u32 s68, s66, 0
	s_add_u32 s71, s18, s48
	s_addc_u32 s72, s19, s49
	s_add_u32 s73, s71, 0x26132100
	s_addc_u32 s74, s72, 0
	s_mov_b32 m0, s64
	s_nop 0
	global_load_lds_dwordx4 v164, s[62:63]
.Ldma_mla0_skip0:
	v_mfma_scale_f32_32x32x64_f8f6f4 v[2:17], v[236:243], v[118:125], v[2:17], v174, v174 op_sel_hi:[0,0,0] blgp:1
	ds_read_b128 v[206:209], v167 offset:12288
	ds_read_b128 v[210:213], v167 offset:13312
	ds_read_b128 v[220:223], v167 offset:14336
	ds_read_b128 v[224:227], v167 offset:15360
	s_cbranch_vccz .Ldma_mla0_skip1
	s_and_b64 s[62:63], s[26:27], exec
	s_cselect_b32 s63, s68, s74
	s_cselect_b32 s62, s67, s73
	s_add_i32 m0, s64, 0x400
	s_add_u32 s67, s65, 0x23076900
	s_addc_u32 s68, s66, 0
	s_add_u32 s73, s18, s46
	s_addc_u32 s74, s19, s47
	s_add_u32 s75, s73, 0x26132100
	s_addc_u32 s76, s74, 0
	global_load_lds_dwordx4 v164, s[62:63]
.Ldma_mla0_skip1:
	v_mfma_scale_f32_16x16x128_f8f6f4 v[50:53], v[154:161], v[118:125], v[50:53], v174, v174 op_sel_hi:[0,0,0] blgp:1
	ds_read_b128 v[228:231], v167 offset:16384
	ds_read_b128 v[232:235], v167 offset:17408
	ds_read_b128 v[236:239], v167 offset:18432
	ds_read_b128 v[240:243], v167 offset:19456
	v_med3_f32 v54, v54, 0, v180
	v_med3_f32 v58, v58, 0, v180
	v_med3_f32 v62, v62, 0, v180
	v_med3_f32 v66, v66, 0, v180
	v_cvt_pk_u8_f32 v118, v54, 0, 0
	v_cvt_pk_u8_f32 v119, v58, 0, 0
	v_cvt_pk_u8_f32 v120, v62, 0, 0
	v_cvt_pk_u8_f32 v121, v66, 0, 0
	v_med3_f32 v55, v55, 0, v180
	v_med3_f32 v59, v59, 0, v180
	v_med3_f32 v63, v63, 0, v180
	v_med3_f32 v67, v67, 0, v180
	v_cvt_pk_u8_f32 v118, v55, 1, v118
	v_cvt_pk_u8_f32 v119, v59, 1, v119
	v_cvt_pk_u8_f32 v120, v63, 1, v120
	v_cvt_pk_u8_f32 v121, v67, 1, v121
	s_waitcnt lgkmcnt(10)
	v_mfma_scale_f32_32x32x64_f8f6f4 v[86:101], v[190:197], v[138:145], v[34:49], v174, v174 op_sel_hi:[0,0,0]
	v_med3_f32 v56, v56, 0, v180
	v_med3_f32 v60, v60, 0, v180
	v_med3_f32 v64, v64, 0, v180
	v_med3_f32 v68, v68, 0, v180
	v_cvt_pk_u8_f32 v118, v56, 2, v118
	v_cvt_pk_u8_f32 v119, v60, 2, v119
	v_cvt_pk_u8_f32 v120, v64, 2, v120
	v_cvt_pk_u8_f32 v121, v68, 2, v121
	v_med3_f32 v57, v57, 0, v180
	v_med3_f32 v61, v61, 0, v180
	v_med3_f32 v65, v65, 0, v180
	v_med3_f32 v69, v69, 0, v180
	v_cvt_pk_u8_f32 v118, v57, 3, v118
	v_cvt_pk_u8_f32 v119, v61, 3, v119
	v_cvt_pk_u8_f32 v120, v65, 3, v120
	v_cvt_pk_u8_f32 v121, v69, 3, v121
	s_waitcnt lgkmcnt(8)
	v_mfma_scale_f32_32x32x64_f8f6f4 v[86:101], v[198:205], v[146:153], v[86:101], v174, v174 op_sel_hi:[0,0,0]
	v_med3_f32 v70, v70, 0, v180
	v_med3_f32 v74, v74, 0, v180
	v_med3_f32 v78, v78, 0, v180
	v_med3_f32 v82, v82, 0, v180
	v_cvt_pk_u8_f32 v122, v70, 0, 0
	v_cvt_pk_u8_f32 v123, v74, 0, 0
	v_cvt_pk_u8_f32 v124, v78, 0, 0
	v_cvt_pk_u8_f32 v125, v82, 0, 0
	v_med3_f32 v71, v71, 0, v180
	v_med3_f32 v75, v75, 0, v180
	v_med3_f32 v79, v79, 0, v180
	v_med3_f32 v83, v83, 0, v180
	v_cvt_pk_u8_f32 v122, v71, 1, v122
	v_cvt_pk_u8_f32 v123, v75, 1, v123
	v_cvt_pk_u8_f32 v124, v79, 1, v124
	v_cvt_pk_u8_f32 v125, v83, 1, v125
	s_waitcnt lgkmcnt(6)
	v_mfma_scale_f32_32x32x64_f8f6f4 v[102:117], v[206:213], v[138:145], v[34:49], v174, v174 op_sel_hi:[0,0,0]
	v_med3_f32 v72, v72, 0, v180
	v_med3_f32 v76, v76, 0, v180
	v_med3_f32 v80, v80, 0, v180
	v_med3_f32 v84, v84, 0, v180
	v_cvt_pk_u8_f32 v122, v72, 2, v122
	v_cvt_pk_u8_f32 v123, v76, 2, v123
	v_cvt_pk_u8_f32 v124, v80, 2, v124
	v_cvt_pk_u8_f32 v125, v84, 2, v125
	v_med3_f32 v73, v73, 0, v180
	v_med3_f32 v77, v77, 0, v180
	v_med3_f32 v81, v81, 0, v180
	v_med3_f32 v85, v85, 0, v180
	v_cvt_pk_u8_f32 v122, v73, 3, v122
	v_cvt_pk_u8_f32 v123, v77, 3, v123
	v_cvt_pk_u8_f32 v124, v81, 3, v124
	v_cvt_pk_u8_f32 v125, v85, 3, v125
	s_waitcnt lgkmcnt(4)
	v_mfma_scale_f32_32x32x64_f8f6f4 v[102:117], v[220:227], v[146:153], v[102:117], v174, v174 op_sel_hi:[0,0,0]
	s_nop 1
	s_waitcnt lgkmcnt(2)
	v_mfma_scale_f32_32x32x64_f8f6f4 v[18:33], v[228:235], v[118:125], v[18:33], v174, v174 op_sel_hi:[0,0,0] blgp:1
	ds_read_b128 v[190:193], v167 offset:24576
	ds_read_b128 v[194:197], v167 offset:25600
	ds_read_b128 v[198:201], v167 offset:26624
	ds_read_b128 v[202:205], v167 offset:27648
	s_cbranch_vccz .Ldma_mla0_skip2
	s_and_b64 s[62:63], s[26:27], exec
	s_cselect_b32 s63, s68, s76
	s_cselect_b32 s62, s67, s75
	s_add_i32 m0, s64, 0x800
	s_add_u32 s67, s65, 0x2307a100
	s_addc_u32 s68, s66, 0
	s_add_u32 s69, s69, 0x26134100
	s_addc_u32 s70, s70, 0
	global_load_lds_dwordx4 v164, s[62:63]
.Ldma_mla0_skip2:
	s_waitcnt lgkmcnt(4)
	v_mfma_scale_f32_32x32x64_f8f6f4 v[2:17], v[236:243], v[118:125], v[2:17], v174, v174 op_sel_hi:[0,0,0] blgp:1
	ds_read_b128 v[206:209], v167 offset:28672
	ds_read_b128 v[210:213], v167 offset:29696
	ds_read_b128 v[220:223], v167 offset:30720
	ds_read_b128 v[224:227], v167 offset:31744
	s_cbranch_vccz .Ldma_mla0_skip3
	s_and_b64 s[62:63], s[8:9], exec
	s_cselect_b32 s63, s68, s70
	s_cselect_b32 s62, s67, s69
	s_add_i32 m0, s64, 0x6000
	s_add_u32 s67, s65, 0x2307a500
	s_addc_u32 s68, s66, 0
	s_add_u32 s69, s71, 0x26134100
	s_addc_u32 s70, s72, 0
	global_load_lds_dwordx4 v164, s[62:63]
.Ldma_mla0_skip3:
	v_mfma_scale_f32_16x16x128_f8f6f4 v[50:53], v[154:161], v[118:125], v[50:53], v174, v174 op_sel_hi:[0,0,0] blgp:1
	ds_read_b128 v[228:231], v167 offset:20480
	ds_read_b128 v[232:235], v167 offset:21504
	ds_read_b128 v[236:239], v167 offset:22528
	ds_read_b128 v[240:243], v167 offset:23552
	v_med3_f32 v86, v86, 0, v180
	v_med3_f32 v90, v90, 0, v180
	v_med3_f32 v94, v94, 0, v180
	v_med3_f32 v98, v98, 0, v180
	v_cvt_pk_u8_f32 v118, v86, 0, 0
	v_cvt_pk_u8_f32 v119, v90, 0, 0
	v_cvt_pk_u8_f32 v120, v94, 0, 0
	v_cvt_pk_u8_f32 v121, v98, 0, 0
	v_med3_f32 v87, v87, 0, v180
	v_med3_f32 v91, v91, 0, v180
	v_med3_f32 v95, v95, 0, v180
	v_med3_f32 v99, v99, 0, v180
	v_cvt_pk_u8_f32 v118, v87, 1, v118
	v_cvt_pk_u8_f32 v119, v91, 1, v119
	v_cvt_pk_u8_f32 v120, v95, 1, v120
	v_cvt_pk_u8_f32 v121, v99, 1, v121
	s_waitcnt lgkmcnt(10)
	v_mfma_scale_f32_32x32x64_f8f6f4 v[54:69], v[190:197], v[138:145], v[34:49], v174, v174 op_sel_hi:[0,0,0]
	v_med3_f32 v88, v88, 0, v180
	v_med3_f32 v92, v92, 0, v180
	v_med3_f32 v96, v96, 0, v180
	v_med3_f32 v100, v100, 0, v180
	v_cvt_pk_u8_f32 v118, v88, 2, v118
	v_cvt_pk_u8_f32 v119, v92, 2, v119
	v_cvt_pk_u8_f32 v120, v96, 2, v120
	v_cvt_pk_u8_f32 v121, v100, 2, v121
	v_med3_f32 v89, v89, 0, v180
	v_med3_f32 v93, v93, 0, v180
	v_med3_f32 v97, v97, 0, v180
	v_med3_f32 v101, v101, 0, v180
	v_cvt_pk_u8_f32 v118, v89, 3, v118
	v_cvt_pk_u8_f32 v119, v93, 3, v119
	v_cvt_pk_u8_f32 v120, v97, 3, v120
	v_cvt_pk_u8_f32 v121, v101, 3, v121
	s_waitcnt lgkmcnt(8)
	v_mfma_scale_f32_32x32x64_f8f6f4 v[54:69], v[198:205], v[146:153], v[54:69], v174, v174 op_sel_hi:[0,0,0]
	v_med3_f32 v102, v102, 0, v180
	v_med3_f32 v106, v106, 0, v180
	v_med3_f32 v110, v110, 0, v180
	v_med3_f32 v114, v114, 0, v180
	v_cvt_pk_u8_f32 v122, v102, 0, 0
	v_cvt_pk_u8_f32 v123, v106, 0, 0
	v_cvt_pk_u8_f32 v124, v110, 0, 0
	v_cvt_pk_u8_f32 v125, v114, 0, 0
	v_med3_f32 v103, v103, 0, v180
	v_med3_f32 v107, v107, 0, v180
	v_med3_f32 v111, v111, 0, v180
	v_med3_f32 v115, v115, 0, v180
	v_cvt_pk_u8_f32 v122, v103, 1, v122
	v_cvt_pk_u8_f32 v123, v107, 1, v123
	v_cvt_pk_u8_f32 v124, v111, 1, v124
	v_cvt_pk_u8_f32 v125, v115, 1, v125
	s_waitcnt lgkmcnt(6)
	v_mfma_scale_f32_32x32x64_f8f6f4 v[70:85], v[206:213], v[138:145], v[34:49], v174, v174 op_sel_hi:[0,0,0]
	v_med3_f32 v104, v104, 0, v180
	v_med3_f32 v108, v108, 0, v180
	v_med3_f32 v112, v112, 0, v180
	v_med3_f32 v116, v116, 0, v180
	v_cvt_pk_u8_f32 v122, v104, 2, v122
	v_cvt_pk_u8_f32 v123, v108, 2, v123
	v_cvt_pk_u8_f32 v124, v112, 2, v124
	v_cvt_pk_u8_f32 v125, v116, 2, v125
	v_med3_f32 v105, v105, 0, v180
	v_med3_f32 v109, v109, 0, v180
	v_med3_f32 v113, v113, 0, v180
	v_med3_f32 v117, v117, 0, v180
	v_cvt_pk_u8_f32 v122, v105, 3, v122
	v_cvt_pk_u8_f32 v123, v109, 3, v123
	v_cvt_pk_u8_f32 v124, v113, 3, v124
	v_cvt_pk_u8_f32 v125, v117, 3, v125
	s_waitcnt lgkmcnt(4)
	v_mfma_scale_f32_32x32x64_f8f6f4 v[70:85], v[220:227], v[146:153], v[70:85], v174, v174 op_sel_hi:[0,0,0]
	s_nop 1
	s_waitcnt lgkmcnt(2)
	v_mfma_scale_f32_32x32x64_f8f6f4 v[18:33], v[228:235], v[118:125], v[18:33], v174, v174 op_sel_hi:[0,0,0] blgp:1
	ds_read_b128 v[190:193], v167 offset:32768
	ds_read_b128 v[194:197], v167 offset:33792
	ds_read_b128 v[198:201], v167 offset:34816
	ds_read_b128 v[202:205], v167 offset:35840
	s_cbranch_vccz .Ldma_mla0_skip4
	s_and_b64 s[62:63], s[26:27], exec
	s_cselect_b32 s63, s68, s70
	s_cselect_b32 s62, s67, s69
	s_add_i32 m0, s64, 0x6400
	s_add_u32 s65, s65, 0x2307a900
	s_addc_u32 s66, s66, 0
	s_add_u32 s67, s73, 0x26134100
	s_addc_u32 s68, s74, 0
	global_load_lds_dwordx4 v164, s[62:63]
.Ldma_mla0_skip4:
	s_waitcnt lgkmcnt(4)
	v_mfma_scale_f32_32x32x64_f8f6f4 v[2:17], v[236:243], v[118:125], v[2:17], v174, v174 op_sel_hi:[0,0,0] blgp:1
	ds_read_b128 v[206:209], v167 offset:36864
	ds_read_b128 v[210:213], v167 offset:37888
	ds_read_b128 v[220:223], v167 offset:38912
	ds_read_b128 v[224:227], v167 offset:39936
	s_cbranch_vccz .Ldma_mla0_skip5
	s_and_b64 s[62:63], s[26:27], exec
	s_cselect_b32 s63, s66, s68
	s_cselect_b32 s62, s65, s67
	s_add_i32 m0, s64, 0x6800
	s_nop 0
	global_load_lds_dwordx4 v164, s[62:63]
.Ldma_mla0_skip5:
	s_add_u32 s44, s44, 0x8000
	s_addc_u32 s45, s45, 0
	s_add_u32 s46, s46, 0x4000
	s_addc_u32 s47, s47, 0
	s_add_u32 s48, s48, 0x4000
	s_addc_u32 s49, s49, 0
	s_add_u32 s50, s50, 0x4000
	s_addc_u32 s51, s51, 0
	v_mfma_scale_f32_16x16x128_f8f6f4 v[50:53], v[154:161], v[118:125], v[50:53], v174, v174 op_sel_hi:[0,0,0] blgp:1
	ds_read_b128 v[228:231], v167 offset:40960
	ds_read_b128 v[232:235], v167 offset:41984
	ds_read_b128 v[236:239], v167 offset:43008
	ds_read_b128 v[240:243], v167 offset:44032
	v_med3_f32 v54, v54, 0, v180
	v_med3_f32 v58, v58, 0, v180
	v_med3_f32 v62, v62, 0, v180
	v_med3_f32 v66, v66, 0, v180
	v_cvt_pk_u8_f32 v118, v54, 0, 0
	v_cvt_pk_u8_f32 v119, v58, 0, 0
	v_cvt_pk_u8_f32 v120, v62, 0, 0
	v_cvt_pk_u8_f32 v121, v66, 0, 0
	v_med3_f32 v55, v55, 0, v180
	v_med3_f32 v59, v59, 0, v180
	v_med3_f32 v63, v63, 0, v180
	v_med3_f32 v67, v67, 0, v180
	v_cvt_pk_u8_f32 v118, v55, 1, v118
	v_cvt_pk_u8_f32 v119, v59, 1, v119
	v_cvt_pk_u8_f32 v120, v63, 1, v120
	v_cvt_pk_u8_f32 v121, v67, 1, v121
	s_waitcnt lgkmcnt(10)
	v_mfma_scale_f32_32x32x64_f8f6f4 v[86:101], v[190:197], v[138:145], v[34:49], v174, v174 op_sel_hi:[0,0,0]
	v_med3_f32 v56, v56, 0, v180
	v_med3_f32 v60, v60, 0, v180
	v_med3_f32 v64, v64, 0, v180
	v_med3_f32 v68, v68, 0, v180
	v_cvt_pk_u8_f32 v118, v56, 2, v118
	v_cvt_pk_u8_f32 v119, v60, 2, v119
	v_cvt_pk_u8_f32 v120, v64, 2, v120
	v_cvt_pk_u8_f32 v121, v68, 2, v121
	v_med3_f32 v57, v57, 0, v180
	v_med3_f32 v61, v61, 0, v180
	v_med3_f32 v65, v65, 0, v180
	v_med3_f32 v69, v69, 0, v180
	v_cvt_pk_u8_f32 v118, v57, 3, v118
	v_cvt_pk_u8_f32 v119, v61, 3, v119
	v_cvt_pk_u8_f32 v120, v65, 3, v120
	v_cvt_pk_u8_f32 v121, v69, 3, v121
	s_waitcnt lgkmcnt(8)
	v_mfma_scale_f32_32x32x64_f8f6f4 v[86:101], v[198:205], v[146:153], v[86:101], v174, v174 op_sel_hi:[0,0,0]
	v_med3_f32 v70, v70, 0, v180
	v_med3_f32 v74, v74, 0, v180
	v_med3_f32 v78, v78, 0, v180
	v_med3_f32 v82, v82, 0, v180
	v_cvt_pk_u8_f32 v122, v70, 0, 0
	v_cvt_pk_u8_f32 v123, v74, 0, 0
	v_cvt_pk_u8_f32 v124, v78, 0, 0
	v_cvt_pk_u8_f32 v125, v82, 0, 0
	v_med3_f32 v71, v71, 0, v180
	v_med3_f32 v75, v75, 0, v180
	v_med3_f32 v79, v79, 0, v180
	v_med3_f32 v83, v83, 0, v180
	v_cvt_pk_u8_f32 v122, v71, 1, v122
	v_cvt_pk_u8_f32 v123, v75, 1, v123
	v_cvt_pk_u8_f32 v124, v79, 1, v124
	v_cvt_pk_u8_f32 v125, v83, 1, v125
	s_waitcnt lgkmcnt(6)
	v_mfma_scale_f32_32x32x64_f8f6f4 v[102:117], v[206:213], v[138:145], v[34:49], v174, v174 op_sel_hi:[0,0,0]
	v_med3_f32 v72, v72, 0, v180
	v_med3_f32 v76, v76, 0, v180
	v_med3_f32 v80, v80, 0, v180
	v_med3_f32 v84, v84, 0, v180
	v_cvt_pk_u8_f32 v122, v72, 2, v122
	v_cvt_pk_u8_f32 v123, v76, 2, v123
	v_cvt_pk_u8_f32 v124, v80, 2, v124
	v_cvt_pk_u8_f32 v125, v84, 2, v125
	v_med3_f32 v73, v73, 0, v180
	v_med3_f32 v77, v77, 0, v180
	v_med3_f32 v81, v81, 0, v180
	v_med3_f32 v85, v85, 0, v180
	v_cvt_pk_u8_f32 v122, v73, 3, v122
	v_cvt_pk_u8_f32 v123, v77, 3, v123
	v_cvt_pk_u8_f32 v124, v81, 3, v124
	v_cvt_pk_u8_f32 v125, v85, 3, v125
	s_waitcnt lgkmcnt(4)
	v_mfma_scale_f32_32x32x64_f8f6f4 v[102:117], v[220:227], v[146:153], v[102:117], v174, v174 op_sel_hi:[0,0,0]
	s_nop 1
	s_waitcnt lgkmcnt(2)
	v_mfma_scale_f32_32x32x64_f8f6f4 v[18:33], v[228:235], v[118:125], v[18:33], v174, v174 op_sel_hi:[0,0,0] blgp:1
	s_waitcnt lgkmcnt(0)
	v_mfma_scale_f32_32x32x64_f8f6f4 v[2:17], v[236:243], v[118:125], v[2:17], v174, v174 op_sel_hi:[0,0,0] blgp:1
	v_mfma_scale_f32_16x16x128_f8f6f4 v[50:53], v[154:161], v[118:125], v[50:53], v174, v174 op_sel_hi:[0,0,0] blgp:1
	ds_read_b128 v[228:231], v167 offset:45056
	ds_read_b128 v[232:235], v167 offset:46080
	ds_read_b128 v[236:239], v167 offset:47104
	ds_read_b128 v[240:243], v167 offset:48128
	s_cbranch_vccnz .LBB0_1290
	s_waitcnt lgkmcnt(0)
	v_med3_f32 v86, v86, 0, v180
	v_med3_f32 v90, v90, 0, v180
	v_med3_f32 v94, v94, 0, v180
	v_med3_f32 v98, v98, 0, v180
	v_cvt_pk_u8_f32 v118, v86, 0, 0
	v_cvt_pk_u8_f32 v119, v90, 0, 0
	v_cvt_pk_u8_f32 v120, v94, 0, 0
	v_cvt_pk_u8_f32 v121, v98, 0, 0
	v_med3_f32 v87, v87, 0, v180
	v_med3_f32 v91, v91, 0, v180
	v_med3_f32 v95, v95, 0, v180
	v_med3_f32 v99, v99, 0, v180
	v_cvt_pk_u8_f32 v118, v87, 1, v118
	v_cvt_pk_u8_f32 v119, v91, 1, v119
	v_cvt_pk_u8_f32 v120, v95, 1, v120
	v_cvt_pk_u8_f32 v121, v99, 1, v121
	v_med3_f32 v88, v88, 0, v180
	v_med3_f32 v92, v92, 0, v180
	v_med3_f32 v96, v96, 0, v180
	v_med3_f32 v100, v100, 0, v180
	v_cvt_pk_u8_f32 v118, v88, 2, v118
	v_cvt_pk_u8_f32 v119, v92, 2, v119
	v_cvt_pk_u8_f32 v120, v96, 2, v120
	v_cvt_pk_u8_f32 v121, v100, 2, v121
	v_med3_f32 v89, v89, 0, v180
	v_med3_f32 v93, v93, 0, v180
	v_med3_f32 v97, v97, 0, v180
	v_med3_f32 v101, v101, 0, v180
	v_cvt_pk_u8_f32 v118, v89, 3, v118
	v_cvt_pk_u8_f32 v119, v93, 3, v119
	v_cvt_pk_u8_f32 v120, v97, 3, v120
	v_cvt_pk_u8_f32 v121, v101, 3, v121
	v_med3_f32 v102, v102, 0, v180
	v_med3_f32 v106, v106, 0, v180
	v_med3_f32 v110, v110, 0, v180
	v_med3_f32 v114, v114, 0, v180
	v_cvt_pk_u8_f32 v122, v102, 0, 0
	v_cvt_pk_u8_f32 v123, v106, 0, 0
	v_cvt_pk_u8_f32 v124, v110, 0, 0
	v_cvt_pk_u8_f32 v125, v114, 0, 0
	v_med3_f32 v103, v103, 0, v180
	v_med3_f32 v107, v107, 0, v180
	v_med3_f32 v111, v111, 0, v180
	v_med3_f32 v115, v115, 0, v180
	v_cvt_pk_u8_f32 v122, v103, 1, v122
	v_cvt_pk_u8_f32 v123, v107, 1, v123
	v_cvt_pk_u8_f32 v124, v111, 1, v124
	v_cvt_pk_u8_f32 v125, v115, 1, v125
	v_med3_f32 v104, v104, 0, v180
	v_med3_f32 v108, v108, 0, v180
	v_med3_f32 v112, v112, 0, v180
	v_med3_f32 v116, v116, 0, v180
	v_cvt_pk_u8_f32 v122, v104, 2, v122
	v_cvt_pk_u8_f32 v123, v108, 2, v123
	v_cvt_pk_u8_f32 v124, v112, 2, v124
	v_cvt_pk_u8_f32 v125, v116, 2, v125
	v_med3_f32 v105, v105, 0, v180
	v_med3_f32 v109, v109, 0, v180
	v_med3_f32 v113, v113, 0, v180
	v_med3_f32 v117, v117, 0, v180
	v_cvt_pk_u8_f32 v122, v105, 3, v122
	v_cvt_pk_u8_f32 v123, v109, 3, v123
	v_cvt_pk_u8_f32 v124, v113, 3, v124
	v_cvt_pk_u8_f32 v125, v117, 3, v125
	s_nop 1
	v_mfma_scale_f32_32x32x64_f8f6f4 v[18:33], v[228:235], v[118:125], v[18:33], v174, v174 op_sel_hi:[0,0,0] blgp:1
	v_mfma_scale_f32_32x32x64_f8f6f4 v[2:17], v[236:243], v[118:125], v[2:17], v174, v174 op_sel_hi:[0,0,0] blgp:1
	v_mfma_scale_f32_16x16x128_f8f6f4 v[50:53], v[154:161], v[118:125], v[50:53], v174, v174 op_sel_hi:[0,0,0] blgp:1
	s_branch .LBB0_1287

.LBB0_1298:
	s_ashr_i32 s10, s8, 6
	s_and_b32 s11, s8, 63
	s_lshr_b32 s8, s42, 1
	s_add_i32 s22, s8, s34
	s_lshl_b32 s8, s42, 5
	s_and_b32 s8, s8, 32
	s_add_i32 s26, s8, s31
	s_and_b64 s[8:9], s[16:17], exec
	s_cselect_b32 s9, s22, s10
	s_cselect_b32 s8, s26, s11
	s_ashr_i32 s10, s9, 3
	s_mul_i32 s11, s10, 0x4100
	s_lshl_b32 s8, s8, 8
	s_add_i32 s11, s11, s8
	v_add_u32_e32 v166, s11, v170
	v_ashrrev_i32_e32 v167, 31, v166
	s_and_b32 s43, s9, 7
	v_lshlrev_b64 v[2:3], 9, v[166:167]
	v_lshl_add_u64 v[2:3], s[18:19], 0, v[2:3]
	s_lshl_b32 s22, s43, 6
	v_lshl_add_u64 v[2:3], v[2:3], 0, s[22:23]
	s_lshl_b32 s22, s43, 2
	s_mul_i32 s44, s9, 0x104000
	s_mul_hi_i32 s45, s9, 0x104000
	s_add_u32 s53, s35, s44
	s_addc_u32 s55, s36, s45
	s_lshl_b32 s8, s10, 2
	s_bfe_u32 s10, s9, 0x20001
	s_or_b32 s50, s8, s10
	s_mul_hi_i32 s51, s50, 0x208000
	s_mul_i32 s50, s50, 0x208000
	s_add_u32 s62, s37, s50
	s_addc_u32 s63, s38, s51
	s_add_i32 s8, s9, 16
	s_ashr_i32 s9, s8, 31
	v_lshlrev_b64 v[4:5], 5, v[166:167]
	s_lshl_b64 s[8:9], s[8:9], 2
	v_lshl_add_u64 v[4:5], s[12:13], 0, v[4:5]
	s_add_u32 s8, s3, s8
	v_lshl_add_u64 v[4:5], v[4:5], 0, s[22:23]
	s_addc_u32 s9, s28, s9
	global_load_dword v42, v[4:5], off
	global_load_dword v18, v163, s[8:9]
	v_lshl_add_u64 v[2:3], v[2:3], 0, v[210:211]
	global_load_dwordx4 v[150:153], v[2:3], off offset:16
	global_load_dwordx4 v[146:149], v[2:3], off
	v_readfirstlane_b32 s8, v1
	s_ashr_i32 s26, s8, 6
	s_cmp_lt_i32 s26, 3
	s_mul_i32 s46, s26, 0xc00
	s_cselect_b64 s[10:11], -1, 0
	s_add_i32 s52, s46, 0xffffe000
	s_add_u32 s22, s62, s52
	s_addc_u32 s27, s63, 0
	s_ashr_i32 s47, s46, 31
	s_add_u32 s49, s53, s46
	s_addc_u32 s64, s55, s47
	s_and_b64 s[8:9], s[10:11], exec
	s_cselect_b32 s9, s64, s27
	s_cselect_b32 s8, s49, s22
	s_add_i32 s65, s46, 0x400
	s_add_i32 s22, s46, 0
	s_ashr_i32 s66, s65, 31
	s_add_u32 s27, s49, 0x400
	s_addc_u32 s67, s64, 0
	s_add_i32 s48, s46, 0xffffe400
	s_add_u32 s68, s62, s48
	s_addc_u32 s69, s63, 0
	v_lshl_add_u64 v[2:3], s[8:9], 0, v[164:165]
	s_mov_b32 m0, s22
	s_and_b64 s[8:9], s[10:11], exec
	v_lshrrev_b32 v154, 2, v0
	v_xor_b32 v154, v154, v0
	v_bfe_u32 v154, v154, 2, 1
	v_add_u32 v154, -1, v154
	v_and_b32 v154, 0x38383838, v154
	v_mov_b32 v155, v154
	v_mov_b32 v156, v154
	v_mov_b32 v157, v154
	v_mov_b32 v158, v154
	v_mov_b32 v159, v154
	v_mov_b32 v160, v154
	v_mov_b32 v161, v154
	global_load_lds_dwordx4 v[2:3], off
	s_cselect_b32 s9, s67, s69
	s_cselect_b32 s8, s27, s68
	s_add_i32 m0, s22, 0x400
	s_cmp_lt_i32 s26, 2
	s_cselect_b64 s[26:27], -1, 0
	s_add_i32 s67, s46, 0x800
	s_ashr_i32 s68, s67, 31
	s_add_u32 s69, s49, 0x800
	s_addc_u32 s64, s64, 0
	s_add_i32 s49, s46, 0xffffe800
	s_add_u32 s70, s62, s49
	s_addc_u32 s71, s63, 0
	v_lshl_add_u64 v[2:3], s[8:9], 0, v[164:165]
	s_and_b64 s[8:9], s[26:27], exec
	global_load_lds_dwordx4 v[2:3], off
	s_cselect_b32 s9, s64, s71
	s_cselect_b32 s8, s69, s70
	s_add_i32 m0, s22, 0x800
	s_add_u32 s62, s62, 0x4000
	s_addc_u32 s63, s63, 0
	s_add_u32 s53, s53, 0x2000
	s_addc_u32 s55, s55, 0
	s_add_u32 s64, s53, s46
	s_addc_u32 s69, s55, s47
	s_add_u32 s70, s62, s52
	s_addc_u32 s71, s63, 0
	v_lshl_add_u64 v[2:3], s[8:9], 0, v[164:165]
	s_and_b64 s[8:9], s[10:11], exec
	global_load_lds_dwordx4 v[2:3], off
	s_cselect_b32 s9, s69, s71
	s_cselect_b32 s8, s64, s70
	s_add_i32 m0, s22, 0x6000
	s_add_u32 s64, s53, s65
	s_addc_u32 s65, s55, s66
	s_add_u32 s66, s62, s48
	s_addc_u32 s69, s63, 0
	v_lshl_add_u64 v[2:3], s[8:9], 0, v[164:165]
	s_and_b64 s[8:9], s[10:11], exec
	global_load_lds_dwordx4 v[2:3], off
	s_cselect_b32 s9, s65, s69
	s_cselect_b32 s8, s64, s66
	s_add_i32 m0, s22, 0x6400
	s_add_u32 s53, s53, s67
	s_addc_u32 s55, s55, s68
	s_add_u32 s62, s62, s49
	s_addc_u32 s63, s63, 0
	v_lshl_add_u64 v[2:3], s[8:9], 0, v[164:165]
	s_and_b64 s[8:9], s[26:27], exec
	s_cselect_b32 s9, s55, s63
	s_cselect_b32 s8, s53, s62
	global_load_lds_dwordx4 v[2:3], off
	v_lshl_add_u64 v[2:3], s[8:9], 0, v[164:165]
	s_add_i32 m0, s22, 0x6800
	s_waitcnt vmcnt(0)
	v_mul_f32_e32 v19, 0x4f800000, v18
	global_load_lds_dwordx4 v[2:3], off
	s_waitcnt vmcnt(3)
	s_barrier
	ds_read_b128 v[2:5], v171
	ds_read_b128 v[6:9], v171 offset:1024
	v_cmp_gt_f32_e32 vcc, s39, v18
	s_waitcnt lgkmcnt(0)
	v_mfma_scale_f32_32x32x64_f8f6f4 v[2:17], v[2:9], v[146:153], 0, v174, v174 op_sel_hi:[0,0,0]
	v_cndmask_b32_e32 v43, v18, v19, vcc
	v_sqrt_f32_e32 v26, v43
	ds_read_b128 v[18:21], v171 offset:2048
	ds_read_b128 v[22:25], v171 offset:3072
	s_add_u32 s44, s44, s46
	s_addc_u32 s45, s45, s47
	v_add_u32_e32 v27, -1, v26
	v_fma_f32 v28, -v27, v26, v43
	v_cmp_ge_f32_e64 s[8:9], 0, v28
	v_add_u32_e32 v28, 1, v26
	s_add_u32 s46, s50, s49
	v_cndmask_b32_e64 v27, v26, v27, s[8:9]
	v_fma_f32 v26, -v28, v26, v43
	v_cmp_lt_f32_e64 s[8:9], 0, v26
	s_addc_u32 s47, s51, 0
	s_add_u32 s48, s50, s48
	v_cndmask_b32_e64 v34, v27, v28, s[8:9]
	s_waitcnt lgkmcnt(0)
	v_mfma_scale_f32_32x32x64_f8f6f4 v[18:33], v[18:25], v[146:153], 0, v174, v174 op_sel_hi:[0,0,0]
	v_max3_f32 v2, v2, s40, v3
	v_max3_f32 v2, v2, v4, v5
	v_max3_f32 v2, v2, v6, v7
	v_max3_f32 v2, v2, v8, v9
	v_mul_f32_e32 v35, 0x37800000, v34
	v_max3_f32 v2, v2, v10, v11
	v_cndmask_b32_e32 v44, v34, v35, vcc
	ds_read_b128 v[34:37], v171 offset:4096
	ds_read_b128 v[38:41], v171 offset:5120
	v_max3_f32 v2, v2, v12, v13
	v_max3_f32 v2, v2, v14, v15
	v_max3_f32 v2, v2, v16, v17
	v_cmp_lt_i32_e32 vcc, v176, v177
	s_addc_u32 s49, s51, 0
	s_add_u32 s50, s50, s52
	s_addc_u32 s51, s51, 0
	s_nop 3
	v_max3_f32 v2, v2, v18, v19
	v_max3_f32 v2, v2, v20, v21
	v_max3_f32 v18, v2, v22, v23
	s_waitcnt lgkmcnt(0)
	v_mfma_scale_f32_32x32x64_f8f6f4 v[2:17], v[34:41], v[146:153], 0, v174, v174 op_sel_hi:[0,0,0]
	v_max3_f32 v18, v18, v24, v25
	v_max3_f32 v18, v18, v26, v27
	v_max3_f32 v18, v18, v28, v29
	v_max3_f32 v18, v18, v30, v31
	v_max3_f32 v26, v18, v32, v33
	ds_read_b128 v[18:21], v171 offset:6144
	ds_read_b128 v[22:25], v171 offset:7168
	s_mov_b32 s55, 0
	s_mov_b32 s52, 0
	v_mov_b32_e32 v27, v163
	v_mov_b32_e32 v28, v163
	v_mov_b32_e32 v29, v163
	v_mov_b32_e32 v30, v163
	v_mov_b32_e32 v31, v163
	v_mov_b32_e32 v32, v163
	v_mov_b32_e32 v33, v163
	s_nop 3
	v_max3_f32 v2, v26, v2, v3
	v_max3_f32 v2, v2, v4, v5
	v_max3_f32 v2, v2, v6, v7
	v_max3_f32 v2, v2, v8, v9
	v_max3_f32 v2, v2, v10, v11
	v_max3_f32 v2, v2, v12, v13
	v_max3_f32 v2, v2, v14, v15
	v_max3_f32 v26, v2, v16, v17
	s_waitcnt lgkmcnt(0)
	v_mfma_scale_f32_32x32x64_f8f6f4 v[2:17], v[18:25], v[146:153], 0, v174, v174 op_sel_hi:[0,0,0]
	v_mov_b32_e32 v18, 0
	v_mov_b32_e32 v19, v163
	v_mov_b32_e32 v20, v163
	v_mov_b32_e32 v21, v163
	v_mov_b32_e32 v22, v163
	v_mov_b32_e32 v23, v163
	v_mov_b32_e32 v24, v163
	v_mov_b32_e32 v25, v163
	v_mov_b32_e32 v34, 0
	v_mov_b32_e32 v35, v163
	v_mov_b32_e32 v36, v163
	v_mov_b32_e32 v37, v163
	v_mov_b32_e32 v38, v163
	v_mov_b32_e32 v39, v163
	v_mov_b32_e32 v40, v163
	s_nop 4
	v_max3_f32 v2, v26, v2, v3
	v_max3_f32 v2, v2, v4, v5
	v_max3_f32 v2, v2, v6, v7
	v_max3_f32 v2, v2, v8, v9
	v_max3_f32 v2, v2, v10, v11
	v_max3_f32 v2, v2, v12, v13
	v_max3_f32 v2, v2, v14, v15
	v_cndmask_b32_e32 v3, v175, v176, vcc
	v_max3_f32 v2, v2, v16, v17
	v_lshlrev_b32_e32 v3, 2, v3
	ds_bpermute_b32 v3, v3, v2
	v_cmp_class_f32_e32 vcc, v43, v172
	v_mov_b32_e32 v5, v163
	v_mov_b32_e32 v6, v163
	v_cndmask_b32_e32 v4, v44, v43, vcc
	s_waitcnt lgkmcnt(0)
	v_max_f32_e32 v3, v3, v3
	v_mul_f32_e32 v4, v42, v4
	v_max_f32_e32 v2, v2, v3
	v_fmamk_f32 v4, v4, 0x3f90a3d7, v173
	v_add_f32_e32 v2, 0x42800000, v2
	v_min_f32_e32 v2, v4, v2
	v_add_f32_e32 v2, 0xc2ec0000, v2
	v_xor_b32_e32 v50, 0x80000000, v2
	v_mov_b32_e32 v51, v50
	v_mov_b32_e32 v52, v50
	v_mov_b32_e32 v53, v50
	v_mov_b32_e32 v54, v50
	v_mov_b32_e32 v55, v50
	v_mov_b32_e32 v56, v50
	v_mov_b32_e32 v57, v50
	v_mov_b32_e32 v58, v50
	v_mov_b32_e32 v59, v50
	v_mov_b32_e32 v60, v50
	v_mov_b32_e32 v61, v50
	v_mov_b32_e32 v62, v50
	v_mov_b32_e32 v63, v50
	v_mov_b32_e32 v64, v50
	v_mov_b32_e32 v65, v50
	v_mov_b32_e32 v2, 0
	v_mov_b32_e32 v3, v163
	v_mov_b32_e32 v4, v163
	v_mov_b32_e32 v7, v163
	v_mov_b32_e32 v8, v163
	v_mov_b32_e32 v9, v163
	v_mov_b32_e32 v10, v163
	v_mov_b32_e32 v11, v163
	v_mov_b32_e32 v12, v163
	v_mov_b32_e32 v13, v163
	v_mov_b32_e32 v14, v163
	v_mov_b32_e32 v15, v163
	v_mov_b32_e32 v16, v163
	v_mov_b32_e32 v17, v163
	v_mov_b32_e32 v26, v163
	v_mov_b32_e32 v41, v163
	v_mov_b32_e32 v42, v163
	v_mov_b32_e32 v43, v163
	v_mov_b32_e32 v44, v163
	v_mov_b32_e32 v45, v163
	v_mov_b32_e32 v46, v163
	v_mov_b32_e32 v47, v163
	v_mov_b32_e32 v48, v163
	v_mov_b32_e32 v49, v163
	v_mov_b32_e32 v66, 0
	v_mov_b32_e32 v67, v163
	v_mov_b32_e32 v68, v163
	v_mov_b32_e32 v69, v163
	v_mov_b32_e32 v70, v163
	v_mov_b32_e32 v71, v163
	v_mov_b32_e32 v72, v163
	v_mov_b32_e32 v73, v163
	v_mov_b32_e32 v74, v163
	v_mov_b32_e32 v75, v163
	v_mov_b32_e32 v76, v163
	v_mov_b32_e32 v77, v163
	v_mov_b32_e32 v78, v163
	v_mov_b32_e32 v79, v163
	v_mov_b32_e32 v80, v163
	v_mov_b32_e32 v81, v163
	v_mov_b32_e32 v82, 0
	v_mov_b32_e32 v83, v163
	v_mov_b32_e32 v84, v163
	v_mov_b32_e32 v85, v163
	v_mov_b32_e32 v86, v163
	v_mov_b32_e32 v87, v163
	v_mov_b32_e32 v88, v163
	v_mov_b32_e32 v89, v163
	v_mov_b32_e32 v90, v163
	v_mov_b32_e32 v91, v163
	v_mov_b32_e32 v92, v163
	v_mov_b32_e32 v93, v163
	v_mov_b32_e32 v94, v163
	v_mov_b32_e32 v95, v163
	v_mov_b32_e32 v96, v163
	v_mov_b32_e32 v97, v163
	v_mov_b32_e32 v142, v210
	v_mov_b32_e32 v143, v211
	v_mov_b32_e32 v144, v218
	v_mov_b32_e32 v145, v219
	v_mov_b32_e32 v118, v163
	v_mov_b32_e32 v119, v163
	v_mov_b32_e32 v120, v163
	v_mov_b32_e32 v121, v163
	v_mov_b32_e32 v122, v163
	v_mov_b32_e32 v123, v163
	v_mov_b32_e32 v124, v163
	v_mov_b32_e32 v125, v163
	v_mov_b32_e32 v126, v163
	v_mov_b32_e32 v127, v163
	v_mov_b32_e32 v128, v163
	v_mov_b32_e32 v129, v163
	v_mov_b32_e32 v130, v163
	v_mov_b32_e32 v131, v163
	v_mov_b32_e32 v132, v163
	v_mov_b32_e32 v133, v163
	v_mov_b32_e32 v180, v163
	v_mov_b32_e32 v181, v163
	v_mov_b32_e32 v182, v163
	v_mov_b32_e32 v183, v163
	v_mov_b32_e32 v184, v163
	v_mov_b32_e32 v185, v163
	v_mov_b32_e32 v186, v163
	v_mov_b32_e32 v187, v163
	v_mov_b32_e32 v188, v163
	v_mov_b32_e32 v189, v163
	v_mov_b32_e32 v190, v163
	v_mov_b32_e32 v191, v163
	v_mov_b32_e32 v192, v163
	v_mov_b32_e32 v193, v163
	v_mov_b32_e32 v194, v163
	v_mov_b32_e32 v195, v163
	v_mov_b32_e32 v220, v163
	v_mov_b32_e32 v221, v163
	v_mov_b32_e32 v222, v163
	v_mov_b32_e32 v223, v163
	v_mov_b32_e32 v224, v163
	v_mov_b32_e32 v225, v163
	v_mov_b32_e32 v226, v163
	v_mov_b32_e32 v227, v163
	v_mov_b32_e32 v228, v163
	v_mov_b32_e32 v229, v163
	v_mov_b32_e32 v230, v163
	v_mov_b32_e32 v231, v163
	v_mov_b32_e32 v232, v163
	v_mov_b32_e32 v233, v163
	v_mov_b32_e32 v234, v163
	v_mov_b32_e32 v235, v163
	v_mov_b32_e32 v236, v163
	v_mov_b32_e32 v237, v163
	v_mov_b32_e32 v238, v163
	v_mov_b32_e32 v239, v163
	v_mov_b32_e32 v240, v163
	v_mov_b32_e32 v241, v163
	v_mov_b32_e32 v242, v163
	v_mov_b32_e32 v243, v163
	v_mov_b32_e32 v244, v163
	v_mov_b32_e32 v245, v163
	v_mov_b32_e32 v246, v163
	v_mov_b32_e32 v247, v163
	v_mov_b32_e32 v248, v163
	v_mov_b32_e32 v249, v163
	v_mov_b32_e32 v250, v163
	v_mov_b32_e32 v251, v163
	s_branch .LBB0_1300
.LBB0_1300:
	s_waitcnt vmcnt(0) lgkmcnt(0)
	s_barrier
	s_cmpk_gt_u32 s52, 0x7f
	s_cselect_b64 s[8:9], -1, 0
	s_xor_b32 s53, s55, 2
	s_mul_i32 s100, s55, 0x6000
	s_add_i32 s52, s52, 2
	s_andn2_b64 vcc, exec, s[8:9]
	v_add_u32_e32 v179, s100, v171
	s_mov_b32 s55, s53
.LBB0_1299:
	ds_read_b128 v[204:207], v179
	ds_read_b128 v[208:211], v179 offset:1024
	ds_read_b128 v[212:215], v179 offset:2048
	ds_read_b128 v[216:219], v179 offset:3072
	v_med3_f32 v118, v118, 0, v178
	v_med3_f32 v122, v122, 0, v178
	v_med3_f32 v126, v126, 0, v178
	v_med3_f32 v130, v130, 0, v178
	v_cvt_pk_u8_f32 v196, v118, 0, 0
	v_cvt_pk_u8_f32 v197, v122, 0, 0
	v_cvt_pk_u8_f32 v198, v126, 0, 0
	v_cvt_pk_u8_f32 v199, v130, 0, 0
	v_med3_f32 v119, v119, 0, v178
	v_med3_f32 v123, v123, 0, v178
	v_med3_f32 v127, v127, 0, v178
	v_med3_f32 v131, v131, 0, v178
	v_cvt_pk_u8_f32 v196, v119, 1, v196
	v_cvt_pk_u8_f32 v197, v123, 1, v197
	v_cvt_pk_u8_f32 v198, v127, 1, v198
	v_cvt_pk_u8_f32 v199, v131, 1, v199
	s_waitcnt lgkmcnt(2)
	v_mfma_scale_f32_32x32x64_f8f6f4 v[86:101], v[204:211], v[146:153], v[50:65], v174, v174 op_sel_hi:[0,0,0]
	v_med3_f32 v120, v120, 0, v178
	v_med3_f32 v124, v124, 0, v178
	v_med3_f32 v128, v128, 0, v178
	v_med3_f32 v132, v132, 0, v178
	v_cvt_pk_u8_f32 v196, v120, 2, v196
	v_cvt_pk_u8_f32 v197, v124, 2, v197
	v_cvt_pk_u8_f32 v198, v128, 2, v198
	v_cvt_pk_u8_f32 v199, v132, 2, v199
	v_med3_f32 v121, v121, 0, v178
	v_med3_f32 v125, v125, 0, v178
	v_med3_f32 v129, v129, 0, v178
	v_med3_f32 v133, v133, 0, v178
	v_cvt_pk_u8_f32 v196, v121, 3, v196
	v_cvt_pk_u8_f32 v197, v125, 3, v197
	v_cvt_pk_u8_f32 v198, v129, 3, v198
	v_cvt_pk_u8_f32 v199, v133, 3, v199
	v_med3_f32 v180, v180, 0, v178
	v_med3_f32 v184, v184, 0, v178
	v_med3_f32 v188, v188, 0, v178
	v_med3_f32 v192, v192, 0, v178
	v_cvt_pk_u8_f32 v200, v180, 0, 0
	v_cvt_pk_u8_f32 v201, v184, 0, 0
	v_cvt_pk_u8_f32 v202, v188, 0, 0
	v_cvt_pk_u8_f32 v203, v192, 0, 0
	s_waitcnt lgkmcnt(0)
	v_mfma_scale_f32_32x32x64_f8f6f4 v[102:117], v[212:219], v[146:153], v[50:65], v174, v174 op_sel_hi:[0,0,0]
	v_med3_f32 v181, v181, 0, v178
	v_med3_f32 v185, v185, 0, v178
	v_med3_f32 v189, v189, 0, v178
	v_med3_f32 v193, v193, 0, v178
	v_cvt_pk_u8_f32 v200, v181, 1, v200
	v_cvt_pk_u8_f32 v201, v185, 1, v201
	v_cvt_pk_u8_f32 v202, v189, 1, v202
	v_cvt_pk_u8_f32 v203, v193, 1, v203
	v_med3_f32 v182, v182, 0, v178
	v_med3_f32 v186, v186, 0, v178
	v_med3_f32 v190, v190, 0, v178
	v_med3_f32 v194, v194, 0, v178
	v_cvt_pk_u8_f32 v200, v182, 2, v200
	v_cvt_pk_u8_f32 v201, v186, 2, v201
	v_cvt_pk_u8_f32 v202, v190, 2, v202
	v_cvt_pk_u8_f32 v203, v194, 2, v203
	v_med3_f32 v183, v183, 0, v178
	v_med3_f32 v187, v187, 0, v178
	v_med3_f32 v191, v191, 0, v178
	v_med3_f32 v195, v195, 0, v178
	v_cvt_pk_u8_f32 v200, v183, 3, v200
	v_cvt_pk_u8_f32 v201, v187, 3, v201
	v_cvt_pk_u8_f32 v202, v191, 3, v202
	v_cvt_pk_u8_f32 v203, v195, 3, v203
	s_nop 1
	v_mfma_scale_f32_32x32x64_f8f6f4 v[66:81], v[220:227], v[196:203], v[66:81], v174, v174 op_sel_hi:[0,0,0] blgp:1
	ds_read_b128 v[204:207], v179 offset:4096
	ds_read_b128 v[208:211], v179 offset:5120
	ds_read_b128 v[212:215], v179 offset:6144
	ds_read_b128 v[216:219], v179 offset:7168
	s_cbranch_vccz .Ldma_dif0_skip0
	s_add_u32 s65, s29, s44
	s_addc_u32 s66, s30, s45
	s_add_u32 s67, s65, 0x36532100
	s_addc_u32 s68, s66, 0
	s_add_u32 s69, s29, s50
	s_addc_u32 s70, s30, s51
	s_add_u32 s71, s69, 0x385b6100
	s_addc_u32 s72, s70, 0
	s_mul_i32 s64, s53, 0x6000
	s_and_b64 s[62:63], s[10:11], exec
	s_cselect_b32 s63, s68, s72
	s_cselect_b32 s62, s67, s71
	s_add_i32 s64, s22, s64
	s_add_u32 s67, s65, 0x36532500
	s_addc_u32 s68, s66, 0
	s_add_u32 s71, s29, s48
	s_addc_u32 s72, s30, s49
	s_add_u32 s73, s71, 0x385b6100
	s_addc_u32 s74, s72, 0
	s_mov_b32 m0, s64
	s_nop 0
	global_load_lds_dwordx4 v164, s[62:63]
.Ldma_dif0_skip0:
	v_mfma_scale_f32_32x32x64_f8f6f4 v[34:49], v[228:235], v[196:203], v[34:49], v174, v174 op_sel_hi:[0,0,0] blgp:1
	ds_read_b128 v[220:223], v179 offset:8192
	ds_read_b128 v[224:227], v179 offset:9216
	s_cbranch_vccz .Ldma_dif0_skip1
	s_and_b64 s[62:63], s[10:11], exec
	s_cselect_b32 s63, s68, s74
	s_cselect_b32 s62, s67, s73
	s_add_i32 m0, s64, 0x400
	s_add_u32 s67, s65, 0x36532900
	s_addc_u32 s68, s66, 0
	s_add_u32 s73, s29, s46
	s_addc_u32 s74, s30, s47
	s_add_u32 s75, s73, 0x385b6100
	s_addc_u32 s76, s74, 0
	global_load_lds_dwordx4 v164, s[62:63]
.Ldma_dif0_skip1:
	v_mfma_scale_f32_32x32x64_f8f6f4 v[18:33], v[236:243], v[196:203], v[18:33], v174, v174 op_sel_hi:[0,0,0] blgp:1
	ds_read_b128 v[228:231], v179 offset:10240
	ds_read_b128 v[232:235], v179 offset:11264
	v_mfma_scale_f32_32x32x64_f8f6f4 v[2:17], v[244:251], v[196:203], v[2:17], v174, v174 op_sel_hi:[0,0,0] blgp:1
	ds_read_b128 v[236:239], v179 offset:12288
	ds_read_b128 v[240:243], v179 offset:13312
	v_mfma_scale_f32_16x16x128_f8f6f4 v[82:85], v[154:161], v[196:203], v[82:85], v174, v174 op_sel_hi:[0,0,0] blgp:1
	ds_read_b128 v[244:247], v179 offset:14336
	ds_read_b128 v[248:251], v179 offset:15360
	v_med3_f32 v86, v86, 0, v178
	v_med3_f32 v90, v90, 0, v178
	v_med3_f32 v94, v94, 0, v178
	v_med3_f32 v98, v98, 0, v178
	v_cvt_pk_u8_f32 v196, v86, 0, 0
	v_cvt_pk_u8_f32 v197, v90, 0, 0
	v_cvt_pk_u8_f32 v198, v94, 0, 0
	v_cvt_pk_u8_f32 v199, v98, 0, 0
	v_med3_f32 v87, v87, 0, v178
	v_med3_f32 v91, v91, 0, v178
	v_med3_f32 v95, v95, 0, v178
	v_med3_f32 v99, v99, 0, v178
	v_cvt_pk_u8_f32 v196, v87, 1, v196
	v_cvt_pk_u8_f32 v197, v91, 1, v197
	v_cvt_pk_u8_f32 v198, v95, 1, v198
	v_cvt_pk_u8_f32 v199, v99, 1, v199
	s_waitcnt lgkmcnt(10)
	v_mfma_scale_f32_32x32x64_f8f6f4 v[118:133], v[204:211], v[146:153], v[50:65], v174, v174 op_sel_hi:[0,0,0]
	v_med3_f32 v88, v88, 0, v178
	v_med3_f32 v92, v92, 0, v178
	v_med3_f32 v96, v96, 0, v178
	v_med3_f32 v100, v100, 0, v178
	v_cvt_pk_u8_f32 v196, v88, 2, v196
	v_cvt_pk_u8_f32 v197, v92, 2, v197
	v_cvt_pk_u8_f32 v198, v96, 2, v198
	v_cvt_pk_u8_f32 v199, v100, 2, v199
	v_med3_f32 v89, v89, 0, v178
	v_med3_f32 v93, v93, 0, v178
	v_med3_f32 v97, v97, 0, v178
	v_med3_f32 v101, v101, 0, v178
	v_cvt_pk_u8_f32 v196, v89, 3, v196
	v_cvt_pk_u8_f32 v197, v93, 3, v197
	v_cvt_pk_u8_f32 v198, v97, 3, v198
	v_cvt_pk_u8_f32 v199, v101, 3, v199
	v_med3_f32 v102, v102, 0, v178
	v_med3_f32 v106, v106, 0, v178
	v_med3_f32 v110, v110, 0, v178
	v_med3_f32 v114, v114, 0, v178
	v_cvt_pk_u8_f32 v200, v102, 0, 0
	v_cvt_pk_u8_f32 v201, v106, 0, 0
	v_cvt_pk_u8_f32 v202, v110, 0, 0
	v_cvt_pk_u8_f32 v203, v114, 0, 0
	s_waitcnt lgkmcnt(8)
	v_mfma_scale_f32_32x32x64_f8f6f4 v[180:195], v[212:219], v[146:153], v[50:65], v174, v174 op_sel_hi:[0,0,0]
	v_med3_f32 v103, v103, 0, v178
	v_med3_f32 v107, v107, 0, v178
	v_med3_f32 v111, v111, 0, v178
	v_med3_f32 v115, v115, 0, v178
	v_cvt_pk_u8_f32 v200, v103, 1, v200
	v_cvt_pk_u8_f32 v201, v107, 1, v201
	v_cvt_pk_u8_f32 v202, v111, 1, v202
	v_cvt_pk_u8_f32 v203, v115, 1, v203
	v_med3_f32 v104, v104, 0, v178
	v_med3_f32 v108, v108, 0, v178
	v_med3_f32 v112, v112, 0, v178
	v_med3_f32 v116, v116, 0, v178
	v_cvt_pk_u8_f32 v200, v104, 2, v200
	v_cvt_pk_u8_f32 v201, v108, 2, v201
	v_cvt_pk_u8_f32 v202, v112, 2, v202
	v_cvt_pk_u8_f32 v203, v116, 2, v203
	v_med3_f32 v105, v105, 0, v178
	v_med3_f32 v109, v109, 0, v178
	v_med3_f32 v113, v113, 0, v178
	v_med3_f32 v117, v117, 0, v178
	v_cvt_pk_u8_f32 v200, v105, 3, v200
	v_cvt_pk_u8_f32 v201, v109, 3, v201
	v_cvt_pk_u8_f32 v202, v113, 3, v202
	v_cvt_pk_u8_f32 v203, v117, 3, v203
	s_nop 1
	s_waitcnt lgkmcnt(6)
	v_mfma_scale_f32_32x32x64_f8f6f4 v[66:81], v[220:227], v[196:203], v[66:81], v174, v174 op_sel_hi:[0,0,0] blgp:1
	ds_read_b128 v[204:207], v179 offset:24576
	ds_read_b128 v[208:211], v179 offset:25600
	ds_read_b128 v[212:215], v179 offset:26624
	ds_read_b128 v[216:219], v179 offset:27648
	s_cbranch_vccz .Ldma_dif0_skip2
	s_and_b64 s[62:63], s[26:27], exec
	s_cselect_b32 s63, s68, s76
	s_cselect_b32 s62, s67, s75
	s_add_i32 m0, s64, 0x800
	s_add_u32 s67, s65, 0x36534100
	s_addc_u32 s68, s66, 0
	s_add_u32 s69, s69, 0x385ba100
	s_addc_u32 s70, s70, 0
	global_load_lds_dwordx4 v164, s[62:63]
.Ldma_dif0_skip2:
	s_waitcnt lgkmcnt(8)
	v_mfma_scale_f32_32x32x64_f8f6f4 v[34:49], v[228:235], v[196:203], v[34:49], v174, v174 op_sel_hi:[0,0,0] blgp:1
	ds_read_b128 v[220:223], v179 offset:16384
	ds_read_b128 v[224:227], v179 offset:17408
	s_cbranch_vccz .Ldma_dif0_skip3
	s_and_b64 s[62:63], s[10:11], exec
	s_cselect_b32 s63, s68, s70
	s_cselect_b32 s62, s67, s69
	s_add_i32 m0, s64, 0x6000
	s_add_u32 s67, s65, 0x36534500
	s_addc_u32 s68, s66, 0
	s_add_u32 s69, s71, 0x385ba100
	s_addc_u32 s70, s72, 0
	global_load_lds_dwordx4 v164, s[62:63]
.Ldma_dif0_skip3:
	s_waitcnt lgkmcnt(8)
	v_mfma_scale_f32_32x32x64_f8f6f4 v[18:33], v[236:243], v[196:203], v[18:33], v174, v174 op_sel_hi:[0,0,0] blgp:1
	ds_read_b128 v[228:231], v179 offset:18432
	ds_read_b128 v[232:235], v179 offset:19456
	s_waitcnt lgkmcnt(8)
	v_mfma_scale_f32_32x32x64_f8f6f4 v[2:17], v[244:251], v[196:203], v[2:17], v174, v174 op_sel_hi:[0,0,0] blgp:1
	ds_read_b128 v[236:239], v179 offset:20480
	ds_read_b128 v[240:243], v179 offset:21504
	v_mfma_scale_f32_16x16x128_f8f6f4 v[82:85], v[154:161], v[196:203], v[82:85], v174, v174 op_sel_hi:[0,0,0] blgp:1
	ds_read_b128 v[244:247], v179 offset:22528
	ds_read_b128 v[248:251], v179 offset:23552
	v_med3_f32 v118, v118, 0, v178
	v_med3_f32 v122, v122, 0, v178
	v_med3_f32 v126, v126, 0, v178
	v_med3_f32 v130, v130, 0, v178
	v_cvt_pk_u8_f32 v196, v118, 0, 0
	v_cvt_pk_u8_f32 v197, v122, 0, 0
	v_cvt_pk_u8_f32 v198, v126, 0, 0
	v_cvt_pk_u8_f32 v199, v130, 0, 0
	v_med3_f32 v119, v119, 0, v178
	v_med3_f32 v123, v123, 0, v178
	v_med3_f32 v127, v127, 0, v178
	v_med3_f32 v131, v131, 0, v178
	v_cvt_pk_u8_f32 v196, v119, 1, v196
	v_cvt_pk_u8_f32 v197, v123, 1, v197
	v_cvt_pk_u8_f32 v198, v127, 1, v198
	v_cvt_pk_u8_f32 v199, v131, 1, v199
	s_waitcnt lgkmcnt(10)
	v_mfma_scale_f32_32x32x64_f8f6f4 v[86:101], v[204:211], v[146:153], v[50:65], v174, v174 op_sel_hi:[0,0,0]
	v_med3_f32 v120, v120, 0, v178
	v_med3_f32 v124, v124, 0, v178
	v_med3_f32 v128, v128, 0, v178
	v_med3_f32 v132, v132, 0, v178
	v_cvt_pk_u8_f32 v196, v120, 2, v196
	v_cvt_pk_u8_f32 v197, v124, 2, v197
	v_cvt_pk_u8_f32 v198, v128, 2, v198
	v_cvt_pk_u8_f32 v199, v132, 2, v199
	v_med3_f32 v121, v121, 0, v178
	v_med3_f32 v125, v125, 0, v178
	v_med3_f32 v129, v129, 0, v178
	v_med3_f32 v133, v133, 0, v178
	v_cvt_pk_u8_f32 v196, v121, 3, v196
	v_cvt_pk_u8_f32 v197, v125, 3, v197
	v_cvt_pk_u8_f32 v198, v129, 3, v198
	v_cvt_pk_u8_f32 v199, v133, 3, v199
	v_med3_f32 v180, v180, 0, v178
	v_med3_f32 v184, v184, 0, v178
	v_med3_f32 v188, v188, 0, v178
	v_med3_f32 v192, v192, 0, v178
	v_cvt_pk_u8_f32 v200, v180, 0, 0
	v_cvt_pk_u8_f32 v201, v184, 0, 0
	v_cvt_pk_u8_f32 v202, v188, 0, 0
	v_cvt_pk_u8_f32 v203, v192, 0, 0
	s_waitcnt lgkmcnt(8)
	v_mfma_scale_f32_32x32x64_f8f6f4 v[102:117], v[212:219], v[146:153], v[50:65], v174, v174 op_sel_hi:[0,0,0]
	v_med3_f32 v181, v181, 0, v178
	v_med3_f32 v185, v185, 0, v178
	v_med3_f32 v189, v189, 0, v178
	v_med3_f32 v193, v193, 0, v178
	v_cvt_pk_u8_f32 v200, v181, 1, v200
	v_cvt_pk_u8_f32 v201, v185, 1, v201
	v_cvt_pk_u8_f32 v202, v189, 1, v202
	v_cvt_pk_u8_f32 v203, v193, 1, v203
	v_med3_f32 v182, v182, 0, v178
	v_med3_f32 v186, v186, 0, v178
	v_med3_f32 v190, v190, 0, v178
	v_med3_f32 v194, v194, 0, v178
	v_cvt_pk_u8_f32 v200, v182, 2, v200
	v_cvt_pk_u8_f32 v201, v186, 2, v201
	v_cvt_pk_u8_f32 v202, v190, 2, v202
	v_cvt_pk_u8_f32 v203, v194, 2, v203
	v_med3_f32 v183, v183, 0, v178
	v_med3_f32 v187, v187, 0, v178
	v_med3_f32 v191, v191, 0, v178
	v_med3_f32 v195, v195, 0, v178
	v_cvt_pk_u8_f32 v200, v183, 3, v200
	v_cvt_pk_u8_f32 v201, v187, 3, v201
	v_cvt_pk_u8_f32 v202, v191, 3, v202
	v_cvt_pk_u8_f32 v203, v195, 3, v203
	s_nop 1
	s_waitcnt lgkmcnt(6)
	v_mfma_scale_f32_32x32x64_f8f6f4 v[66:81], v[220:227], v[196:203], v[66:81], v174, v174 op_sel_hi:[0,0,0] blgp:1
	ds_read_b128 v[204:207], v179 offset:28672
	ds_read_b128 v[208:211], v179 offset:29696
	ds_read_b128 v[212:215], v179 offset:30720
	ds_read_b128 v[216:219], v179 offset:31744
	s_cbranch_vccz .Ldma_dif0_skip4
	s_and_b64 s[62:63], s[10:11], exec
	s_cselect_b32 s63, s68, s70
	s_cselect_b32 s62, s67, s69
	s_add_i32 m0, s64, 0x6400
	s_add_u32 s65, s65, 0x36534900
	s_addc_u32 s66, s66, 0
	s_add_u32 s67, s73, 0x385ba100
	s_addc_u32 s68, s74, 0
	global_load_lds_dwordx4 v164, s[62:63]
.Ldma_dif0_skip4:
	s_waitcnt lgkmcnt(8)
	v_mfma_scale_f32_32x32x64_f8f6f4 v[34:49], v[228:235], v[196:203], v[34:49], v174, v174 op_sel_hi:[0,0,0] blgp:1
	ds_read_b128 v[220:223], v179 offset:32768
	ds_read_b128 v[224:227], v179 offset:33792
	s_cbranch_vccz .Ldma_dif0_skip5
	s_and_b64 s[62:63], s[26:27], exec
	s_cselect_b32 s63, s66, s68
	s_cselect_b32 s62, s65, s67
	s_add_i32 m0, s64, 0x6800
	s_nop 0
	global_load_lds_dwordx4 v164, s[62:63]
.Ldma_dif0_skip5:
	s_add_u32 s44, s44, 0x4000
	s_addc_u32 s45, s45, 0
	s_add_u32 s46, s46, 0x8000
	s_addc_u32 s47, s47, 0
	s_add_u32 s48, s48, 0x8000
	s_addc_u32 s49, s49, 0
	s_add_u32 s50, s50, 0x8000
	s_addc_u32 s51, s51, 0
	s_waitcnt lgkmcnt(8)
	v_mfma_scale_f32_32x32x64_f8f6f4 v[18:33], v[236:243], v[196:203], v[18:33], v174, v174 op_sel_hi:[0,0,0] blgp:1
	ds_read_b128 v[228:231], v179 offset:34816
	ds_read_b128 v[232:235], v179 offset:35840
	s_waitcnt lgkmcnt(8)
	v_mfma_scale_f32_32x32x64_f8f6f4 v[2:17], v[244:251], v[196:203], v[2:17], v174, v174 op_sel_hi:[0,0,0] blgp:1
	ds_read_b128 v[236:239], v179 offset:36864
	ds_read_b128 v[240:243], v179 offset:37888
	v_mfma_scale_f32_16x16x128_f8f6f4 v[82:85], v[154:161], v[196:203], v[82:85], v174, v174 op_sel_hi:[0,0,0] blgp:1
	ds_read_b128 v[244:247], v179 offset:38912
	ds_read_b128 v[248:251], v179 offset:39936
	v_med3_f32 v86, v86, 0, v178
	v_med3_f32 v90, v90, 0, v178
	v_med3_f32 v94, v94, 0, v178
	v_med3_f32 v98, v98, 0, v178
	v_cvt_pk_u8_f32 v196, v86, 0, 0
	v_cvt_pk_u8_f32 v197, v90, 0, 0
	v_cvt_pk_u8_f32 v198, v94, 0, 0
	v_cvt_pk_u8_f32 v199, v98, 0, 0
	v_med3_f32 v87, v87, 0, v178
	v_med3_f32 v91, v91, 0, v178
	v_med3_f32 v95, v95, 0, v178
	v_med3_f32 v99, v99, 0, v178
	v_cvt_pk_u8_f32 v196, v87, 1, v196
	v_cvt_pk_u8_f32 v197, v91, 1, v197
	v_cvt_pk_u8_f32 v198, v95, 1, v198
	v_cvt_pk_u8_f32 v199, v99, 1, v199
	s_waitcnt lgkmcnt(10)
	v_mfma_scale_f32_32x32x64_f8f6f4 v[118:133], v[204:211], v[146:153], v[50:65], v174, v174 op_sel_hi:[0,0,0]
	v_med3_f32 v88, v88, 0, v178
	v_med3_f32 v92, v92, 0, v178
	v_med3_f32 v96, v96, 0, v178
	v_med3_f32 v100, v100, 0, v178
	v_cvt_pk_u8_f32 v196, v88, 2, v196
	v_cvt_pk_u8_f32 v197, v92, 2, v197
	v_cvt_pk_u8_f32 v198, v96, 2, v198
	v_cvt_pk_u8_f32 v199, v100, 2, v199
	v_med3_f32 v89, v89, 0, v178
	v_med3_f32 v93, v93, 0, v178
	v_med3_f32 v97, v97, 0, v178
	v_med3_f32 v101, v101, 0, v178
	v_cvt_pk_u8_f32 v196, v89, 3, v196
	v_cvt_pk_u8_f32 v197, v93, 3, v197
	v_cvt_pk_u8_f32 v198, v97, 3, v198
	v_cvt_pk_u8_f32 v199, v101, 3, v199
	v_med3_f32 v102, v102, 0, v178
	v_med3_f32 v106, v106, 0, v178
	v_med3_f32 v110, v110, 0, v178
	v_med3_f32 v114, v114, 0, v178
	v_cvt_pk_u8_f32 v200, v102, 0, 0
	v_cvt_pk_u8_f32 v201, v106, 0, 0
	v_cvt_pk_u8_f32 v202, v110, 0, 0
	v_cvt_pk_u8_f32 v203, v114, 0, 0
	s_waitcnt lgkmcnt(8)
	v_mfma_scale_f32_32x32x64_f8f6f4 v[180:195], v[212:219], v[146:153], v[50:65], v174, v174 op_sel_hi:[0,0,0]
	v_med3_f32 v103, v103, 0, v178
	v_med3_f32 v107, v107, 0, v178
	v_med3_f32 v111, v111, 0, v178
	v_med3_f32 v115, v115, 0, v178
	v_cvt_pk_u8_f32 v200, v103, 1, v200
	v_cvt_pk_u8_f32 v201, v107, 1, v201
	v_cvt_pk_u8_f32 v202, v111, 1, v202
	v_cvt_pk_u8_f32 v203, v115, 1, v203
	v_med3_f32 v104, v104, 0, v178
	v_med3_f32 v108, v108, 0, v178
	v_med3_f32 v112, v112, 0, v178
	v_med3_f32 v116, v116, 0, v178
	v_cvt_pk_u8_f32 v200, v104, 2, v200
	v_cvt_pk_u8_f32 v201, v108, 2, v201
	v_cvt_pk_u8_f32 v202, v112, 2, v202
	v_cvt_pk_u8_f32 v203, v116, 2, v203
	v_med3_f32 v105, v105, 0, v178
	v_med3_f32 v109, v109, 0, v178
	v_med3_f32 v113, v113, 0, v178
	v_med3_f32 v117, v117, 0, v178
	v_cvt_pk_u8_f32 v200, v105, 3, v200
	v_cvt_pk_u8_f32 v201, v109, 3, v201
	v_cvt_pk_u8_f32 v202, v113, 3, v202
	v_cvt_pk_u8_f32 v203, v117, 3, v203
	s_nop 1
	s_waitcnt lgkmcnt(6)
	v_mfma_scale_f32_32x32x64_f8f6f4 v[66:81], v[220:227], v[196:203], v[66:81], v174, v174 op_sel_hi:[0,0,0] blgp:1
	s_waitcnt lgkmcnt(4)
	v_mfma_scale_f32_32x32x64_f8f6f4 v[34:49], v[228:235], v[196:203], v[34:49], v174, v174 op_sel_hi:[0,0,0] blgp:1
	ds_read_b128 v[220:223], v179 offset:40960
	ds_read_b128 v[224:227], v179 offset:41984
	s_waitcnt lgkmcnt(4)
	v_mfma_scale_f32_32x32x64_f8f6f4 v[18:33], v[236:243], v[196:203], v[18:33], v174, v174 op_sel_hi:[0,0,0] blgp:1
	ds_read_b128 v[228:231], v179 offset:43008
	ds_read_b128 v[232:235], v179 offset:44032
	s_waitcnt lgkmcnt(4)
	v_mfma_scale_f32_32x32x64_f8f6f4 v[2:17], v[244:251], v[196:203], v[2:17], v174, v174 op_sel_hi:[0,0,0] blgp:1
	ds_read_b128 v[236:239], v179 offset:45056
	ds_read_b128 v[240:243], v179 offset:46080
	v_mfma_scale_f32_16x16x128_f8f6f4 v[82:85], v[154:161], v[196:203], v[82:85], v174, v174 op_sel_hi:[0,0,0] blgp:1
	ds_read_b128 v[244:247], v179 offset:47104
	ds_read_b128 v[248:251], v179 offset:48128
	s_cbranch_vccnz .LBB0_1300
	s_waitcnt lgkmcnt(0)
	v_med3_f32 v118, v118, 0, v178
	v_med3_f32 v122, v122, 0, v178
	v_med3_f32 v126, v126, 0, v178
	v_med3_f32 v130, v130, 0, v178
	v_cvt_pk_u8_f32 v196, v118, 0, 0
	v_cvt_pk_u8_f32 v197, v122, 0, 0
	v_cvt_pk_u8_f32 v198, v126, 0, 0
	v_cvt_pk_u8_f32 v199, v130, 0, 0
	v_med3_f32 v119, v119, 0, v178
	v_med3_f32 v123, v123, 0, v178
	v_med3_f32 v127, v127, 0, v178
	v_med3_f32 v131, v131, 0, v178
	v_cvt_pk_u8_f32 v196, v119, 1, v196
	v_cvt_pk_u8_f32 v197, v123, 1, v197
	v_cvt_pk_u8_f32 v198, v127, 1, v198
	v_cvt_pk_u8_f32 v199, v131, 1, v199
	v_med3_f32 v120, v120, 0, v178
	v_med3_f32 v124, v124, 0, v178
	v_med3_f32 v128, v128, 0, v178
	v_med3_f32 v132, v132, 0, v178
	v_cvt_pk_u8_f32 v196, v120, 2, v196
	v_cvt_pk_u8_f32 v197, v124, 2, v197
	v_cvt_pk_u8_f32 v198, v128, 2, v198
	v_cvt_pk_u8_f32 v199, v132, 2, v199
	v_med3_f32 v121, v121, 0, v178
	v_med3_f32 v125, v125, 0, v178
	v_med3_f32 v129, v129, 0, v178
	v_med3_f32 v133, v133, 0, v178
	v_cvt_pk_u8_f32 v196, v121, 3, v196
	v_cvt_pk_u8_f32 v197, v125, 3, v197
	v_cvt_pk_u8_f32 v198, v129, 3, v198
	v_cvt_pk_u8_f32 v199, v133, 3, v199
	v_med3_f32 v180, v180, 0, v178
	v_med3_f32 v184, v184, 0, v178
	v_med3_f32 v188, v188, 0, v178
	v_med3_f32 v192, v192, 0, v178
	v_cvt_pk_u8_f32 v200, v180, 0, 0
	v_cvt_pk_u8_f32 v201, v184, 0, 0
	v_cvt_pk_u8_f32 v202, v188, 0, 0
	v_cvt_pk_u8_f32 v203, v192, 0, 0
	v_med3_f32 v181, v181, 0, v178
	v_med3_f32 v185, v185, 0, v178
	v_med3_f32 v189, v189, 0, v178
	v_med3_f32 v193, v193, 0, v178
	v_cvt_pk_u8_f32 v200, v181, 1, v200
	v_cvt_pk_u8_f32 v201, v185, 1, v201
	v_cvt_pk_u8_f32 v202, v189, 1, v202
	v_cvt_pk_u8_f32 v203, v193, 1, v203
	v_med3_f32 v182, v182, 0, v178
	v_med3_f32 v186, v186, 0, v178
	v_med3_f32 v190, v190, 0, v178
	v_med3_f32 v194, v194, 0, v178
	v_cvt_pk_u8_f32 v200, v182, 2, v200
	v_cvt_pk_u8_f32 v201, v186, 2, v201
	v_cvt_pk_u8_f32 v202, v190, 2, v202
	v_cvt_pk_u8_f32 v203, v194, 2, v203
	v_med3_f32 v183, v183, 0, v178
	v_med3_f32 v187, v187, 0, v178
	v_med3_f32 v191, v191, 0, v178
	v_med3_f32 v195, v195, 0, v178
	v_cvt_pk_u8_f32 v200, v183, 3, v200
	v_cvt_pk_u8_f32 v201, v187, 3, v201
	v_cvt_pk_u8_f32 v202, v191, 3, v202
	v_cvt_pk_u8_f32 v203, v195, 3, v203
	s_nop 1
	v_mfma_scale_f32_32x32x64_f8f6f4 v[66:81], v[220:227], v[196:203], v[66:81], v174, v174 op_sel_hi:[0,0,0] blgp:1
	v_mfma_scale_f32_32x32x64_f8f6f4 v[34:49], v[228:235], v[196:203], v[34:49], v174, v174 op_sel_hi:[0,0,0] blgp:1
	v_mfma_scale_f32_32x32x64_f8f6f4 v[18:33], v[236:243], v[196:203], v[18:33], v174, v174 op_sel_hi:[0,0,0] blgp:1
	v_mfma_scale_f32_32x32x64_f8f6f4 v[2:17], v[244:251], v[196:203], v[2:17], v174, v174 op_sel_hi:[0,0,0] blgp:1
	v_mfma_scale_f32_16x16x128_f8f6f4 v[82:85], v[154:161], v[196:203], v[82:85], v174, v174 op_sel_hi:[0,0,0] blgp:1
	v_mov_b32_e32 v210, v142
	v_mov_b32_e32 v211, v143
	v_mov_b32_e32 v218, v144
	v_mov_b32_e32 v219, v145
	s_branch .LBB0_1297

.LBB0_4060:
	s_lshl_b32 s4, s44, 5
	s_lshr_b32 s2, s44, 1
	s_and_b32 s4, s4, 32
	s_ashr_i32 s0, s12, 6
	s_and_b32 s1, s12, 63
	s_add_i32 s2, s2, s34
	s_add_i32 s4, s4, s31
	s_and_b64 s[12:13], s[18:19], exec
	s_cselect_b32 s0, s2, s0
	s_cselect_b32 s1, s4, s1
	s_lshr_b32 s2, s0, 3
	s_mulk_i32 s2, 0x4100
	s_lshl_b32 s1, s1, 8
	s_and_b32 s4, s0, 7
	s_add_i32 s2, s2, s1
	v_add_u32_e32 v166, s2, v170
	s_lshl_b32 s24, s4, 7
	s_lshl_b32 s12, s4, 2
	s_mul_i32 s46, s0, 0x208000
	v_ashrrev_i32_e32 v167, 31, v166
	s_mul_hi_i32 s47, s0, 0x208000
	s_add_u32 s1, s35, s46
	v_lshlrev_b64 v[4:5], 5, v[166:167]
	s_addc_u32 s2, s36, s47
	s_mul_i32 s55, s0, 0x104000
	v_lshl_add_u64 v[4:5], s[16:17], 0, v[4:5]
	s_mov_b32 s13, s25
	s_mul_hi_i32 s64, s0, 0x104000
	s_add_u32 s4, s37, s55
	v_lshl_add_u64 v[4:5], v[4:5], 0, s[12:13]
	s_addc_u32 s5, s38, s64
	s_add_i32 s12, s0, 32
	v_lshlrev_b64 v[2:3], 10, v[166:167]
	s_ashr_i32 s13, s12, 31
	v_lshl_add_u64 v[2:3], s[22:23], 0, v[2:3]
	s_lshl_b64 s[12:13], s[12:13], 2
	v_lshl_add_u64 v[2:3], v[2:3], 0, s[24:25]
	s_add_u32 s12, s3, s12
	s_addc_u32 s13, s30, s13
	v_lshl_add_u64 v[2:3], v[2:3], 0, v[178:179]
	global_load_dword v58, v[4:5], off
	global_load_dword v50, v163, s[12:13]
	global_load_dwordx4 v[142:145], v[2:3], off offset:16
	global_load_dwordx4 v[138:141], v[2:3], off
	global_load_dwordx4 v[150:153], v[2:3], off offset:80
	global_load_dwordx4 v[146:149], v[2:3], off offset:64
	v_readfirstlane_b32 s0, v1
	s_ashr_i32 s0, s0, 6
	s_cmp_lt_i32 s0, 6
	s_mul_i32 s48, s0, 0xc00
	s_cselect_b64 s[14:15], -1, 0
	s_add_i32 s65, s48, 0xffffc000
	s_add_u32 s6, s4, s65
	s_addc_u32 s7, s5, 0
	s_ashr_i32 s49, s48, 31
	s_add_u32 s8, s1, s48
	s_addc_u32 s9, s2, s49
	s_and_b64 s[12:13], s[14:15], exec
	s_cselect_b32 s13, s9, s7
	s_cselect_b32 s12, s8, s6
	s_add_i32 s45, s48, 0
	s_cmp_lt_i32 s0, 5
	s_cselect_b64 s[28:29], -1, 0
	s_add_i32 s0, s48, 0x400
	s_ashr_i32 s6, s0, 31
	s_add_u32 s7, s8, 0x400
	s_addc_u32 s10, s9, 0
	s_add_i32 s52, s48, 0xffffc400
	s_add_u32 s11, s4, s52
	s_addc_u32 s33, s5, 0
	v_lshl_add_u64 v[2:3], s[12:13], 0, v[164:165]
	s_and_b64 s[12:13], s[28:29], exec
	s_mov_b32 m0, s45
	s_cselect_b32 s13, s10, s33
	s_cselect_b32 s12, s7, s11
	s_add_i32 s7, s48, 0x800
	v_lshrrev_b32 v154, 2, v0
	v_xor_b32 v154, v154, v0
	v_bfe_u32 v154, v154, 2, 1
	v_add_u32 v154, -1, v154
	v_and_b32 v154, 0x38383838, v154
	v_mov_b32 v155, v154
	v_mov_b32 v156, v154
	v_mov_b32 v157, v154
	v_mov_b32 v158, v154
	v_mov_b32 v159, v154
	v_mov_b32 v160, v154
	v_mov_b32 v161, v154
	global_load_lds_dwordx4 v[2:3], off
	s_add_i32 m0, s45, 0x400
	s_ashr_i32 s10, s7, 31
	s_add_u32 s8, s8, 0x800
	s_addc_u32 s9, s9, 0
	s_add_i32 s53, s48, 0xffffc800
	s_add_u32 s11, s4, s53
	s_addc_u32 s33, s5, 0
	v_lshl_add_u64 v[2:3], s[12:13], 0, v[164:165]
	s_and_b64 s[12:13], s[28:29], exec
	global_load_lds_dwordx4 v[2:3], off
	s_cselect_b32 s13, s9, s33
	s_cselect_b32 s12, s8, s11
	s_add_i32 m0, s45, 0x800
	s_add_u32 s4, s4, 0x2000
	s_addc_u32 s5, s5, 0
	s_add_u32 s1, s1, 0x4000
	s_addc_u32 s2, s2, 0
	s_add_u32 s8, s1, s48
	s_addc_u32 s9, s2, s49
	s_add_u32 s11, s4, s65
	s_addc_u32 s33, s5, 0
	v_lshl_add_u64 v[2:3], s[12:13], 0, v[164:165]
	s_and_b64 s[12:13], s[14:15], exec
	global_load_lds_dwordx4 v[2:3], off
	s_cselect_b32 s13, s9, s33
	s_cselect_b32 s12, s8, s11
	s_add_i32 m0, s45, 0x6000
	s_add_u32 s0, s1, s0
	s_addc_u32 s6, s2, s6
	s_add_u32 s8, s4, s52
	s_addc_u32 s9, s5, 0
	v_lshl_add_u64 v[2:3], s[12:13], 0, v[164:165]
	s_and_b64 s[12:13], s[28:29], exec
	global_load_lds_dwordx4 v[2:3], off
	s_cselect_b32 s13, s6, s9
	s_cselect_b32 s12, s0, s8
	s_add_i32 m0, s45, 0x6400
	s_add_u32 s0, s1, s7
	s_addc_u32 s1, s2, s10
	s_add_u32 s2, s4, s53
	s_addc_u32 s4, s5, 0
	v_lshl_add_u64 v[2:3], s[12:13], 0, v[164:165]
	s_and_b64 s[12:13], s[28:29], exec
	s_cselect_b32 s13, s1, s4
	s_cselect_b32 s12, s0, s2
	global_load_lds_dwordx4 v[2:3], off
	v_lshl_add_u64 v[2:3], s[12:13], 0, v[164:165]
	s_add_i32 m0, s45, 0x6800
	s_waitcnt vmcnt(0)
	v_mul_f32_e32 v51, 0x4f800000, v50
	global_load_lds_dwordx4 v[2:3], off
	s_waitcnt vmcnt(3)
	s_barrier
	ds_read_b128 v[2:5], v171
	ds_read_b128 v[6:9], v171 offset:1024
	s_waitcnt lgkmcnt(0)
	v_mfma_scale_f32_32x32x64_f8f6f4 v[2:17], v[2:9], v[138:145], 0, v174, v174 op_sel_hi:[0,0,0]
	ds_read_b128 v[18:21], v171 offset:2048
	ds_read_b128 v[22:25], v171 offset:3072
	v_cmp_gt_f32_e32 vcc, s39, v50
	s_add_u32 s46, s46, s48
	s_addc_u32 s47, s47, s49
	v_cndmask_b32_e32 v59, v50, v51, vcc
	v_sqrt_f32_e32 v60, v59
	s_add_u32 s48, s55, s53
	s_addc_u32 s49, s64, 0
	s_add_u32 s52, s55, s52
	v_add_u32_e32 v61, -1, v60
	v_fma_f32 v62, -v61, v60, v59
	v_cmp_ge_f32_e64 s[12:13], 0, v62
	v_add_u32_e32 v62, 1, v60
	s_addc_u32 s53, s64, 0
	v_cndmask_b32_e64 v61, v60, v61, s[12:13]
	s_waitcnt lgkmcnt(0)
	v_mfma_scale_f32_32x32x64_f8f6f4 v[2:17], v[18:25], v[146:153], v[2:17], v174, v174 op_sel_hi:[0,0,0]
	ds_read_b128 v[18:21], v171 offset:4096
	ds_read_b128 v[22:25], v171 offset:5120
	ds_read_b128 v[34:37], v171 offset:6144
	ds_read_b128 v[38:41], v171 offset:7168
	v_fma_f32 v60, -v62, v60, v59
	v_cmp_lt_f32_e64 s[12:13], 0, v60
	s_add_u32 s55, s55, s65
	s_addc_u32 s64, s64, 0
	v_cndmask_b32_e64 v60, v61, v62, s[12:13]
	s_mov_b32 s67, 0
	s_mov_b32 s65, 0
	v_mov_b32_e32 v61, v163
	v_mov_b32_e32 v62, v163
	v_mov_b32_e32 v63, v163
	v_mov_b32_e32 v64, v163
	v_mov_b32_e32 v65, v163
	s_nop 3
	v_max3_f32 v2, v2, s41, v3
	s_waitcnt lgkmcnt(0)
	v_mfma_scale_f32_32x32x64_f8f6f4 v[18:33], v[18:25], v[138:145], 0, v174, v174 op_sel_hi:[0,0,0]
	v_max3_f32 v2, v2, v4, v5
	v_max3_f32 v2, v2, v6, v7
	v_max3_f32 v2, v2, v8, v9
	v_max3_f32 v2, v2, v10, v11
	v_max3_f32 v2, v2, v12, v13
	v_max3_f32 v2, v2, v14, v15
	v_max3_f32 v2, v2, v16, v17
	v_mfma_scale_f32_32x32x64_f8f6f4 v[18:33], v[34:41], v[146:153], v[18:33], v174, v174 op_sel_hi:[0,0,0]
	ds_read_b128 v[34:37], v171 offset:8192
	ds_read_b128 v[38:41], v171 offset:9216
	ds_read_b128 v[50:53], v171 offset:10240
	ds_read_b128 v[54:57], v171 offset:11264
	s_waitcnt lgkmcnt(0)
	v_mfma_scale_f32_32x32x64_f8f6f4 v[34:49], v[34:41], v[138:145], 0, v174, v174 op_sel_hi:[0,0,0]
	s_nop 13
	v_max3_f32 v2, v2, v18, v19
	v_max3_f32 v2, v2, v20, v21
	v_max3_f32 v18, v2, v22, v23
	v_max3_f32 v18, v18, v24, v25
	v_max3_f32 v18, v18, v26, v27
	v_max3_f32 v18, v18, v28, v29
	v_max3_f32 v18, v18, v30, v31
	v_max3_f32 v26, v18, v32, v33
	v_mov_b32_e32 v27, v163
	v_mov_b32_e32 v28, v163
	v_mov_b32_e32 v29, v163
	v_mov_b32_e32 v30, v163
	v_mov_b32_e32 v31, v163
	v_mov_b32_e32 v32, v163
	v_mov_b32_e32 v33, v163
	v_mfma_scale_f32_32x32x64_f8f6f4 v[34:49], v[50:57], v[146:153], v[34:49], v174, v174 op_sel_hi:[0,0,0]
	v_mul_f32_e32 v50, 0x37800000, v60
	v_cndmask_b32_e32 v60, v60, v50, vcc
	ds_read_b128 v[50:53], v171 offset:12288
	ds_read_b128 v[54:57], v171 offset:13312
	ds_read_b128 v[18:21], v171 offset:14336
	ds_read_b128 v[22:25], v171 offset:15360
	v_cmp_lt_i32_e32 vcc, v176, v177
	s_nop 12
	v_max3_f32 v26, v26, v34, v35
	s_waitcnt lgkmcnt(0)
	v_mfma_scale_f32_32x32x64_f8f6f4 v[2:17], v[50:57], v[138:145], 0, v174, v174 op_sel_hi:[0,0,0]
	v_max3_f32 v26, v26, v36, v37
	v_max3_f32 v26, v26, v38, v39
	v_max3_f32 v26, v26, v40, v41
	v_max3_f32 v26, v26, v42, v43
	v_max3_f32 v26, v26, v44, v45
	v_max3_f32 v26, v26, v46, v47
	v_max3_f32 v26, v26, v48, v49
	v_mov_b32_e32 v50, 0
	v_mov_b32_e32 v51, v163
	v_mov_b32_e32 v52, v163
	v_mov_b32_e32 v53, v163
	v_mov_b32_e32 v54, v163
	v_mov_b32_e32 v55, v163
	v_mov_b32_e32 v56, v163
	v_mov_b32_e32 v57, v163
	v_mfma_scale_f32_32x32x64_f8f6f4 v[2:17], v[18:25], v[146:153], v[2:17], v174, v174 op_sel_hi:[0,0,0]
	v_mov_b32_e32 v18, 0
	v_mov_b32_e32 v19, v163
	v_mov_b32_e32 v20, v163
	v_mov_b32_e32 v21, v163
	v_mov_b32_e32 v22, v163
	v_mov_b32_e32 v23, v163
	v_mov_b32_e32 v24, v163
	v_mov_b32_e32 v25, v163
	s_nop 11
	v_max3_f32 v2, v26, v2, v3
	v_max3_f32 v2, v2, v4, v5
	v_max3_f32 v2, v2, v6, v7
	v_max3_f32 v2, v2, v8, v9
	v_max3_f32 v2, v2, v10, v11
	v_max3_f32 v2, v2, v12, v13
	v_max3_f32 v2, v2, v14, v15
	v_cndmask_b32_e32 v3, v175, v176, vcc
	v_max3_f32 v2, v2, v16, v17
	v_lshlrev_b32_e32 v3, 2, v3
	ds_bpermute_b32 v3, v3, v2
	v_cmp_class_f32_e32 vcc, v59, v172
	v_mov_b32_e32 v26, v163
	v_mov_b32_e32 v5, v163
	v_cndmask_b32_e32 v4, v60, v59, vcc
	s_waitcnt lgkmcnt(0)
	v_max_f32_e32 v3, v3, v3
	v_mul_f32_e32 v4, v58, v4
	v_max_f32_e32 v2, v2, v3
	v_fmamk_f32 v4, v4, 0x3f90a3d7, v173
	v_add_f32_e32 v2, 0x42800000, v2
	v_min_f32_e32 v2, v4, v2
	v_add_f32_e32 v2, 0xc2ec0000, v2
	v_xor_b32_e32 v34, 0x80000000, v2
	v_mov_b32_e32 v35, v34
	v_mov_b32_e32 v36, v34
	v_mov_b32_e32 v37, v34
	v_mov_b32_e32 v38, v34
	v_mov_b32_e32 v39, v34
	v_mov_b32_e32 v40, v34
	v_mov_b32_e32 v41, v34
	v_mov_b32_e32 v42, v34
	v_mov_b32_e32 v43, v34
	v_mov_b32_e32 v44, v34
	v_mov_b32_e32 v45, v34
	v_mov_b32_e32 v46, v34
	v_mov_b32_e32 v47, v34
	v_mov_b32_e32 v48, v34
	v_mov_b32_e32 v49, v34
	v_mov_b32_e32 v58, v163
	v_mov_b32_e32 v59, v163
	v_mov_b32_e32 v60, v163
	v_mov_b32_e32 v2, 0
	v_mov_b32_e32 v3, v163
	v_mov_b32_e32 v4, v163
	v_mov_b32_e32 v6, v163
	v_mov_b32_e32 v7, v163
	v_mov_b32_e32 v8, v163
	v_mov_b32_e32 v9, v163
	v_mov_b32_e32 v10, v163
	v_mov_b32_e32 v11, v163
	v_mov_b32_e32 v12, v163
	v_mov_b32_e32 v13, v163
	v_mov_b32_e32 v14, v163
	v_mov_b32_e32 v15, v163
	v_mov_b32_e32 v16, v163
	v_mov_b32_e32 v17, v163
	v_mov_b32_e32 v86, v163
	v_mov_b32_e32 v87, v163
	v_mov_b32_e32 v88, v163
	v_mov_b32_e32 v89, v163
	v_mov_b32_e32 v90, v163
	v_mov_b32_e32 v91, v163
	v_mov_b32_e32 v92, v163
	v_mov_b32_e32 v93, v163
	v_mov_b32_e32 v94, v163
	v_mov_b32_e32 v95, v163
	v_mov_b32_e32 v96, v163
	v_mov_b32_e32 v97, v163
	v_mov_b32_e32 v98, v163
	v_mov_b32_e32 v99, v163
	v_mov_b32_e32 v100, v163
	v_mov_b32_e32 v101, v163
	v_mov_b32_e32 v102, v163
	v_mov_b32_e32 v103, v163
	v_mov_b32_e32 v104, v163
	v_mov_b32_e32 v105, v163
	v_mov_b32_e32 v106, v163
	v_mov_b32_e32 v107, v163
	v_mov_b32_e32 v108, v163
	v_mov_b32_e32 v109, v163
	v_mov_b32_e32 v110, v163
	v_mov_b32_e32 v111, v163
	v_mov_b32_e32 v112, v163
	v_mov_b32_e32 v113, v163
	v_mov_b32_e32 v114, v163
	v_mov_b32_e32 v115, v163
	v_mov_b32_e32 v116, v163
	v_mov_b32_e32 v117, v163
	v_mov_b32_e32 v228, v163
	v_mov_b32_e32 v229, v163
	v_mov_b32_e32 v230, v163
	v_mov_b32_e32 v231, v163
	v_mov_b32_e32 v232, v163
	v_mov_b32_e32 v233, v163
	v_mov_b32_e32 v234, v163
	v_mov_b32_e32 v235, v163
	v_mov_b32_e32 v236, v163
	v_mov_b32_e32 v237, v163
	v_mov_b32_e32 v238, v163
	v_mov_b32_e32 v239, v163
	v_mov_b32_e32 v240, v163
	v_mov_b32_e32 v241, v163
	v_mov_b32_e32 v242, v163
	v_mov_b32_e32 v243, v163
	s_branch .LBB0_4062
.LBB0_4062:
	s_waitcnt vmcnt(0) lgkmcnt(0)
	s_barrier
	s_cmpk_gt_u32 s65, 0x7f
	s_cselect_b64 s[12:13], -1, 0
	s_xor_b32 s66, s67, 2
	s_mul_i32 s100, s67, 0x6000
	s_add_i32 s65, s65, 2
	s_andn2_b64 vcc, exec, s[12:13]
	v_add_u32_e32 v167, s100, v171
	s_mov_b32 s67, s66
.LBB0_4061:
	ds_read_b128 v[190:193], v167
	ds_read_b128 v[194:197], v167 offset:1024
	ds_read_b128 v[198:201], v167 offset:2048
	ds_read_b128 v[202:205], v167 offset:3072
	ds_read_b128 v[206:209], v167 offset:4096
	ds_read_b128 v[210:213], v167 offset:5120
	ds_read_b128 v[220:223], v167 offset:6144
	ds_read_b128 v[224:227], v167 offset:7168
	v_med3_f32 v86, v86, 0, v180
	v_med3_f32 v90, v90, 0, v180
	v_med3_f32 v94, v94, 0, v180
	v_med3_f32 v98, v98, 0, v180
	v_cvt_pk_u8_f32 v118, v86, 0, 0
	v_cvt_pk_u8_f32 v119, v90, 0, 0
	v_cvt_pk_u8_f32 v120, v94, 0, 0
	v_cvt_pk_u8_f32 v121, v98, 0, 0
	v_med3_f32 v87, v87, 0, v180
	v_med3_f32 v91, v91, 0, v180
	v_med3_f32 v95, v95, 0, v180
	v_med3_f32 v99, v99, 0, v180
	v_cvt_pk_u8_f32 v118, v87, 1, v118
	v_cvt_pk_u8_f32 v119, v91, 1, v119
	v_cvt_pk_u8_f32 v120, v95, 1, v120
	v_cvt_pk_u8_f32 v121, v99, 1, v121
	s_waitcnt lgkmcnt(6)
	v_mfma_scale_f32_32x32x64_f8f6f4 v[54:69], v[190:197], v[138:145], v[34:49], v174, v174 op_sel_hi:[0,0,0]
	v_med3_f32 v88, v88, 0, v180
	v_med3_f32 v92, v92, 0, v180
	v_med3_f32 v96, v96, 0, v180
	v_med3_f32 v100, v100, 0, v180
	v_cvt_pk_u8_f32 v118, v88, 2, v118
	v_cvt_pk_u8_f32 v119, v92, 2, v119
	v_cvt_pk_u8_f32 v120, v96, 2, v120
	v_cvt_pk_u8_f32 v121, v100, 2, v121
	v_med3_f32 v89, v89, 0, v180
	v_med3_f32 v93, v93, 0, v180
	v_med3_f32 v97, v97, 0, v180
	v_med3_f32 v101, v101, 0, v180
	v_cvt_pk_u8_f32 v118, v89, 3, v118
	v_cvt_pk_u8_f32 v119, v93, 3, v119
	v_cvt_pk_u8_f32 v120, v97, 3, v120
	v_cvt_pk_u8_f32 v121, v101, 3, v121
	s_waitcnt lgkmcnt(4)
	v_mfma_scale_f32_32x32x64_f8f6f4 v[54:69], v[198:205], v[146:153], v[54:69], v174, v174 op_sel_hi:[0,0,0]
	v_med3_f32 v102, v102, 0, v180
	v_med3_f32 v106, v106, 0, v180
	v_med3_f32 v110, v110, 0, v180
	v_med3_f32 v114, v114, 0, v180
	v_cvt_pk_u8_f32 v122, v102, 0, 0
	v_cvt_pk_u8_f32 v123, v106, 0, 0
	v_cvt_pk_u8_f32 v124, v110, 0, 0
	v_cvt_pk_u8_f32 v125, v114, 0, 0
	v_med3_f32 v103, v103, 0, v180
	v_med3_f32 v107, v107, 0, v180
	v_med3_f32 v111, v111, 0, v180
	v_med3_f32 v115, v115, 0, v180
	v_cvt_pk_u8_f32 v122, v103, 1, v122
	v_cvt_pk_u8_f32 v123, v107, 1, v123
	v_cvt_pk_u8_f32 v124, v111, 1, v124
	v_cvt_pk_u8_f32 v125, v115, 1, v125
	s_waitcnt lgkmcnt(2)
	v_mfma_scale_f32_32x32x64_f8f6f4 v[70:85], v[206:213], v[138:145], v[34:49], v174, v174 op_sel_hi:[0,0,0]
	v_med3_f32 v104, v104, 0, v180
	v_med3_f32 v108, v108, 0, v180
	v_med3_f32 v112, v112, 0, v180
	v_med3_f32 v116, v116, 0, v180
	v_cvt_pk_u8_f32 v122, v104, 2, v122
	v_cvt_pk_u8_f32 v123, v108, 2, v123
	v_cvt_pk_u8_f32 v124, v112, 2, v124
	v_cvt_pk_u8_f32 v125, v116, 2, v125
	v_med3_f32 v105, v105, 0, v180
	v_med3_f32 v109, v109, 0, v180
	v_med3_f32 v113, v113, 0, v180
	v_med3_f32 v117, v117, 0, v180
	v_cvt_pk_u8_f32 v122, v105, 3, v122
	v_cvt_pk_u8_f32 v123, v109, 3, v123
	v_cvt_pk_u8_f32 v124, v113, 3, v124
	v_cvt_pk_u8_f32 v125, v117, 3, v125
	s_waitcnt lgkmcnt(0)
	v_mfma_scale_f32_32x32x64_f8f6f4 v[70:85], v[220:227], v[146:153], v[70:85], v174, v174 op_sel_hi:[0,0,0]
	s_nop 1
	v_mfma_scale_f32_32x32x64_f8f6f4 v[18:33], v[228:235], v[118:125], v[18:33], v174, v174 op_sel_hi:[0,0,0] blgp:1
	ds_read_b128 v[190:193], v167 offset:8192
	ds_read_b128 v[194:197], v167 offset:9216
	ds_read_b128 v[198:201], v167 offset:10240
	ds_read_b128 v[202:205], v167 offset:11264
	s_cbranch_vccz .Ldma_mla1_skip0
	s_add_u32 s1, s20, s46
	s_addc_u32 s2, s21, s47
	s_add_u32 s4, s1, 0x23076100
	s_addc_u32 s5, s2, 0
	s_add_u32 s6, s20, s55
	s_addc_u32 s7, s21, s64
	s_add_u32 s8, s6, 0x26132100
	s_addc_u32 s9, s7, 0
	s_mul_i32 s0, s66, 0x6000
	s_and_b64 s[68:69], s[14:15], exec
	s_cselect_b32 s69, s5, s9
	s_cselect_b32 s68, s4, s8
	s_add_i32 s0, s45, s0
	s_add_u32 s4, s1, 0x23076500
	s_addc_u32 s5, s2, 0
	s_add_u32 s8, s20, s52
	s_addc_u32 s9, s21, s53
	s_add_u32 s10, s8, 0x26132100
	s_addc_u32 s11, s9, 0
	s_mov_b32 m0, s0
	s_nop 0
	global_load_lds_dwordx4 v164, s[68:69]
.Ldma_mla1_skip0:
	v_mfma_scale_f32_32x32x64_f8f6f4 v[2:17], v[236:243], v[118:125], v[2:17], v174, v174 op_sel_hi:[0,0,0] blgp:1
	ds_read_b128 v[206:209], v167 offset:12288
	ds_read_b128 v[210:213], v167 offset:13312
	ds_read_b128 v[220:223], v167 offset:14336
	ds_read_b128 v[224:227], v167 offset:15360
	s_cbranch_vccz .Ldma_mla1_skip1
	s_and_b64 s[68:69], s[28:29], exec
	s_cselect_b32 s69, s5, s11
	s_cselect_b32 s68, s4, s10
	s_add_i32 m0, s0, 0x400
	s_add_u32 s4, s1, 0x23076900
	s_addc_u32 s5, s2, 0
	s_add_u32 s10, s20, s48
	s_addc_u32 s11, s21, s49
	s_add_u32 s33, s10, 0x26132100
	s_addc_u32 s50, s11, 0
	global_load_lds_dwordx4 v164, s[68:69]
.Ldma_mla1_skip1:
	v_mfma_scale_f32_16x16x128_f8f6f4 v[50:53], v[154:161], v[118:125], v[50:53], v174, v174 op_sel_hi:[0,0,0] blgp:1
	ds_read_b128 v[228:231], v167 offset:16384
	ds_read_b128 v[232:235], v167 offset:17408
	ds_read_b128 v[236:239], v167 offset:18432
	ds_read_b128 v[240:243], v167 offset:19456
	v_med3_f32 v54, v54, 0, v180
	v_med3_f32 v58, v58, 0, v180
	v_med3_f32 v62, v62, 0, v180
	v_med3_f32 v66, v66, 0, v180
	v_cvt_pk_u8_f32 v118, v54, 0, 0
	v_cvt_pk_u8_f32 v119, v58, 0, 0
	v_cvt_pk_u8_f32 v120, v62, 0, 0
	v_cvt_pk_u8_f32 v121, v66, 0, 0
	v_med3_f32 v55, v55, 0, v180
	v_med3_f32 v59, v59, 0, v180
	v_med3_f32 v63, v63, 0, v180
	v_med3_f32 v67, v67, 0, v180
	v_cvt_pk_u8_f32 v118, v55, 1, v118
	v_cvt_pk_u8_f32 v119, v59, 1, v119
	v_cvt_pk_u8_f32 v120, v63, 1, v120
	v_cvt_pk_u8_f32 v121, v67, 1, v121
	s_waitcnt lgkmcnt(10)
	v_mfma_scale_f32_32x32x64_f8f6f4 v[86:101], v[190:197], v[138:145], v[34:49], v174, v174 op_sel_hi:[0,0,0]
	v_med3_f32 v56, v56, 0, v180
	v_med3_f32 v60, v60, 0, v180
	v_med3_f32 v64, v64, 0, v180
	v_med3_f32 v68, v68, 0, v180
	v_cvt_pk_u8_f32 v118, v56, 2, v118
	v_cvt_pk_u8_f32 v119, v60, 2, v119
	v_cvt_pk_u8_f32 v120, v64, 2, v120
	v_cvt_pk_u8_f32 v121, v68, 2, v121
	v_med3_f32 v57, v57, 0, v180
	v_med3_f32 v61, v61, 0, v180
	v_med3_f32 v65, v65, 0, v180
	v_med3_f32 v69, v69, 0, v180
	v_cvt_pk_u8_f32 v118, v57, 3, v118
	v_cvt_pk_u8_f32 v119, v61, 3, v119
	v_cvt_pk_u8_f32 v120, v65, 3, v120
	v_cvt_pk_u8_f32 v121, v69, 3, v121
	s_waitcnt lgkmcnt(8)
	v_mfma_scale_f32_32x32x64_f8f6f4 v[86:101], v[198:205], v[146:153], v[86:101], v174, v174 op_sel_hi:[0,0,0]
	v_med3_f32 v70, v70, 0, v180
	v_med3_f32 v74, v74, 0, v180
	v_med3_f32 v78, v78, 0, v180
	v_med3_f32 v82, v82, 0, v180
	v_cvt_pk_u8_f32 v122, v70, 0, 0
	v_cvt_pk_u8_f32 v123, v74, 0, 0
	v_cvt_pk_u8_f32 v124, v78, 0, 0
	v_cvt_pk_u8_f32 v125, v82, 0, 0
	v_med3_f32 v71, v71, 0, v180
	v_med3_f32 v75, v75, 0, v180
	v_med3_f32 v79, v79, 0, v180
	v_med3_f32 v83, v83, 0, v180
	v_cvt_pk_u8_f32 v122, v71, 1, v122
	v_cvt_pk_u8_f32 v123, v75, 1, v123
	v_cvt_pk_u8_f32 v124, v79, 1, v124
	v_cvt_pk_u8_f32 v125, v83, 1, v125
	s_waitcnt lgkmcnt(6)
	v_mfma_scale_f32_32x32x64_f8f6f4 v[102:117], v[206:213], v[138:145], v[34:49], v174, v174 op_sel_hi:[0,0,0]
	v_med3_f32 v72, v72, 0, v180
	v_med3_f32 v76, v76, 0, v180
	v_med3_f32 v80, v80, 0, v180
	v_med3_f32 v84, v84, 0, v180
	v_cvt_pk_u8_f32 v122, v72, 2, v122
	v_cvt_pk_u8_f32 v123, v76, 2, v123
	v_cvt_pk_u8_f32 v124, v80, 2, v124
	v_cvt_pk_u8_f32 v125, v84, 2, v125
	v_med3_f32 v73, v73, 0, v180
	v_med3_f32 v77, v77, 0, v180
	v_med3_f32 v81, v81, 0, v180
	v_med3_f32 v85, v85, 0, v180
	v_cvt_pk_u8_f32 v122, v73, 3, v122
	v_cvt_pk_u8_f32 v123, v77, 3, v123
	v_cvt_pk_u8_f32 v124, v81, 3, v124
	v_cvt_pk_u8_f32 v125, v85, 3, v125
	s_waitcnt lgkmcnt(4)
	v_mfma_scale_f32_32x32x64_f8f6f4 v[102:117], v[220:227], v[146:153], v[102:117], v174, v174 op_sel_hi:[0,0,0]
	s_nop 1
	s_waitcnt lgkmcnt(2)
	v_mfma_scale_f32_32x32x64_f8f6f4 v[18:33], v[228:235], v[118:125], v[18:33], v174, v174 op_sel_hi:[0,0,0] blgp:1
	ds_read_b128 v[190:193], v167 offset:24576
	ds_read_b128 v[194:197], v167 offset:25600
	ds_read_b128 v[198:201], v167 offset:26624
	ds_read_b128 v[202:205], v167 offset:27648
	s_cbranch_vccz .Ldma_mla1_skip2
	s_and_b64 s[68:69], s[28:29], exec
	s_cselect_b32 s69, s5, s50
	s_cselect_b32 s68, s4, s33
	s_add_i32 m0, s0, 0x800
	s_add_u32 s4, s1, 0x2307a100
	s_addc_u32 s5, s2, 0
	s_add_u32 s6, s6, 0x26134100
	s_addc_u32 s7, s7, 0
	global_load_lds_dwordx4 v164, s[68:69]
.Ldma_mla1_skip2:
	s_waitcnt lgkmcnt(4)
	v_mfma_scale_f32_32x32x64_f8f6f4 v[2:17], v[236:243], v[118:125], v[2:17], v174, v174 op_sel_hi:[0,0,0] blgp:1
	ds_read_b128 v[206:209], v167 offset:28672
	ds_read_b128 v[210:213], v167 offset:29696
	ds_read_b128 v[220:223], v167 offset:30720
	ds_read_b128 v[224:227], v167 offset:31744
	s_cbranch_vccz .Ldma_mla1_skip3
	s_and_b64 s[68:69], s[14:15], exec
	s_cselect_b32 s69, s5, s7
	s_cselect_b32 s68, s4, s6
	s_add_i32 m0, s0, 0x6000
	s_add_u32 s4, s1, 0x2307a500
	s_addc_u32 s5, s2, 0
	s_add_u32 s6, s8, 0x26134100
	s_addc_u32 s7, s9, 0
	global_load_lds_dwordx4 v164, s[68:69]
.Ldma_mla1_skip3:
	v_mfma_scale_f32_16x16x128_f8f6f4 v[50:53], v[154:161], v[118:125], v[50:53], v174, v174 op_sel_hi:[0,0,0] blgp:1
	ds_read_b128 v[228:231], v167 offset:20480
	ds_read_b128 v[232:235], v167 offset:21504
	ds_read_b128 v[236:239], v167 offset:22528
	ds_read_b128 v[240:243], v167 offset:23552
	v_med3_f32 v86, v86, 0, v180
	v_med3_f32 v90, v90, 0, v180
	v_med3_f32 v94, v94, 0, v180
	v_med3_f32 v98, v98, 0, v180
	v_cvt_pk_u8_f32 v118, v86, 0, 0
	v_cvt_pk_u8_f32 v119, v90, 0, 0
	v_cvt_pk_u8_f32 v120, v94, 0, 0
	v_cvt_pk_u8_f32 v121, v98, 0, 0
	v_med3_f32 v87, v87, 0, v180
	v_med3_f32 v91, v91, 0, v180
	v_med3_f32 v95, v95, 0, v180
	v_med3_f32 v99, v99, 0, v180
	v_cvt_pk_u8_f32 v118, v87, 1, v118
	v_cvt_pk_u8_f32 v119, v91, 1, v119
	v_cvt_pk_u8_f32 v120, v95, 1, v120
	v_cvt_pk_u8_f32 v121, v99, 1, v121
	s_waitcnt lgkmcnt(10)
	v_mfma_scale_f32_32x32x64_f8f6f4 v[54:69], v[190:197], v[138:145], v[34:49], v174, v174 op_sel_hi:[0,0,0]
	v_med3_f32 v88, v88, 0, v180
	v_med3_f32 v92, v92, 0, v180
	v_med3_f32 v96, v96, 0, v180
	v_med3_f32 v100, v100, 0, v180
	v_cvt_pk_u8_f32 v118, v88, 2, v118
	v_cvt_pk_u8_f32 v119, v92, 2, v119
	v_cvt_pk_u8_f32 v120, v96, 2, v120
	v_cvt_pk_u8_f32 v121, v100, 2, v121
	v_med3_f32 v89, v89, 0, v180
	v_med3_f32 v93, v93, 0, v180
	v_med3_f32 v97, v97, 0, v180
	v_med3_f32 v101, v101, 0, v180
	v_cvt_pk_u8_f32 v118, v89, 3, v118
	v_cvt_pk_u8_f32 v119, v93, 3, v119
	v_cvt_pk_u8_f32 v120, v97, 3, v120
	v_cvt_pk_u8_f32 v121, v101, 3, v121
	s_waitcnt lgkmcnt(8)
	v_mfma_scale_f32_32x32x64_f8f6f4 v[54:69], v[198:205], v[146:153], v[54:69], v174, v174 op_sel_hi:[0,0,0]
	v_med3_f32 v102, v102, 0, v180
	v_med3_f32 v106, v106, 0, v180
	v_med3_f32 v110, v110, 0, v180
	v_med3_f32 v114, v114, 0, v180
	v_cvt_pk_u8_f32 v122, v102, 0, 0
	v_cvt_pk_u8_f32 v123, v106, 0, 0
	v_cvt_pk_u8_f32 v124, v110, 0, 0
	v_cvt_pk_u8_f32 v125, v114, 0, 0
	v_med3_f32 v103, v103, 0, v180
	v_med3_f32 v107, v107, 0, v180
	v_med3_f32 v111, v111, 0, v180
	v_med3_f32 v115, v115, 0, v180
	v_cvt_pk_u8_f32 v122, v103, 1, v122
	v_cvt_pk_u8_f32 v123, v107, 1, v123
	v_cvt_pk_u8_f32 v124, v111, 1, v124
	v_cvt_pk_u8_f32 v125, v115, 1, v125
	s_waitcnt lgkmcnt(6)
	v_mfma_scale_f32_32x32x64_f8f6f4 v[70:85], v[206:213], v[138:145], v[34:49], v174, v174 op_sel_hi:[0,0,0]
	v_med3_f32 v104, v104, 0, v180
	v_med3_f32 v108, v108, 0, v180
	v_med3_f32 v112, v112, 0, v180
	v_med3_f32 v116, v116, 0, v180
	v_cvt_pk_u8_f32 v122, v104, 2, v122
	v_cvt_pk_u8_f32 v123, v108, 2, v123
	v_cvt_pk_u8_f32 v124, v112, 2, v124
	v_cvt_pk_u8_f32 v125, v116, 2, v125
	v_med3_f32 v105, v105, 0, v180
	v_med3_f32 v109, v109, 0, v180
	v_med3_f32 v113, v113, 0, v180
	v_med3_f32 v117, v117, 0, v180
	v_cvt_pk_u8_f32 v122, v105, 3, v122
	v_cvt_pk_u8_f32 v123, v109, 3, v123
	v_cvt_pk_u8_f32 v124, v113, 3, v124
	v_cvt_pk_u8_f32 v125, v117, 3, v125
	s_waitcnt lgkmcnt(4)
	v_mfma_scale_f32_32x32x64_f8f6f4 v[70:85], v[220:227], v[146:153], v[70:85], v174, v174 op_sel_hi:[0,0,0]
	s_nop 1
	s_waitcnt lgkmcnt(2)
	v_mfma_scale_f32_32x32x64_f8f6f4 v[18:33], v[228:235], v[118:125], v[18:33], v174, v174 op_sel_hi:[0,0,0] blgp:1
	ds_read_b128 v[190:193], v167 offset:32768
	ds_read_b128 v[194:197], v167 offset:33792
	ds_read_b128 v[198:201], v167 offset:34816
	ds_read_b128 v[202:205], v167 offset:35840
	s_cbranch_vccz .Ldma_mla1_skip4
	s_and_b64 s[68:69], s[28:29], exec
	s_cselect_b32 s69, s5, s7
	s_cselect_b32 s68, s4, s6
	s_add_i32 m0, s0, 0x6400
	s_add_u32 s1, s1, 0x2307a900
	s_addc_u32 s2, s2, 0
	s_add_u32 s4, s10, 0x26134100
	s_addc_u32 s5, s11, 0
	global_load_lds_dwordx4 v164, s[68:69]
.Ldma_mla1_skip4:
	s_waitcnt lgkmcnt(4)
	v_mfma_scale_f32_32x32x64_f8f6f4 v[2:17], v[236:243], v[118:125], v[2:17], v174, v174 op_sel_hi:[0,0,0] blgp:1
	ds_read_b128 v[206:209], v167 offset:36864
	ds_read_b128 v[210:213], v167 offset:37888
	ds_read_b128 v[220:223], v167 offset:38912
	ds_read_b128 v[224:227], v167 offset:39936
	s_cbranch_vccz .Ldma_mla1_skip5
	s_and_b64 s[68:69], s[28:29], exec
	s_cselect_b32 s69, s2, s5
	s_cselect_b32 s68, s1, s4
	s_add_i32 m0, s0, 0x6800
	s_nop 0
	global_load_lds_dwordx4 v164, s[68:69]
.Ldma_mla1_skip5:
	s_add_u32 s46, s46, 0x8000
	s_addc_u32 s47, s47, 0
	s_add_u32 s48, s48, 0x4000
	s_addc_u32 s49, s49, 0
	s_add_u32 s52, s52, 0x4000
	s_addc_u32 s53, s53, 0
	s_add_u32 s55, s55, 0x4000
	s_addc_u32 s64, s64, 0
	v_mfma_scale_f32_16x16x128_f8f6f4 v[50:53], v[154:161], v[118:125], v[50:53], v174, v174 op_sel_hi:[0,0,0] blgp:1
	ds_read_b128 v[228:231], v167 offset:40960
	ds_read_b128 v[232:235], v167 offset:41984
	ds_read_b128 v[236:239], v167 offset:43008
	ds_read_b128 v[240:243], v167 offset:44032
	v_med3_f32 v54, v54, 0, v180
	v_med3_f32 v58, v58, 0, v180
	v_med3_f32 v62, v62, 0, v180
	v_med3_f32 v66, v66, 0, v180
	v_cvt_pk_u8_f32 v118, v54, 0, 0
	v_cvt_pk_u8_f32 v119, v58, 0, 0
	v_cvt_pk_u8_f32 v120, v62, 0, 0
	v_cvt_pk_u8_f32 v121, v66, 0, 0
	v_med3_f32 v55, v55, 0, v180
	v_med3_f32 v59, v59, 0, v180
	v_med3_f32 v63, v63, 0, v180
	v_med3_f32 v67, v67, 0, v180
	v_cvt_pk_u8_f32 v118, v55, 1, v118
	v_cvt_pk_u8_f32 v119, v59, 1, v119
	v_cvt_pk_u8_f32 v120, v63, 1, v120
	v_cvt_pk_u8_f32 v121, v67, 1, v121
	s_waitcnt lgkmcnt(10)
	v_mfma_scale_f32_32x32x64_f8f6f4 v[86:101], v[190:197], v[138:145], v[34:49], v174, v174 op_sel_hi:[0,0,0]
	v_med3_f32 v56, v56, 0, v180
	v_med3_f32 v60, v60, 0, v180
	v_med3_f32 v64, v64, 0, v180
	v_med3_f32 v68, v68, 0, v180
	v_cvt_pk_u8_f32 v118, v56, 2, v118
	v_cvt_pk_u8_f32 v119, v60, 2, v119
	v_cvt_pk_u8_f32 v120, v64, 2, v120
	v_cvt_pk_u8_f32 v121, v68, 2, v121
	v_med3_f32 v57, v57, 0, v180
	v_med3_f32 v61, v61, 0, v180
	v_med3_f32 v65, v65, 0, v180
	v_med3_f32 v69, v69, 0, v180
	v_cvt_pk_u8_f32 v118, v57, 3, v118
	v_cvt_pk_u8_f32 v119, v61, 3, v119
	v_cvt_pk_u8_f32 v120, v65, 3, v120
	v_cvt_pk_u8_f32 v121, v69, 3, v121
	s_waitcnt lgkmcnt(8)
	v_mfma_scale_f32_32x32x64_f8f6f4 v[86:101], v[198:205], v[146:153], v[86:101], v174, v174 op_sel_hi:[0,0,0]
	v_med3_f32 v70, v70, 0, v180
	v_med3_f32 v74, v74, 0, v180
	v_med3_f32 v78, v78, 0, v180
	v_med3_f32 v82, v82, 0, v180
	v_cvt_pk_u8_f32 v122, v70, 0, 0
	v_cvt_pk_u8_f32 v123, v74, 0, 0
	v_cvt_pk_u8_f32 v124, v78, 0, 0
	v_cvt_pk_u8_f32 v125, v82, 0, 0
	v_med3_f32 v71, v71, 0, v180
	v_med3_f32 v75, v75, 0, v180
	v_med3_f32 v79, v79, 0, v180
	v_med3_f32 v83, v83, 0, v180
	v_cvt_pk_u8_f32 v122, v71, 1, v122
	v_cvt_pk_u8_f32 v123, v75, 1, v123
	v_cvt_pk_u8_f32 v124, v79, 1, v124
	v_cvt_pk_u8_f32 v125, v83, 1, v125
	s_waitcnt lgkmcnt(6)
	v_mfma_scale_f32_32x32x64_f8f6f4 v[102:117], v[206:213], v[138:145], v[34:49], v174, v174 op_sel_hi:[0,0,0]
	v_med3_f32 v72, v72, 0, v180
	v_med3_f32 v76, v76, 0, v180
	v_med3_f32 v80, v80, 0, v180
	v_med3_f32 v84, v84, 0, v180
	v_cvt_pk_u8_f32 v122, v72, 2, v122
	v_cvt_pk_u8_f32 v123, v76, 2, v123
	v_cvt_pk_u8_f32 v124, v80, 2, v124
	v_cvt_pk_u8_f32 v125, v84, 2, v125
	v_med3_f32 v73, v73, 0, v180
	v_med3_f32 v77, v77, 0, v180
	v_med3_f32 v81, v81, 0, v180
	v_med3_f32 v85, v85, 0, v180
	v_cvt_pk_u8_f32 v122, v73, 3, v122
	v_cvt_pk_u8_f32 v123, v77, 3, v123
	v_cvt_pk_u8_f32 v124, v81, 3, v124
	v_cvt_pk_u8_f32 v125, v85, 3, v125
	s_waitcnt lgkmcnt(4)
	v_mfma_scale_f32_32x32x64_f8f6f4 v[102:117], v[220:227], v[146:153], v[102:117], v174, v174 op_sel_hi:[0,0,0]
	s_nop 1
	s_waitcnt lgkmcnt(2)
	v_mfma_scale_f32_32x32x64_f8f6f4 v[18:33], v[228:235], v[118:125], v[18:33], v174, v174 op_sel_hi:[0,0,0] blgp:1
	s_waitcnt lgkmcnt(0)
	v_mfma_scale_f32_32x32x64_f8f6f4 v[2:17], v[236:243], v[118:125], v[2:17], v174, v174 op_sel_hi:[0,0,0] blgp:1
	v_mfma_scale_f32_16x16x128_f8f6f4 v[50:53], v[154:161], v[118:125], v[50:53], v174, v174 op_sel_hi:[0,0,0] blgp:1
	ds_read_b128 v[228:231], v167 offset:45056
	ds_read_b128 v[232:235], v167 offset:46080
	ds_read_b128 v[236:239], v167 offset:47104
	ds_read_b128 v[240:243], v167 offset:48128
	s_cbranch_vccnz .LBB0_4062
	s_waitcnt lgkmcnt(0)
	v_med3_f32 v86, v86, 0, v180
	v_med3_f32 v90, v90, 0, v180
	v_med3_f32 v94, v94, 0, v180
	v_med3_f32 v98, v98, 0, v180
	v_cvt_pk_u8_f32 v118, v86, 0, 0
	v_cvt_pk_u8_f32 v119, v90, 0, 0
	v_cvt_pk_u8_f32 v120, v94, 0, 0
	v_cvt_pk_u8_f32 v121, v98, 0, 0
	v_med3_f32 v87, v87, 0, v180
	v_med3_f32 v91, v91, 0, v180
	v_med3_f32 v95, v95, 0, v180
	v_med3_f32 v99, v99, 0, v180
	v_cvt_pk_u8_f32 v118, v87, 1, v118
	v_cvt_pk_u8_f32 v119, v91, 1, v119
	v_cvt_pk_u8_f32 v120, v95, 1, v120
	v_cvt_pk_u8_f32 v121, v99, 1, v121
	v_med3_f32 v88, v88, 0, v180
	v_med3_f32 v92, v92, 0, v180
	v_med3_f32 v96, v96, 0, v180
	v_med3_f32 v100, v100, 0, v180
	v_cvt_pk_u8_f32 v118, v88, 2, v118
	v_cvt_pk_u8_f32 v119, v92, 2, v119
	v_cvt_pk_u8_f32 v120, v96, 2, v120
	v_cvt_pk_u8_f32 v121, v100, 2, v121
	v_med3_f32 v89, v89, 0, v180
	v_med3_f32 v93, v93, 0, v180
	v_med3_f32 v97, v97, 0, v180
	v_med3_f32 v101, v101, 0, v180
	v_cvt_pk_u8_f32 v118, v89, 3, v118
	v_cvt_pk_u8_f32 v119, v93, 3, v119
	v_cvt_pk_u8_f32 v120, v97, 3, v120
	v_cvt_pk_u8_f32 v121, v101, 3, v121
	v_med3_f32 v102, v102, 0, v180
	v_med3_f32 v106, v106, 0, v180
	v_med3_f32 v110, v110, 0, v180
	v_med3_f32 v114, v114, 0, v180
	v_cvt_pk_u8_f32 v122, v102, 0, 0
	v_cvt_pk_u8_f32 v123, v106, 0, 0
	v_cvt_pk_u8_f32 v124, v110, 0, 0
	v_cvt_pk_u8_f32 v125, v114, 0, 0
	v_med3_f32 v103, v103, 0, v180
	v_med3_f32 v107, v107, 0, v180
	v_med3_f32 v111, v111, 0, v180
	v_med3_f32 v115, v115, 0, v180
	v_cvt_pk_u8_f32 v122, v103, 1, v122
	v_cvt_pk_u8_f32 v123, v107, 1, v123
	v_cvt_pk_u8_f32 v124, v111, 1, v124
	v_cvt_pk_u8_f32 v125, v115, 1, v125
	v_med3_f32 v104, v104, 0, v180
	v_med3_f32 v108, v108, 0, v180
	v_med3_f32 v112, v112, 0, v180
	v_med3_f32 v116, v116, 0, v180
	v_cvt_pk_u8_f32 v122, v104, 2, v122
	v_cvt_pk_u8_f32 v123, v108, 2, v123
	v_cvt_pk_u8_f32 v124, v112, 2, v124
	v_cvt_pk_u8_f32 v125, v116, 2, v125
	v_med3_f32 v105, v105, 0, v180
	v_med3_f32 v109, v109, 0, v180
	v_med3_f32 v113, v113, 0, v180
	v_med3_f32 v117, v117, 0, v180
	v_cvt_pk_u8_f32 v122, v105, 3, v122
	v_cvt_pk_u8_f32 v123, v109, 3, v123
	v_cvt_pk_u8_f32 v124, v113, 3, v124
	v_cvt_pk_u8_f32 v125, v117, 3, v125
	s_nop 1
	v_mfma_scale_f32_32x32x64_f8f6f4 v[18:33], v[228:235], v[118:125], v[18:33], v174, v174 op_sel_hi:[0,0,0] blgp:1
	v_mfma_scale_f32_32x32x64_f8f6f4 v[2:17], v[236:243], v[118:125], v[2:17], v174, v174 op_sel_hi:[0,0,0] blgp:1
	v_mfma_scale_f32_16x16x128_f8f6f4 v[50:53], v[154:161], v[118:125], v[50:53], v174, v174 op_sel_hi:[0,0,0] blgp:1
	s_branch .LBB0_4059

.LBB0_4070:
	s_lshl_b32 s4, s42, 5
	s_lshr_b32 s2, s42, 1
	s_and_b32 s4, s4, 32
	s_ashr_i32 s0, s12, 6
	s_and_b32 s1, s12, 63
	s_add_i32 s2, s2, s34
	s_add_i32 s4, s4, s31
	s_and_b64 s[12:13], s[18:19], exec
	s_cselect_b32 s0, s2, s0
	s_cselect_b32 s1, s4, s1
	s_ashr_i32 s2, s0, 3
	s_mul_i32 s4, s2, 0x4100
	s_lshl_b32 s1, s1, 8
	s_add_i32 s4, s4, s1
	v_add_u32_e32 v166, s4, v170
	v_ashrrev_i32_e32 v167, 31, v166
	s_and_b32 s43, s0, 7
	v_lshlrev_b64 v[2:3], 9, v[166:167]
	v_lshl_add_u64 v[2:3], s[20:21], 0, v[2:3]
	s_lshl_b32 s24, s43, 6
	v_lshl_add_u64 v[2:3], v[2:3], 0, s[24:25]
	s_lshl_b32 s24, s43, 2
	s_mul_i32 s44, s0, 0x104000
	s_mul_hi_i32 s45, s0, 0x104000
	s_add_u32 s1, s35, s44
	s_addc_u32 s4, s36, s45
	s_lshl_b32 s2, s2, 2
	s_bfe_u32 s5, s0, 0x20001
	s_or_b32 s52, s2, s5
	s_mul_hi_i32 s53, s52, 0x208000
	s_mul_i32 s52, s52, 0x208000
	s_add_u32 s2, s37, s52
	s_addc_u32 s5, s38, s53
	s_add_i32 s12, s0, 16
	s_ashr_i32 s13, s12, 31
	v_lshlrev_b64 v[4:5], 5, v[166:167]
	s_lshl_b64 s[12:13], s[12:13], 2
	v_lshl_add_u64 v[4:5], s[16:17], 0, v[4:5]
	s_add_u32 s12, s3, s12
	v_lshl_add_u64 v[4:5], v[4:5], 0, s[24:25]
	s_addc_u32 s13, s28, s13
	global_load_dword v42, v[4:5], off
	global_load_dword v18, v163, s[12:13]
	v_lshl_add_u64 v[2:3], v[2:3], 0, v[210:211]
	global_load_dwordx4 v[150:153], v[2:3], off offset:16
	global_load_dwordx4 v[146:149], v[2:3], off
	v_readfirstlane_b32 s0, v1
	s_ashr_i32 s0, s0, 6
	s_cmp_lt_i32 s0, 3
	s_mul_i32 s46, s0, 0xc00
	s_cselect_b64 s[14:15], -1, 0
	s_add_i32 s55, s46, 0xffffe000
	s_add_u32 s6, s2, s55
	s_addc_u32 s7, s5, 0
	s_ashr_i32 s47, s46, 31
	s_add_u32 s8, s1, s46
	s_addc_u32 s9, s4, s47
	s_and_b64 s[12:13], s[14:15], exec
	s_cselect_b32 s13, s9, s7
	s_cselect_b32 s12, s8, s6
	s_add_i32 s6, s46, 0x400
	s_add_i32 s24, s46, 0
	s_ashr_i32 s7, s6, 31
	s_add_u32 s10, s8, 0x400
	s_addc_u32 s11, s9, 0
	s_add_i32 s48, s46, 0xffffe400
	s_add_u32 s26, s2, s48
	s_addc_u32 s27, s5, 0
	v_lshl_add_u64 v[2:3], s[12:13], 0, v[164:165]
	s_mov_b32 m0, s24
	s_and_b64 s[12:13], s[14:15], exec
	v_lshrrev_b32 v154, 2, v0
	v_xor_b32 v154, v154, v0
	v_bfe_u32 v154, v154, 2, 1
	v_add_u32 v154, -1, v154
	v_and_b32 v154, 0x38383838, v154
	v_mov_b32 v155, v154
	v_mov_b32 v156, v154
	v_mov_b32 v157, v154
	v_mov_b32 v158, v154
	v_mov_b32 v159, v154
	v_mov_b32 v160, v154
	v_mov_b32 v161, v154
	global_load_lds_dwordx4 v[2:3], off
	s_cselect_b32 s13, s11, s27
	s_cselect_b32 s12, s10, s26
	s_add_i32 m0, s24, 0x400
	s_cmp_lt_i32 s0, 2
	s_cselect_b64 s[26:27], -1, 0
	s_add_i32 s0, s46, 0x800
	s_ashr_i32 s10, s0, 31
	s_add_u32 s8, s8, 0x800
	s_addc_u32 s9, s9, 0
	s_add_i32 s49, s46, 0xffffe800
	s_add_u32 s11, s2, s49
	s_addc_u32 s33, s5, 0
	v_lshl_add_u64 v[2:3], s[12:13], 0, v[164:165]
	s_and_b64 s[12:13], s[26:27], exec
	global_load_lds_dwordx4 v[2:3], off
	s_cselect_b32 s13, s9, s33
	s_cselect_b32 s12, s8, s11
	s_add_i32 m0, s24, 0x800
	s_add_u32 s2, s2, 0x4000
	s_addc_u32 s5, s5, 0
	s_add_u32 s1, s1, 0x2000
	s_addc_u32 s4, s4, 0
	s_add_u32 s8, s1, s46
	s_addc_u32 s9, s4, s47
	s_add_u32 s11, s2, s55
	s_addc_u32 s33, s5, 0
	v_lshl_add_u64 v[2:3], s[12:13], 0, v[164:165]
	s_and_b64 s[12:13], s[14:15], exec
	global_load_lds_dwordx4 v[2:3], off
	s_cselect_b32 s13, s9, s33
	s_cselect_b32 s12, s8, s11
	s_add_i32 m0, s24, 0x6000
	s_add_u32 s6, s1, s6
	s_addc_u32 s7, s4, s7
	s_add_u32 s8, s2, s48
	s_addc_u32 s9, s5, 0
	v_lshl_add_u64 v[2:3], s[12:13], 0, v[164:165]
	s_and_b64 s[12:13], s[14:15], exec
	global_load_lds_dwordx4 v[2:3], off
	s_cselect_b32 s13, s7, s9
	s_cselect_b32 s12, s6, s8
	s_add_i32 m0, s24, 0x6400
	s_add_u32 s0, s1, s0
	s_addc_u32 s1, s4, s10
	s_add_u32 s2, s2, s49
	s_addc_u32 s4, s5, 0
	v_lshl_add_u64 v[2:3], s[12:13], 0, v[164:165]
	s_and_b64 s[12:13], s[26:27], exec
	s_cselect_b32 s13, s1, s4
	s_cselect_b32 s12, s0, s2
	global_load_lds_dwordx4 v[2:3], off
	v_lshl_add_u64 v[2:3], s[12:13], 0, v[164:165]
	s_add_i32 m0, s24, 0x6800
	s_waitcnt vmcnt(0)
	v_mul_f32_e32 v19, 0x4f800000, v18
	global_load_lds_dwordx4 v[2:3], off
	s_waitcnt vmcnt(3)
	s_barrier
	ds_read_b128 v[2:5], v171
	ds_read_b128 v[6:9], v171 offset:1024
	v_cmp_gt_f32_e32 vcc, s39, v18
	s_waitcnt lgkmcnt(0)
	v_mfma_scale_f32_32x32x64_f8f6f4 v[2:17], v[2:9], v[146:153], 0, v174, v174 op_sel_hi:[0,0,0]
	v_cndmask_b32_e32 v43, v18, v19, vcc
	v_sqrt_f32_e32 v26, v43
	ds_read_b128 v[18:21], v171 offset:2048
	ds_read_b128 v[22:25], v171 offset:3072
	s_add_u32 s44, s44, s46
	s_addc_u32 s45, s45, s47
	v_add_u32_e32 v27, -1, v26
	v_fma_f32 v28, -v27, v26, v43
	v_cmp_ge_f32_e64 s[12:13], 0, v28
	v_add_u32_e32 v28, 1, v26
	s_add_u32 s46, s52, s49
	v_cndmask_b32_e64 v27, v26, v27, s[12:13]
	v_fma_f32 v26, -v28, v26, v43
	v_cmp_lt_f32_e64 s[12:13], 0, v26
	s_addc_u32 s47, s53, 0
	s_add_u32 s48, s52, s48
	v_cndmask_b32_e64 v34, v27, v28, s[12:13]
	s_waitcnt lgkmcnt(0)
	v_mfma_scale_f32_32x32x64_f8f6f4 v[18:33], v[18:25], v[146:153], 0, v174, v174 op_sel_hi:[0,0,0]
	v_max3_f32 v2, v2, s40, v3
	v_max3_f32 v2, v2, v4, v5
	v_max3_f32 v2, v2, v6, v7
	v_max3_f32 v2, v2, v8, v9
	v_mul_f32_e32 v35, 0x37800000, v34
	v_max3_f32 v2, v2, v10, v11
	v_cndmask_b32_e32 v44, v34, v35, vcc
	ds_read_b128 v[34:37], v171 offset:4096
	ds_read_b128 v[38:41], v171 offset:5120
	v_max3_f32 v2, v2, v12, v13
	v_max3_f32 v2, v2, v14, v15
	v_max3_f32 v2, v2, v16, v17
	v_cmp_lt_i32_e32 vcc, v176, v177
	s_addc_u32 s49, s53, 0
	s_add_u32 s52, s52, s55
	s_addc_u32 s53, s53, 0
	s_nop 3
	v_max3_f32 v2, v2, v18, v19
	v_max3_f32 v2, v2, v20, v21
	v_max3_f32 v18, v2, v22, v23
	s_waitcnt lgkmcnt(0)
	v_mfma_scale_f32_32x32x64_f8f6f4 v[2:17], v[34:41], v[146:153], 0, v174, v174 op_sel_hi:[0,0,0]
	v_max3_f32 v18, v18, v24, v25
	v_max3_f32 v18, v18, v26, v27
	v_max3_f32 v18, v18, v28, v29
	v_max3_f32 v18, v18, v30, v31
	v_max3_f32 v26, v18, v32, v33
	ds_read_b128 v[18:21], v171 offset:6144
	ds_read_b128 v[22:25], v171 offset:7168
	s_mov_b32 s65, 0
	s_mov_b32 s55, 0
	v_mov_b32_e32 v27, v163
	v_mov_b32_e32 v28, v163
	v_mov_b32_e32 v29, v163
	v_mov_b32_e32 v30, v163
	v_mov_b32_e32 v31, v163
	v_mov_b32_e32 v32, v163
	v_mov_b32_e32 v33, v163
	s_nop 3
	v_max3_f32 v2, v26, v2, v3
	v_max3_f32 v2, v2, v4, v5
	v_max3_f32 v2, v2, v6, v7
	v_max3_f32 v2, v2, v8, v9
	v_max3_f32 v2, v2, v10, v11
	v_max3_f32 v2, v2, v12, v13
	v_max3_f32 v2, v2, v14, v15
	v_max3_f32 v26, v2, v16, v17
	s_waitcnt lgkmcnt(0)
	v_mfma_scale_f32_32x32x64_f8f6f4 v[2:17], v[18:25], v[146:153], 0, v174, v174 op_sel_hi:[0,0,0]
	v_mov_b32_e32 v18, 0
	v_mov_b32_e32 v19, v163
	v_mov_b32_e32 v20, v163
	v_mov_b32_e32 v21, v163
	v_mov_b32_e32 v22, v163
	v_mov_b32_e32 v23, v163
	v_mov_b32_e32 v24, v163
	v_mov_b32_e32 v25, v163
	v_mov_b32_e32 v34, 0
	v_mov_b32_e32 v35, v163
	v_mov_b32_e32 v36, v163
	v_mov_b32_e32 v37, v163
	v_mov_b32_e32 v38, v163
	v_mov_b32_e32 v39, v163
	v_mov_b32_e32 v40, v163
	s_nop 4
	v_max3_f32 v2, v26, v2, v3
	v_max3_f32 v2, v2, v4, v5
	v_max3_f32 v2, v2, v6, v7
	v_max3_f32 v2, v2, v8, v9
	v_max3_f32 v2, v2, v10, v11
	v_max3_f32 v2, v2, v12, v13
	v_max3_f32 v2, v2, v14, v15
	v_cndmask_b32_e32 v3, v175, v176, vcc
	v_max3_f32 v2, v2, v16, v17
	v_lshlrev_b32_e32 v3, 2, v3
	ds_bpermute_b32 v3, v3, v2
	v_cmp_class_f32_e32 vcc, v43, v172
	v_mov_b32_e32 v5, v163
	v_mov_b32_e32 v6, v163
	v_cndmask_b32_e32 v4, v44, v43, vcc
	s_waitcnt lgkmcnt(0)
	v_max_f32_e32 v3, v3, v3
	v_mul_f32_e32 v4, v42, v4
	v_max_f32_e32 v2, v2, v3
	v_fmamk_f32 v4, v4, 0x3f90a3d7, v173
	v_add_f32_e32 v2, 0x42800000, v2
	v_min_f32_e32 v2, v4, v2
	v_add_f32_e32 v2, 0xc2ec0000, v2
	v_xor_b32_e32 v50, 0x80000000, v2
	v_mov_b32_e32 v51, v50
	v_mov_b32_e32 v52, v50
	v_mov_b32_e32 v53, v50
	v_mov_b32_e32 v54, v50
	v_mov_b32_e32 v55, v50
	v_mov_b32_e32 v56, v50
	v_mov_b32_e32 v57, v50
	v_mov_b32_e32 v58, v50
	v_mov_b32_e32 v59, v50
	v_mov_b32_e32 v60, v50
	v_mov_b32_e32 v61, v50
	v_mov_b32_e32 v62, v50
	v_mov_b32_e32 v63, v50
	v_mov_b32_e32 v64, v50
	v_mov_b32_e32 v65, v50
	v_mov_b32_e32 v2, 0
	v_mov_b32_e32 v3, v163
	v_mov_b32_e32 v4, v163
	v_mov_b32_e32 v7, v163
	v_mov_b32_e32 v8, v163
	v_mov_b32_e32 v9, v163
	v_mov_b32_e32 v10, v163
	v_mov_b32_e32 v11, v163
	v_mov_b32_e32 v12, v163
	v_mov_b32_e32 v13, v163
	v_mov_b32_e32 v14, v163
	v_mov_b32_e32 v15, v163
	v_mov_b32_e32 v16, v163
	v_mov_b32_e32 v17, v163
	v_mov_b32_e32 v26, v163
	v_mov_b32_e32 v41, v163
	v_mov_b32_e32 v42, v163
	v_mov_b32_e32 v43, v163
	v_mov_b32_e32 v44, v163
	v_mov_b32_e32 v45, v163
	v_mov_b32_e32 v46, v163
	v_mov_b32_e32 v47, v163
	v_mov_b32_e32 v48, v163
	v_mov_b32_e32 v49, v163
	v_mov_b32_e32 v66, 0
	v_mov_b32_e32 v67, v163
	v_mov_b32_e32 v68, v163
	v_mov_b32_e32 v69, v163
	v_mov_b32_e32 v70, v163
	v_mov_b32_e32 v71, v163
	v_mov_b32_e32 v72, v163
	v_mov_b32_e32 v73, v163
	v_mov_b32_e32 v74, v163
	v_mov_b32_e32 v75, v163
	v_mov_b32_e32 v76, v163
	v_mov_b32_e32 v77, v163
	v_mov_b32_e32 v78, v163
	v_mov_b32_e32 v79, v163
	v_mov_b32_e32 v80, v163
	v_mov_b32_e32 v81, v163
	v_mov_b32_e32 v82, 0
	v_mov_b32_e32 v83, v163
	v_mov_b32_e32 v84, v163
	v_mov_b32_e32 v85, v163
	v_mov_b32_e32 v86, v163
	v_mov_b32_e32 v87, v163
	v_mov_b32_e32 v88, v163
	v_mov_b32_e32 v89, v163
	v_mov_b32_e32 v90, v163
	v_mov_b32_e32 v91, v163
	v_mov_b32_e32 v92, v163
	v_mov_b32_e32 v93, v163
	v_mov_b32_e32 v94, v163
	v_mov_b32_e32 v95, v163
	v_mov_b32_e32 v96, v163
	v_mov_b32_e32 v97, v163
	v_mov_b32_e32 v142, v210
	v_mov_b32_e32 v143, v211
	v_mov_b32_e32 v144, v218
	v_mov_b32_e32 v145, v219
	v_mov_b32_e32 v118, v163
	v_mov_b32_e32 v119, v163
	v_mov_b32_e32 v120, v163
	v_mov_b32_e32 v121, v163
	v_mov_b32_e32 v122, v163
	v_mov_b32_e32 v123, v163
	v_mov_b32_e32 v124, v163
	v_mov_b32_e32 v125, v163
	v_mov_b32_e32 v126, v163
	v_mov_b32_e32 v127, v163
	v_mov_b32_e32 v128, v163
	v_mov_b32_e32 v129, v163
	v_mov_b32_e32 v130, v163
	v_mov_b32_e32 v131, v163
	v_mov_b32_e32 v132, v163
	v_mov_b32_e32 v133, v163
	v_mov_b32_e32 v180, v163
	v_mov_b32_e32 v181, v163
	v_mov_b32_e32 v182, v163
	v_mov_b32_e32 v183, v163
	v_mov_b32_e32 v184, v163
	v_mov_b32_e32 v185, v163
	v_mov_b32_e32 v186, v163
	v_mov_b32_e32 v187, v163
	v_mov_b32_e32 v188, v163
	v_mov_b32_e32 v189, v163
	v_mov_b32_e32 v190, v163
	v_mov_b32_e32 v191, v163
	v_mov_b32_e32 v192, v163
	v_mov_b32_e32 v193, v163
	v_mov_b32_e32 v194, v163
	v_mov_b32_e32 v195, v163
	v_mov_b32_e32 v220, v163
	v_mov_b32_e32 v221, v163
	v_mov_b32_e32 v222, v163
	v_mov_b32_e32 v223, v163
	v_mov_b32_e32 v224, v163
	v_mov_b32_e32 v225, v163
	v_mov_b32_e32 v226, v163
	v_mov_b32_e32 v227, v163
	v_mov_b32_e32 v228, v163
	v_mov_b32_e32 v229, v163
	v_mov_b32_e32 v230, v163
	v_mov_b32_e32 v231, v163
	v_mov_b32_e32 v232, v163
	v_mov_b32_e32 v233, v163
	v_mov_b32_e32 v234, v163
	v_mov_b32_e32 v235, v163
	v_mov_b32_e32 v236, v163
	v_mov_b32_e32 v237, v163
	v_mov_b32_e32 v238, v163
	v_mov_b32_e32 v239, v163
	v_mov_b32_e32 v240, v163
	v_mov_b32_e32 v241, v163
	v_mov_b32_e32 v242, v163
	v_mov_b32_e32 v243, v163
	v_mov_b32_e32 v244, v163
	v_mov_b32_e32 v245, v163
	v_mov_b32_e32 v246, v163
	v_mov_b32_e32 v247, v163
	v_mov_b32_e32 v248, v163
	v_mov_b32_e32 v249, v163
	v_mov_b32_e32 v250, v163
	v_mov_b32_e32 v251, v163
	s_branch .LBB0_4072
.LBB0_4072:
	s_waitcnt vmcnt(0) lgkmcnt(0)
	s_barrier
	s_cmpk_gt_u32 s55, 0x7f
	s_cselect_b64 s[12:13], -1, 0
	s_xor_b32 s64, s65, 2
	s_mul_i32 s100, s65, 0x6000
	s_add_i32 s55, s55, 2
	s_andn2_b64 vcc, exec, s[12:13]
	v_add_u32_e32 v179, s100, v171
	s_mov_b32 s65, s64
.LBB0_4071:
	ds_read_b128 v[204:207], v179
	ds_read_b128 v[208:211], v179 offset:1024
	ds_read_b128 v[212:215], v179 offset:2048
	ds_read_b128 v[216:219], v179 offset:3072
	v_med3_f32 v118, v118, 0, v178
	v_med3_f32 v122, v122, 0, v178
	v_med3_f32 v126, v126, 0, v178
	v_med3_f32 v130, v130, 0, v178
	v_cvt_pk_u8_f32 v196, v118, 0, 0
	v_cvt_pk_u8_f32 v197, v122, 0, 0
	v_cvt_pk_u8_f32 v198, v126, 0, 0
	v_cvt_pk_u8_f32 v199, v130, 0, 0
	v_med3_f32 v119, v119, 0, v178
	v_med3_f32 v123, v123, 0, v178
	v_med3_f32 v127, v127, 0, v178
	v_med3_f32 v131, v131, 0, v178
	v_cvt_pk_u8_f32 v196, v119, 1, v196
	v_cvt_pk_u8_f32 v197, v123, 1, v197
	v_cvt_pk_u8_f32 v198, v127, 1, v198
	v_cvt_pk_u8_f32 v199, v131, 1, v199
	s_waitcnt lgkmcnt(2)
	v_mfma_scale_f32_32x32x64_f8f6f4 v[86:101], v[204:211], v[146:153], v[50:65], v174, v174 op_sel_hi:[0,0,0]
	v_med3_f32 v120, v120, 0, v178
	v_med3_f32 v124, v124, 0, v178
	v_med3_f32 v128, v128, 0, v178
	v_med3_f32 v132, v132, 0, v178
	v_cvt_pk_u8_f32 v196, v120, 2, v196
	v_cvt_pk_u8_f32 v197, v124, 2, v197
	v_cvt_pk_u8_f32 v198, v128, 2, v198
	v_cvt_pk_u8_f32 v199, v132, 2, v199
	v_med3_f32 v121, v121, 0, v178
	v_med3_f32 v125, v125, 0, v178
	v_med3_f32 v129, v129, 0, v178
	v_med3_f32 v133, v133, 0, v178
	v_cvt_pk_u8_f32 v196, v121, 3, v196
	v_cvt_pk_u8_f32 v197, v125, 3, v197
	v_cvt_pk_u8_f32 v198, v129, 3, v198
	v_cvt_pk_u8_f32 v199, v133, 3, v199
	v_med3_f32 v180, v180, 0, v178
	v_med3_f32 v184, v184, 0, v178
	v_med3_f32 v188, v188, 0, v178
	v_med3_f32 v192, v192, 0, v178
	v_cvt_pk_u8_f32 v200, v180, 0, 0
	v_cvt_pk_u8_f32 v201, v184, 0, 0
	v_cvt_pk_u8_f32 v202, v188, 0, 0
	v_cvt_pk_u8_f32 v203, v192, 0, 0
	s_waitcnt lgkmcnt(0)
	v_mfma_scale_f32_32x32x64_f8f6f4 v[102:117], v[212:219], v[146:153], v[50:65], v174, v174 op_sel_hi:[0,0,0]
	v_med3_f32 v181, v181, 0, v178
	v_med3_f32 v185, v185, 0, v178
	v_med3_f32 v189, v189, 0, v178
	v_med3_f32 v193, v193, 0, v178
	v_cvt_pk_u8_f32 v200, v181, 1, v200
	v_cvt_pk_u8_f32 v201, v185, 1, v201
	v_cvt_pk_u8_f32 v202, v189, 1, v202
	v_cvt_pk_u8_f32 v203, v193, 1, v203
	v_med3_f32 v182, v182, 0, v178
	v_med3_f32 v186, v186, 0, v178
	v_med3_f32 v190, v190, 0, v178
	v_med3_f32 v194, v194, 0, v178
	v_cvt_pk_u8_f32 v200, v182, 2, v200
	v_cvt_pk_u8_f32 v201, v186, 2, v201
	v_cvt_pk_u8_f32 v202, v190, 2, v202
	v_cvt_pk_u8_f32 v203, v194, 2, v203
	v_med3_f32 v183, v183, 0, v178
	v_med3_f32 v187, v187, 0, v178
	v_med3_f32 v191, v191, 0, v178
	v_med3_f32 v195, v195, 0, v178
	v_cvt_pk_u8_f32 v200, v183, 3, v200
	v_cvt_pk_u8_f32 v201, v187, 3, v201
	v_cvt_pk_u8_f32 v202, v191, 3, v202
	v_cvt_pk_u8_f32 v203, v195, 3, v203
	s_nop 1
	v_mfma_scale_f32_32x32x64_f8f6f4 v[66:81], v[220:227], v[196:203], v[66:81], v174, v174 op_sel_hi:[0,0,0] blgp:1
	ds_read_b128 v[204:207], v179 offset:4096
	ds_read_b128 v[208:211], v179 offset:5120
	ds_read_b128 v[212:215], v179 offset:6144
	ds_read_b128 v[216:219], v179 offset:7168
	s_cbranch_vccz .Ldma_dif1_skip0
	s_add_u32 s1, s29, s44
	s_addc_u32 s2, s30, s45
	s_add_u32 s4, s1, 0x36532100
	s_addc_u32 s5, s2, 0
	s_add_u32 s6, s29, s52
	s_addc_u32 s7, s30, s53
	s_add_u32 s8, s6, 0x385b6100
	s_addc_u32 s9, s7, 0
	s_mul_i32 s0, s64, 0x6000
	s_and_b64 s[66:67], s[14:15], exec
	s_cselect_b32 s67, s5, s9
	s_cselect_b32 s66, s4, s8
	s_add_i32 s0, s24, s0
	s_add_u32 s4, s1, 0x36532500
	s_addc_u32 s5, s2, 0
	s_add_u32 s8, s29, s48
	s_addc_u32 s9, s30, s49
	s_add_u32 s10, s8, 0x385b6100
	s_addc_u32 s11, s9, 0
	s_mov_b32 m0, s0
	s_nop 0
	global_load_lds_dwordx4 v164, s[66:67]
.Ldma_dif1_skip0:
	v_mfma_scale_f32_32x32x64_f8f6f4 v[34:49], v[228:235], v[196:203], v[34:49], v174, v174 op_sel_hi:[0,0,0] blgp:1
	ds_read_b128 v[220:223], v179 offset:8192
	ds_read_b128 v[224:227], v179 offset:9216
	s_cbranch_vccz .Ldma_dif1_skip1
	s_and_b64 s[66:67], s[14:15], exec
	s_cselect_b32 s67, s5, s11
	s_cselect_b32 s66, s4, s10
	s_add_i32 m0, s0, 0x400
	s_add_u32 s4, s1, 0x36532900
	s_addc_u32 s5, s2, 0
	s_add_u32 s10, s29, s46
	s_addc_u32 s11, s30, s47
	s_add_u32 s33, s10, 0x385b6100
	s_addc_u32 s50, s11, 0
	global_load_lds_dwordx4 v164, s[66:67]
.Ldma_dif1_skip1:
	v_mfma_scale_f32_32x32x64_f8f6f4 v[18:33], v[236:243], v[196:203], v[18:33], v174, v174 op_sel_hi:[0,0,0] blgp:1
	ds_read_b128 v[228:231], v179 offset:10240
	ds_read_b128 v[232:235], v179 offset:11264
	v_mfma_scale_f32_32x32x64_f8f6f4 v[2:17], v[244:251], v[196:203], v[2:17], v174, v174 op_sel_hi:[0,0,0] blgp:1
	ds_read_b128 v[236:239], v179 offset:12288
	ds_read_b128 v[240:243], v179 offset:13312
	v_mfma_scale_f32_16x16x128_f8f6f4 v[82:85], v[154:161], v[196:203], v[82:85], v174, v174 op_sel_hi:[0,0,0] blgp:1
	ds_read_b128 v[244:247], v179 offset:14336
	ds_read_b128 v[248:251], v179 offset:15360
	v_med3_f32 v86, v86, 0, v178
	v_med3_f32 v90, v90, 0, v178
	v_med3_f32 v94, v94, 0, v178
	v_med3_f32 v98, v98, 0, v178
	v_cvt_pk_u8_f32 v196, v86, 0, 0
	v_cvt_pk_u8_f32 v197, v90, 0, 0
	v_cvt_pk_u8_f32 v198, v94, 0, 0
	v_cvt_pk_u8_f32 v199, v98, 0, 0
	v_med3_f32 v87, v87, 0, v178
	v_med3_f32 v91, v91, 0, v178
	v_med3_f32 v95, v95, 0, v178
	v_med3_f32 v99, v99, 0, v178
	v_cvt_pk_u8_f32 v196, v87, 1, v196
	v_cvt_pk_u8_f32 v197, v91, 1, v197
	v_cvt_pk_u8_f32 v198, v95, 1, v198
	v_cvt_pk_u8_f32 v199, v99, 1, v199
	s_waitcnt lgkmcnt(10)
	v_mfma_scale_f32_32x32x64_f8f6f4 v[118:133], v[204:211], v[146:153], v[50:65], v174, v174 op_sel_hi:[0,0,0]
	v_med3_f32 v88, v88, 0, v178
	v_med3_f32 v92, v92, 0, v178
	v_med3_f32 v96, v96, 0, v178
	v_med3_f32 v100, v100, 0, v178
	v_cvt_pk_u8_f32 v196, v88, 2, v196
	v_cvt_pk_u8_f32 v197, v92, 2, v197
	v_cvt_pk_u8_f32 v198, v96, 2, v198
	v_cvt_pk_u8_f32 v199, v100, 2, v199
	v_med3_f32 v89, v89, 0, v178
	v_med3_f32 v93, v93, 0, v178
	v_med3_f32 v97, v97, 0, v178
	v_med3_f32 v101, v101, 0, v178
	v_cvt_pk_u8_f32 v196, v89, 3, v196
	v_cvt_pk_u8_f32 v197, v93, 3, v197
	v_cvt_pk_u8_f32 v198, v97, 3, v198
	v_cvt_pk_u8_f32 v199, v101, 3, v199
	v_med3_f32 v102, v102, 0, v178
	v_med3_f32 v106, v106, 0, v178
	v_med3_f32 v110, v110, 0, v178
	v_med3_f32 v114, v114, 0, v178
	v_cvt_pk_u8_f32 v200, v102, 0, 0
	v_cvt_pk_u8_f32 v201, v106, 0, 0
	v_cvt_pk_u8_f32 v202, v110, 0, 0
	v_cvt_pk_u8_f32 v203, v114, 0, 0
	s_waitcnt lgkmcnt(8)
	v_mfma_scale_f32_32x32x64_f8f6f4 v[180:195], v[212:219], v[146:153], v[50:65], v174, v174 op_sel_hi:[0,0,0]
	v_med3_f32 v103, v103, 0, v178
	v_med3_f32 v107, v107, 0, v178
	v_med3_f32 v111, v111, 0, v178
	v_med3_f32 v115, v115, 0, v178
	v_cvt_pk_u8_f32 v200, v103, 1, v200
	v_cvt_pk_u8_f32 v201, v107, 1, v201
	v_cvt_pk_u8_f32 v202, v111, 1, v202
	v_cvt_pk_u8_f32 v203, v115, 1, v203
	v_med3_f32 v104, v104, 0, v178
	v_med3_f32 v108, v108, 0, v178
	v_med3_f32 v112, v112, 0, v178
	v_med3_f32 v116, v116, 0, v178
	v_cvt_pk_u8_f32 v200, v104, 2, v200
	v_cvt_pk_u8_f32 v201, v108, 2, v201
	v_cvt_pk_u8_f32 v202, v112, 2, v202
	v_cvt_pk_u8_f32 v203, v116, 2, v203
	v_med3_f32 v105, v105, 0, v178
	v_med3_f32 v109, v109, 0, v178
	v_med3_f32 v113, v113, 0, v178
	v_med3_f32 v117, v117, 0, v178
	v_cvt_pk_u8_f32 v200, v105, 3, v200
	v_cvt_pk_u8_f32 v201, v109, 3, v201
	v_cvt_pk_u8_f32 v202, v113, 3, v202
	v_cvt_pk_u8_f32 v203, v117, 3, v203
	s_nop 1
	s_waitcnt lgkmcnt(6)
	v_mfma_scale_f32_32x32x64_f8f6f4 v[66:81], v[220:227], v[196:203], v[66:81], v174, v174 op_sel_hi:[0,0,0] blgp:1
	ds_read_b128 v[204:207], v179 offset:24576
	ds_read_b128 v[208:211], v179 offset:25600
	ds_read_b128 v[212:215], v179 offset:26624
	ds_read_b128 v[216:219], v179 offset:27648
	s_cbranch_vccz .Ldma_dif1_skip2
	s_and_b64 s[66:67], s[26:27], exec
	s_cselect_b32 s67, s5, s50
	s_cselect_b32 s66, s4, s33
	s_add_i32 m0, s0, 0x800
	s_add_u32 s4, s1, 0x36534100
	s_addc_u32 s5, s2, 0
	s_add_u32 s6, s6, 0x385ba100
	s_addc_u32 s7, s7, 0
	global_load_lds_dwordx4 v164, s[66:67]
.Ldma_dif1_skip2:
	s_waitcnt lgkmcnt(8)
	v_mfma_scale_f32_32x32x64_f8f6f4 v[34:49], v[228:235], v[196:203], v[34:49], v174, v174 op_sel_hi:[0,0,0] blgp:1
	ds_read_b128 v[220:223], v179 offset:16384
	ds_read_b128 v[224:227], v179 offset:17408
	s_cbranch_vccz .Ldma_dif1_skip3
	s_and_b64 s[66:67], s[14:15], exec
	s_cselect_b32 s67, s5, s7
	s_cselect_b32 s66, s4, s6
	s_add_i32 m0, s0, 0x6000
	s_add_u32 s4, s1, 0x36534500
	s_addc_u32 s5, s2, 0
	s_add_u32 s6, s8, 0x385ba100
	s_addc_u32 s7, s9, 0
	global_load_lds_dwordx4 v164, s[66:67]
.Ldma_dif1_skip3:
	s_waitcnt lgkmcnt(8)
	v_mfma_scale_f32_32x32x64_f8f6f4 v[18:33], v[236:243], v[196:203], v[18:33], v174, v174 op_sel_hi:[0,0,0] blgp:1
	ds_read_b128 v[228:231], v179 offset:18432
	ds_read_b128 v[232:235], v179 offset:19456
	s_waitcnt lgkmcnt(8)
	v_mfma_scale_f32_32x32x64_f8f6f4 v[2:17], v[244:251], v[196:203], v[2:17], v174, v174 op_sel_hi:[0,0,0] blgp:1
	ds_read_b128 v[236:239], v179 offset:20480
	ds_read_b128 v[240:243], v179 offset:21504
	v_mfma_scale_f32_16x16x128_f8f6f4 v[82:85], v[154:161], v[196:203], v[82:85], v174, v174 op_sel_hi:[0,0,0] blgp:1
	ds_read_b128 v[244:247], v179 offset:22528
	ds_read_b128 v[248:251], v179 offset:23552
	v_med3_f32 v118, v118, 0, v178
	v_med3_f32 v122, v122, 0, v178
	v_med3_f32 v126, v126, 0, v178
	v_med3_f32 v130, v130, 0, v178
	v_cvt_pk_u8_f32 v196, v118, 0, 0
	v_cvt_pk_u8_f32 v197, v122, 0, 0
	v_cvt_pk_u8_f32 v198, v126, 0, 0
	v_cvt_pk_u8_f32 v199, v130, 0, 0
	v_med3_f32 v119, v119, 0, v178
	v_med3_f32 v123, v123, 0, v178
	v_med3_f32 v127, v127, 0, v178
	v_med3_f32 v131, v131, 0, v178
	v_cvt_pk_u8_f32 v196, v119, 1, v196
	v_cvt_pk_u8_f32 v197, v123, 1, v197
	v_cvt_pk_u8_f32 v198, v127, 1, v198
	v_cvt_pk_u8_f32 v199, v131, 1, v199
	s_waitcnt lgkmcnt(10)
	v_mfma_scale_f32_32x32x64_f8f6f4 v[86:101], v[204:211], v[146:153], v[50:65], v174, v174 op_sel_hi:[0,0,0]
	v_med3_f32 v120, v120, 0, v178
	v_med3_f32 v124, v124, 0, v178
	v_med3_f32 v128, v128, 0, v178
	v_med3_f32 v132, v132, 0, v178
	v_cvt_pk_u8_f32 v196, v120, 2, v196
	v_cvt_pk_u8_f32 v197, v124, 2, v197
	v_cvt_pk_u8_f32 v198, v128, 2, v198
	v_cvt_pk_u8_f32 v199, v132, 2, v199
	v_med3_f32 v121, v121, 0, v178
	v_med3_f32 v125, v125, 0, v178
	v_med3_f32 v129, v129, 0, v178
	v_med3_f32 v133, v133, 0, v178
	v_cvt_pk_u8_f32 v196, v121, 3, v196
	v_cvt_pk_u8_f32 v197, v125, 3, v197
	v_cvt_pk_u8_f32 v198, v129, 3, v198
	v_cvt_pk_u8_f32 v199, v133, 3, v199
	v_med3_f32 v180, v180, 0, v178
	v_med3_f32 v184, v184, 0, v178
	v_med3_f32 v188, v188, 0, v178
	v_med3_f32 v192, v192, 0, v178
	v_cvt_pk_u8_f32 v200, v180, 0, 0
	v_cvt_pk_u8_f32 v201, v184, 0, 0
	v_cvt_pk_u8_f32 v202, v188, 0, 0
	v_cvt_pk_u8_f32 v203, v192, 0, 0
	s_waitcnt lgkmcnt(8)
	v_mfma_scale_f32_32x32x64_f8f6f4 v[102:117], v[212:219], v[146:153], v[50:65], v174, v174 op_sel_hi:[0,0,0]
	v_med3_f32 v181, v181, 0, v178
	v_med3_f32 v185, v185, 0, v178
	v_med3_f32 v189, v189, 0, v178
	v_med3_f32 v193, v193, 0, v178
	v_cvt_pk_u8_f32 v200, v181, 1, v200
	v_cvt_pk_u8_f32 v201, v185, 1, v201
	v_cvt_pk_u8_f32 v202, v189, 1, v202
	v_cvt_pk_u8_f32 v203, v193, 1, v203
	v_med3_f32 v182, v182, 0, v178
	v_med3_f32 v186, v186, 0, v178
	v_med3_f32 v190, v190, 0, v178
	v_med3_f32 v194, v194, 0, v178
	v_cvt_pk_u8_f32 v200, v182, 2, v200
	v_cvt_pk_u8_f32 v201, v186, 2, v201
	v_cvt_pk_u8_f32 v202, v190, 2, v202
	v_cvt_pk_u8_f32 v203, v194, 2, v203
	v_med3_f32 v183, v183, 0, v178
	v_med3_f32 v187, v187, 0, v178
	v_med3_f32 v191, v191, 0, v178
	v_med3_f32 v195, v195, 0, v178
	v_cvt_pk_u8_f32 v200, v183, 3, v200
	v_cvt_pk_u8_f32 v201, v187, 3, v201
	v_cvt_pk_u8_f32 v202, v191, 3, v202
	v_cvt_pk_u8_f32 v203, v195, 3, v203
	s_nop 1
	s_waitcnt lgkmcnt(6)
	v_mfma_scale_f32_32x32x64_f8f6f4 v[66:81], v[220:227], v[196:203], v[66:81], v174, v174 op_sel_hi:[0,0,0] blgp:1
	ds_read_b128 v[204:207], v179 offset:28672
	ds_read_b128 v[208:211], v179 offset:29696
	ds_read_b128 v[212:215], v179 offset:30720
	ds_read_b128 v[216:219], v179 offset:31744
	s_cbranch_vccz .Ldma_dif1_skip4
	s_and_b64 s[66:67], s[14:15], exec
	s_cselect_b32 s67, s5, s7
	s_cselect_b32 s66, s4, s6
	s_add_i32 m0, s0, 0x6400
	s_add_u32 s1, s1, 0x36534900
	s_addc_u32 s2, s2, 0
	s_add_u32 s4, s10, 0x385ba100
	s_addc_u32 s5, s11, 0
	global_load_lds_dwordx4 v164, s[66:67]
.Ldma_dif1_skip4:
	s_waitcnt lgkmcnt(8)
	v_mfma_scale_f32_32x32x64_f8f6f4 v[34:49], v[228:235], v[196:203], v[34:49], v174, v174 op_sel_hi:[0,0,0] blgp:1
	ds_read_b128 v[220:223], v179 offset:32768
	ds_read_b128 v[224:227], v179 offset:33792
	s_cbranch_vccz .Ldma_dif1_skip5
	s_and_b64 s[66:67], s[26:27], exec
	s_cselect_b32 s67, s2, s5
	s_cselect_b32 s66, s1, s4
	s_add_i32 m0, s0, 0x6800
	s_nop 0
	global_load_lds_dwordx4 v164, s[66:67]
.Ldma_dif1_skip5:
	s_add_u32 s44, s44, 0x4000
	s_addc_u32 s45, s45, 0
	s_add_u32 s46, s46, 0x8000
	s_addc_u32 s47, s47, 0
	s_add_u32 s48, s48, 0x8000
	s_addc_u32 s49, s49, 0
	s_add_u32 s52, s52, 0x8000
	s_addc_u32 s53, s53, 0
	s_waitcnt lgkmcnt(8)
	v_mfma_scale_f32_32x32x64_f8f6f4 v[18:33], v[236:243], v[196:203], v[18:33], v174, v174 op_sel_hi:[0,0,0] blgp:1
	ds_read_b128 v[228:231], v179 offset:34816
	ds_read_b128 v[232:235], v179 offset:35840
	s_waitcnt lgkmcnt(8)
	v_mfma_scale_f32_32x32x64_f8f6f4 v[2:17], v[244:251], v[196:203], v[2:17], v174, v174 op_sel_hi:[0,0,0] blgp:1
	ds_read_b128 v[236:239], v179 offset:36864
	ds_read_b128 v[240:243], v179 offset:37888
	v_mfma_scale_f32_16x16x128_f8f6f4 v[82:85], v[154:161], v[196:203], v[82:85], v174, v174 op_sel_hi:[0,0,0] blgp:1
	ds_read_b128 v[244:247], v179 offset:38912
	ds_read_b128 v[248:251], v179 offset:39936
	v_med3_f32 v86, v86, 0, v178
	v_med3_f32 v90, v90, 0, v178
	v_med3_f32 v94, v94, 0, v178
	v_med3_f32 v98, v98, 0, v178
	v_cvt_pk_u8_f32 v196, v86, 0, 0
	v_cvt_pk_u8_f32 v197, v90, 0, 0
	v_cvt_pk_u8_f32 v198, v94, 0, 0
	v_cvt_pk_u8_f32 v199, v98, 0, 0
	v_med3_f32 v87, v87, 0, v178
	v_med3_f32 v91, v91, 0, v178
	v_med3_f32 v95, v95, 0, v178
	v_med3_f32 v99, v99, 0, v178
	v_cvt_pk_u8_f32 v196, v87, 1, v196
	v_cvt_pk_u8_f32 v197, v91, 1, v197
	v_cvt_pk_u8_f32 v198, v95, 1, v198
	v_cvt_pk_u8_f32 v199, v99, 1, v199
	s_waitcnt lgkmcnt(10)
	v_mfma_scale_f32_32x32x64_f8f6f4 v[118:133], v[204:211], v[146:153], v[50:65], v174, v174 op_sel_hi:[0,0,0]
	v_med3_f32 v88, v88, 0, v178
	v_med3_f32 v92, v92, 0, v178
	v_med3_f32 v96, v96, 0, v178
	v_med3_f32 v100, v100, 0, v178
	v_cvt_pk_u8_f32 v196, v88, 2, v196
	v_cvt_pk_u8_f32 v197, v92, 2, v197
	v_cvt_pk_u8_f32 v198, v96, 2, v198
	v_cvt_pk_u8_f32 v199, v100, 2, v199
	v_med3_f32 v89, v89, 0, v178
	v_med3_f32 v93, v93, 0, v178
	v_med3_f32 v97, v97, 0, v178
	v_med3_f32 v101, v101, 0, v178
	v_cvt_pk_u8_f32 v196, v89, 3, v196
	v_cvt_pk_u8_f32 v197, v93, 3, v197
	v_cvt_pk_u8_f32 v198, v97, 3, v198
	v_cvt_pk_u8_f32 v199, v101, 3, v199
	v_med3_f32 v102, v102, 0, v178
	v_med3_f32 v106, v106, 0, v178
	v_med3_f32 v110, v110, 0, v178
	v_med3_f32 v114, v114, 0, v178
	v_cvt_pk_u8_f32 v200, v102, 0, 0
	v_cvt_pk_u8_f32 v201, v106, 0, 0
	v_cvt_pk_u8_f32 v202, v110, 0, 0
	v_cvt_pk_u8_f32 v203, v114, 0, 0
	s_waitcnt lgkmcnt(8)
	v_mfma_scale_f32_32x32x64_f8f6f4 v[180:195], v[212:219], v[146:153], v[50:65], v174, v174 op_sel_hi:[0,0,0]
	v_med3_f32 v103, v103, 0, v178
	v_med3_f32 v107, v107, 0, v178
	v_med3_f32 v111, v111, 0, v178
	v_med3_f32 v115, v115, 0, v178
	v_cvt_pk_u8_f32 v200, v103, 1, v200
	v_cvt_pk_u8_f32 v201, v107, 1, v201
	v_cvt_pk_u8_f32 v202, v111, 1, v202
	v_cvt_pk_u8_f32 v203, v115, 1, v203
	v_med3_f32 v104, v104, 0, v178
	v_med3_f32 v108, v108, 0, v178
	v_med3_f32 v112, v112, 0, v178
	v_med3_f32 v116, v116, 0, v178
	v_cvt_pk_u8_f32 v200, v104, 2, v200
	v_cvt_pk_u8_f32 v201, v108, 2, v201
	v_cvt_pk_u8_f32 v202, v112, 2, v202
	v_cvt_pk_u8_f32 v203, v116, 2, v203
	v_med3_f32 v105, v105, 0, v178
	v_med3_f32 v109, v109, 0, v178
	v_med3_f32 v113, v113, 0, v178
	v_med3_f32 v117, v117, 0, v178
	v_cvt_pk_u8_f32 v200, v105, 3, v200
	v_cvt_pk_u8_f32 v201, v109, 3, v201
	v_cvt_pk_u8_f32 v202, v113, 3, v202
	v_cvt_pk_u8_f32 v203, v117, 3, v203
	s_nop 1
	s_waitcnt lgkmcnt(6)
	v_mfma_scale_f32_32x32x64_f8f6f4 v[66:81], v[220:227], v[196:203], v[66:81], v174, v174 op_sel_hi:[0,0,0] blgp:1
	s_waitcnt lgkmcnt(4)
	v_mfma_scale_f32_32x32x64_f8f6f4 v[34:49], v[228:235], v[196:203], v[34:49], v174, v174 op_sel_hi:[0,0,0] blgp:1
	ds_read_b128 v[220:223], v179 offset:40960
	ds_read_b128 v[224:227], v179 offset:41984
	s_waitcnt lgkmcnt(4)
	v_mfma_scale_f32_32x32x64_f8f6f4 v[18:33], v[236:243], v[196:203], v[18:33], v174, v174 op_sel_hi:[0,0,0] blgp:1
	ds_read_b128 v[228:231], v179 offset:43008
	ds_read_b128 v[232:235], v179 offset:44032
	s_waitcnt lgkmcnt(4)
	v_mfma_scale_f32_32x32x64_f8f6f4 v[2:17], v[244:251], v[196:203], v[2:17], v174, v174 op_sel_hi:[0,0,0] blgp:1
	ds_read_b128 v[236:239], v179 offset:45056
	ds_read_b128 v[240:243], v179 offset:46080
	v_mfma_scale_f32_16x16x128_f8f6f4 v[82:85], v[154:161], v[196:203], v[82:85], v174, v174 op_sel_hi:[0,0,0] blgp:1
	ds_read_b128 v[244:247], v179 offset:47104
	ds_read_b128 v[248:251], v179 offset:48128
	s_cbranch_vccnz .LBB0_4072
	s_waitcnt lgkmcnt(0)
	v_med3_f32 v118, v118, 0, v178
	v_med3_f32 v122, v122, 0, v178
	v_med3_f32 v126, v126, 0, v178
	v_med3_f32 v130, v130, 0, v178
	v_cvt_pk_u8_f32 v196, v118, 0, 0
	v_cvt_pk_u8_f32 v197, v122, 0, 0
	v_cvt_pk_u8_f32 v198, v126, 0, 0
	v_cvt_pk_u8_f32 v199, v130, 0, 0
	v_med3_f32 v119, v119, 0, v178
	v_med3_f32 v123, v123, 0, v178
	v_med3_f32 v127, v127, 0, v178
	v_med3_f32 v131, v131, 0, v178
	v_cvt_pk_u8_f32 v196, v119, 1, v196
	v_cvt_pk_u8_f32 v197, v123, 1, v197
	v_cvt_pk_u8_f32 v198, v127, 1, v198
	v_cvt_pk_u8_f32 v199, v131, 1, v199
	v_med3_f32 v120, v120, 0, v178
	v_med3_f32 v124, v124, 0, v178
	v_med3_f32 v128, v128, 0, v178
	v_med3_f32 v132, v132, 0, v178
	v_cvt_pk_u8_f32 v196, v120, 2, v196
	v_cvt_pk_u8_f32 v197, v124, 2, v197
	v_cvt_pk_u8_f32 v198, v128, 2, v198
	v_cvt_pk_u8_f32 v199, v132, 2, v199
	v_med3_f32 v121, v121, 0, v178
	v_med3_f32 v125, v125, 0, v178
	v_med3_f32 v129, v129, 0, v178
	v_med3_f32 v133, v133, 0, v178
	v_cvt_pk_u8_f32 v196, v121, 3, v196
	v_cvt_pk_u8_f32 v197, v125, 3, v197
	v_cvt_pk_u8_f32 v198, v129, 3, v198
	v_cvt_pk_u8_f32 v199, v133, 3, v199
	v_med3_f32 v180, v180, 0, v178
	v_med3_f32 v184, v184, 0, v178
	v_med3_f32 v188, v188, 0, v178
	v_med3_f32 v192, v192, 0, v178
	v_cvt_pk_u8_f32 v200, v180, 0, 0
	v_cvt_pk_u8_f32 v201, v184, 0, 0
	v_cvt_pk_u8_f32 v202, v188, 0, 0
	v_cvt_pk_u8_f32 v203, v192, 0, 0
	v_med3_f32 v181, v181, 0, v178
	v_med3_f32 v185, v185, 0, v178
	v_med3_f32 v189, v189, 0, v178
	v_med3_f32 v193, v193, 0, v178
	v_cvt_pk_u8_f32 v200, v181, 1, v200
	v_cvt_pk_u8_f32 v201, v185, 1, v201
	v_cvt_pk_u8_f32 v202, v189, 1, v202
	v_cvt_pk_u8_f32 v203, v193, 1, v203
	v_med3_f32 v182, v182, 0, v178
	v_med3_f32 v186, v186, 0, v178
	v_med3_f32 v190, v190, 0, v178
	v_med3_f32 v194, v194, 0, v178
	v_cvt_pk_u8_f32 v200, v182, 2, v200
	v_cvt_pk_u8_f32 v201, v186, 2, v201
	v_cvt_pk_u8_f32 v202, v190, 2, v202
	v_cvt_pk_u8_f32 v203, v194, 2, v203
	v_med3_f32 v183, v183, 0, v178
	v_med3_f32 v187, v187, 0, v178
	v_med3_f32 v191, v191, 0, v178
	v_med3_f32 v195, v195, 0, v178
	v_cvt_pk_u8_f32 v200, v183, 3, v200
	v_cvt_pk_u8_f32 v201, v187, 3, v201
	v_cvt_pk_u8_f32 v202, v191, 3, v202
	v_cvt_pk_u8_f32 v203, v195, 3, v203
	s_nop 1
	v_mfma_scale_f32_32x32x64_f8f6f4 v[66:81], v[220:227], v[196:203], v[66:81], v174, v174 op_sel_hi:[0,0,0] blgp:1
	v_mfma_scale_f32_32x32x64_f8f6f4 v[34:49], v[228:235], v[196:203], v[34:49], v174, v174 op_sel_hi:[0,0,0] blgp:1
	v_mfma_scale_f32_32x32x64_f8f6f4 v[18:33], v[236:243], v[196:203], v[18:33], v174, v174 op_sel_hi:[0,0,0] blgp:1
	v_mfma_scale_f32_32x32x64_f8f6f4 v[2:17], v[244:251], v[196:203], v[2:17], v174, v174 op_sel_hi:[0,0,0] blgp:1
	v_mfma_scale_f32_16x16x128_f8f6f4 v[82:85], v[154:161], v[196:203], v[82:85], v174, v174 op_sel_hi:[0,0,0] blgp:1
	v_mov_b32_e32 v210, v142
	v_mov_b32_e32 v211, v143
	v_mov_b32_e32 v218, v144
	v_mov_b32_e32 v219, v145
	s_branch .LBB0_4069

	.amdhsa_kernel _Z6k_mega6Params
		.amdhsa_group_segment_fixed_size 0
		.amdhsa_private_segment_fixed_size 0
		.amdhsa_kernarg_size 520
		.amdhsa_user_sgpr_count 2
		.amdhsa_user_sgpr_dispatch_ptr 0
		.amdhsa_user_sgpr_queue_ptr 0
		.amdhsa_user_sgpr_kernarg_segment_ptr 1
		.amdhsa_user_sgpr_dispatch_id 0
		.amdhsa_user_sgpr_kernarg_preload_length 0
		.amdhsa_user_sgpr_kernarg_preload_offset 0
		.amdhsa_user_sgpr_private_segment_size 0
		.amdhsa_uses_dynamic_stack 0
		.amdhsa_enable_private_segment 0
		.amdhsa_system_sgpr_workgroup_id_x 1
		.amdhsa_system_sgpr_workgroup_id_y 0
		.amdhsa_system_sgpr_workgroup_id_z 0
		.amdhsa_system_sgpr_workgroup_info 0
		.amdhsa_system_vgpr_workitem_id 0
		.amdhsa_next_free_vgpr 256
		.amdhsa_next_free_sgpr 102
		.amdhsa_accum_offset 256
		.amdhsa_reserve_vcc 1
		.amdhsa_float_round_mode_32 0
		.amdhsa_float_round_mode_16_64 0
		.amdhsa_float_denorm_mode_32 3
		.amdhsa_float_denorm_mode_16_64 3
		.amdhsa_dx10_clamp 1
		.amdhsa_ieee_mode 1
		.amdhsa_fp16_overflow 0
		.amdhsa_tg_split 0
		.amdhsa_exception_fp_ieee_invalid_op 0
		.amdhsa_exception_fp_denorm_src 0
		.amdhsa_exception_fp_ieee_div_zero 0
		.amdhsa_exception_fp_ieee_overflow 0
		.amdhsa_exception_fp_ieee_underflow 0
		.amdhsa_exception_fp_ieee_inexact 0
		.amdhsa_exception_int_div_zero 0
	.end_amdhsa_kernel

amdhsa.kernels:
  - .agpr_count:     0
    .args:
      - .offset:         0
        .size:           264
        .value_kind:     by_value
      - .offset:         264
        .size:           4
        .value_kind:     hidden_block_count_x
      - .offset:         268
        .size:           4
        .value_kind:     hidden_block_count_y
      - .offset:         272
        .size:           4
        .value_kind:     hidden_block_count_z
      - .offset:         276
        .size:           2
        .value_kind:     hidden_group_size_x
      - .offset:         278
        .size:           2
        .value_kind:     hidden_group_size_y
      - .offset:         280
        .size:           2
        .value_kind:     hidden_group_size_z
      - .offset:         282
        .size:           2
        .value_kind:     hidden_remainder_x
      - .offset:         284
        .size:           2
        .value_kind:     hidden_remainder_y
      - .offset:         286
        .size:           2
        .value_kind:     hidden_remainder_z
      - .offset:         304
        .size:           8
        .value_kind:     hidden_global_offset_x
      - .offset:         312
        .size:           8
        .value_kind:     hidden_global_offset_y
      - .offset:         320
        .size:           8
        .value_kind:     hidden_global_offset_z
      - .offset:         328
        .size:           2
        .value_kind:     hidden_grid_dims
      - .offset:         384
        .size:           4
        .value_kind:     hidden_dynamic_lds_size
    .group_segment_fixed_size: 0
    .kernarg_segment_align: 8
    .kernarg_segment_size: 520
    .language:       OpenCL C
    .language_version:
      - 2
      - 0
    .max_flat_workgroup_size: 512
    .name:           _Z6k_mega6Params
    .private_segment_fixed_size: 0
    .sgpr_count:     108
    .sgpr_spill_count: 56
    .symbol:         _Z6k_mega6Params.kd
    .uniform_work_group_size: 1
    .uses_dynamic_stack: false
    .vgpr_count:     256
    .vgpr_spill_count: 0
    .wavefront_size: 64
